# removed 14 XNACK-replay s_nop 0 fillers between back-to-back global loads (xnack- process; not a data hazard) (stacked on v17)
# speedup vs baseline: 1.0023x; 1.0023x over previous
; DI unsigned pk2(float lo, float hi) { f32x2 f = {lo, hi}; bf2_t v = __builtin_convertvector(f, bf2_t); return __builtin_bit_cast(unsigned, v); }
; #define MFMA32(a, b, c) __builtin_amdgcn_mfma_f32_32x32x16_bf16((a), (b), (c), 0, 0, 0)
; DI f32x16 zero16() { f32x16 z; for (int i = 0; i < 16; ++i) z[i] = 0.f; return z; }
; DI void gla_gate_phase(int wv, LAS unsigned char* lds, const float* x, const float* w_in, const float* w2, const float* bg, const bf16_t* qk1,
;                        bf16_t* qd, bf16_t* ki, bf16_t* kst, float* decay, bf16_t* sbuf) {
;     ...
;         const int hd = wid >> 1;
; #pragma unroll
;         for (int u = 0; u < 2; ++u) {
;             const int tt2 = (wid & 1) * 2 + u, kt = tt2 >> 1, qt = tt2 & 1;
;             f32x16 S = zero16();
;             if (!(kt == 1 && qt == 0)) {
; #pragma unroll
;                 for (int ks = 0; ks < 8; ++ks) { const bf16x8 A = *(const bf16x8*)(ki + (T0 + kt * 32 + rr) * 512 + hd * 128 + ks * 16 + hh * 8);
;                     const bf16x8 B = *(const bf16x8*)(qd + (T0 + qt * 32 + rr) * 512 + hd * 128 + ks * 16 + hh * 8); S = MFMA32(A, B, S); } }
;             const int q = qt * 32 + rr;
;             bf16_t* srow = sbuf + (((size_t)b * 4 + hd) * 64 + ch) * 4096 + q * 64 + kt * 32;
; #pragma unroll
;             for (int gq = 0; gq < 4; ++gq) { const int k0 = 8 * gq + 4 * hh; float v[4];
; #pragma unroll
;                 for (int e = 0; e < 4; ++e) v[e] = (kt * 32 + k0 + e <= q) ? S[4 * gq + e] : 0.f;
;                 u32x2 w; w.x = pk2(v[0], v[1]); w.y = pk2(v[2], v[3]); *(u32x2*)(srow + k0) = w; }
;         }
.LBB0_140:
	s_or_b64 exec, exec, s[44:45]
	s_lshl_b64 s[44:45], s[84:85], 8
	v_lshl_add_u64 v[100:101], s[44:45], 0, v[40:41]
	v_or_b32_e32 v100, s0, v100
	v_readlane_b32 s0, v254, 40
	v_readlane_b32 s1, v254, 41
	v_lshlrev_b64 v[100:101], 13, v[100:101]
	v_lshl_add_u64 v[106:107], v[42:43], 0, v[100:101]
	s_nop 2
	v_cndmask_b32_e64 v2, v2, 0, s[0:1]
	v_readlane_b32 s0, v254, 42
	v_readlane_b32 s1, v254, 43
	v_lshl_add_u64 v[100:101], v[106:107], 0, v[0:1]
	v_mov_b32_e32 v93, v1
	v_cndmask_b32_e64 v3, 0, v3, s[0:1]
	v_readlane_b32 s0, v254, 44
	v_readlane_b32 s1, v254, 45
	v_cvt_pk_bf16_f32 v2, v2, v3
	v_add_co_u32_e32 v108, vcc, s71, v98
	v_cndmask_b32_e64 v4, v4, 0, s[0:1]
	v_readlane_b32 s0, v254, 46
	v_readlane_b32 s1, v254, 47
	v_addc_co_u32_e32 v109, vcc, 0, v99, vcc
	s_nop 0
	v_cndmask_b32_e64 v5, v5, 0, s[0:1]
	v_readlane_b32 s0, v254, 48
	v_cvt_pk_bf16_f32 v3, v4, v5
	v_lshl_add_u64 v[4:5], v[100:101], 0, v[92:93]
	v_readlane_b32 s1, v254, 49
	global_store_dwordx2 v[4:5], v[2:3], off
	v_mov_b32_e32 v95, v1
	v_cndmask_b32_e64 v2, v6, 0, s[0:1]
	v_readlane_b32 s0, v254, 50
	v_readlane_b32 s1, v254, 51
	s_add_i32 s7, s7, s46
	s_add_i32 s56, s56, s46
	v_cndmask_b32_e64 v3, 0, v7, s[0:1]
	v_readlane_b32 s0, v254, 52
	v_readlane_b32 s1, v254, 53
	v_cvt_pk_bf16_f32 v2, v2, v3
	s_cmpk_lt_i32 s7, 0x200
	v_cndmask_b32_e64 v6, v8, 0, s[0:1]
	v_readlane_b32 s0, v254, 54
	v_readlane_b32 s1, v254, 55
	s_nop 1
	v_cndmask_b32_e64 v7, v9, 0, s[0:1]
	v_readlane_b32 s0, v254, 56
	v_cvt_pk_bf16_f32 v3, v6, v7
	v_readlane_b32 s1, v254, 57
	global_store_dwordx2 v[4:5], v[2:3], off offset:16
	s_nop 0
	v_cndmask_b32_e64 v2, v10, 0, s[0:1]
	v_readlane_b32 s0, v254, 58
	v_readlane_b32 s1, v254, 59
	s_nop 1
	v_cndmask_b32_e64 v3, 0, v11, s[0:1]
	v_readlane_b32 s0, v254, 60
	v_readlane_b32 s1, v254, 61
	v_cvt_pk_bf16_f32 v2, v2, v3
	s_nop 0
	v_cndmask_b32_e64 v6, v12, 0, s[0:1]
	v_readlane_b32 s0, v254, 62
	v_readlane_b32 s1, v254, 63
	s_nop 1
	v_cndmask_b32_e64 v7, v13, 0, s[0:1]
	v_readlane_b32 s0, v255, 0
	v_cvt_pk_bf16_f32 v3, v6, v7
	v_readlane_b32 s1, v255, 1
	global_store_dwordx2 v[4:5], v[2:3], off offset:32
	s_nop 0
	v_cndmask_b32_e64 v2, v14, 0, s[0:1]
	v_readlane_b32 s0, v255, 2
	v_readlane_b32 s1, v255, 3
	s_nop 1
	v_cndmask_b32_e64 v3, 0, v15, s[0:1]
	v_readlane_b32 s0, v255, 4
	v_readlane_b32 s1, v255, 5
	v_cvt_pk_bf16_f32 v2, v2, v3
	s_nop 0
	v_cndmask_b32_e64 v6, v16, 0, s[0:1]
	v_readlane_b32 s0, v255, 6
	v_readlane_b32 s1, v255, 7
	s_nop 1
	v_cndmask_b32_e64 v7, v17, 0, s[0:1]
	v_cvt_pk_bf16_f32 v3, v6, v7
	global_store_dwordx2 v[4:5], v[2:3], off offset:48
	global_load_dwordx4 v[2:5], v[96:97], off
	v_readlane_b32 s0, v255, 8
	global_load_dwordx4 v[6:9], v[108:109], off
	global_load_dwordx4 v[98:101], v[96:97], off offset:32
	global_load_dwordx4 v[102:105], v[108:109], off offset:32
	v_readlane_b32 s1, v255, 9
	s_waitcnt vmcnt(2)
	v_mfma_f32_32x32x16_bf16 v[2:17], v[2:5], v[6:9], 0
	s_waitcnt vmcnt(0)
	v_mfma_f32_32x32x16_bf16 v[2:17], v[98:101], v[102:105], v[2:17]
	global_load_dwordx4 v[98:101], v[96:97], off offset:64
	global_load_dwordx4 v[102:105], v[108:109], off offset:64
	s_waitcnt vmcnt(0)
	v_mfma_f32_32x32x16_bf16 v[2:17], v[98:101], v[102:105], v[2:17]
	global_load_dwordx4 v[98:101], v[96:97], off offset:96
	global_load_dwordx4 v[102:105], v[108:109], off offset:96
	s_waitcnt vmcnt(0)
	v_mfma_f32_32x32x16_bf16 v[2:17], v[98:101], v[102:105], v[2:17]
	global_load_dwordx4 v[98:101], v[96:97], off offset:128
	global_load_dwordx4 v[102:105], v[108:109], off offset:128
	s_waitcnt vmcnt(0)
	v_mfma_f32_32x32x16_bf16 v[2:17], v[98:101], v[102:105], v[2:17]
	global_load_dwordx4 v[98:101], v[96:97], off offset:160
	global_load_dwordx4 v[102:105], v[108:109], off offset:160
	s_waitcnt vmcnt(0)
	v_mfma_f32_32x32x16_bf16 v[2:17], v[98:101], v[102:105], v[2:17]
	global_load_dwordx4 v[98:101], v[96:97], off offset:192
	global_load_dwordx4 v[102:105], v[108:109], off offset:192
	s_waitcnt vmcnt(0)
	v_mfma_f32_32x32x16_bf16 v[2:17], v[98:101], v[102:105], v[2:17]
	global_load_dwordx4 v[96:99], v[96:97], off offset:224
	global_load_dwordx4 v[100:103], v[108:109], off offset:224
	s_waitcnt vmcnt(0)
	v_mfma_f32_32x32x16_bf16 v[2:17], v[96:99], v[100:103], v[2:17]
	v_lshl_add_u64 v[96:97], v[106:107], 0, v[94:95]
	s_nop 10
	v_cndmask_b32_e64 v2, v2, 0, s[0:1]
	v_readlane_b32 s0, v255, 10
	v_readlane_b32 s1, v255, 11
	s_nop 1
	v_cndmask_b32_e64 v3, 0, v3, s[0:1]
	v_readlane_b32 s0, v255, 12
	v_readlane_b32 s1, v255, 13
	v_cvt_pk_bf16_f32 v2, v2, v3
	s_nop 0
	v_cndmask_b32_e64 v4, v4, 0, s[0:1]
	v_readlane_b32 s0, v255, 14
	v_readlane_b32 s1, v255, 15
	s_nop 1
	v_cndmask_b32_e64 v5, v5, 0, s[0:1]
	v_readlane_b32 s0, v255, 16
	v_cvt_pk_bf16_f32 v3, v4, v5
	v_lshl_add_u64 v[4:5], v[96:97], 0, v[92:93]
	v_readlane_b32 s1, v255, 17
	global_store_dwordx2 v[4:5], v[2:3], off
	s_nop 0
	v_cndmask_b32_e64 v2, v6, 0, s[0:1]
	v_readlane_b32 s0, v255, 18
	v_readlane_b32 s1, v255, 19
	s_nop 1
	v_cndmask_b32_e64 v3, 0, v7, s[0:1]
	v_readlane_b32 s0, v255, 20
	v_readlane_b32 s1, v255, 21
	v_cvt_pk_bf16_f32 v2, v2, v3
	s_nop 0
	v_cndmask_b32_e64 v6, v8, 0, s[0:1]
	v_readlane_b32 s0, v255, 22
	v_readlane_b32 s1, v255, 23
	s_nop 1
	v_cndmask_b32_e64 v7, v9, 0, s[0:1]
	v_readlane_b32 s0, v255, 24
	v_cvt_pk_bf16_f32 v3, v6, v7
	v_readlane_b32 s1, v255, 25
	global_store_dwordx2 v[4:5], v[2:3], off offset:16
	s_nop 0
	v_cndmask_b32_e64 v2, v10, 0, s[0:1]
	v_readlane_b32 s0, v255, 26
	v_readlane_b32 s1, v255, 27
	s_nop 1
	v_cndmask_b32_e64 v3, 0, v11, s[0:1]
	v_readlane_b32 s0, v255, 28
	v_readlane_b32 s1, v255, 29
	v_cvt_pk_bf16_f32 v2, v2, v3
	s_nop 0
	v_cndmask_b32_e64 v6, v12, 0, s[0:1]
	v_readlane_b32 s0, v255, 30
	v_readlane_b32 s1, v255, 31
	s_nop 1
	v_cndmask_b32_e64 v7, v13, 0, s[0:1]
	v_readlane_b32 s0, v254, 38
	v_cvt_pk_bf16_f32 v3, v6, v7
	v_readlane_b32 s1, v254, 39
	global_store_dwordx2 v[4:5], v[2:3], off offset:32
	s_nop 0
	v_cndmask_b32_e64 v2, v14, 0, s[0:1]
	v_readlane_b32 s0, v255, 32
	v_readlane_b32 s1, v255, 33
	s_nop 1
	v_cndmask_b32_e64 v3, 0, v15, s[0:1]
	v_readlane_b32 s0, v255, 34
	v_readlane_b32 s1, v255, 35
	v_cvt_pk_bf16_f32 v2, v2, v3
	s_nop 0
	v_cndmask_b32_e64 v6, v16, 0, s[0:1]
	v_readlane_b32 s0, v255, 36
	v_readlane_b32 s1, v255, 37
	s_nop 1
	v_cndmask_b32_e64 v7, v17, 0, s[0:1]
	v_cvt_pk_bf16_f32 v3, v6, v7
	global_store_dwordx2 v[4:5], v[2:3], off offset:48
	s_cbranch_scc0 .LBB0_153

.LBB0_199:
	v_cvt_pk_bf16_f32 v34, v2, v3
	v_cvt_pk_bf16_f32 v35, v4, v5
	v_cvt_pk_bf16_f32 v36, v6, v7
	v_cvt_pk_bf16_f32 v37, v8, v9
	v_lshl_add_u64 v[18:19], s[48:49], 0, v[216:217]
	v_lshl_add_u64 v[20:21], s[48:49], 0, v[220:221]
	v_lshl_add_u64 v[38:39], s[48:49], 0, v[226:227]
	global_load_dwordx4 v[122:125], v[18:19], off
	global_load_dwordx4 v[126:129], v[20:21], off
	v_lshl_add_u64 v[18:19], s[48:49], 0, v[228:229]
	v_lshl_add_u64 v[20:21], s[48:49], 0, v[230:231]
	v_add_co_u32_e32 v146, vcc, s93, v38
	global_load_dwordx4 v[118:121], v[18:19], off offset:160
	global_load_dwordx4 v[114:117], v[18:19], off offset:192
	global_load_dwordx4 v[142:145], v[20:21], off offset:-32
	global_load_dwordx4 v[130:133], v[18:19], off offset:224
	global_load_dwordx4 v[138:141], v[20:21], off
	global_load_dwordx4 v[134:137], v[20:21], off offset:32
	s_waitcnt vmcnt(8)
	v_mfma_f32_32x32x16_bf16 v[18:33], v[34:37], v[94:97], 0
	v_addc_co_u32_e32 v147, vcc, 0, v39, vcc
	s_mov_b32 s2, 0x10008000
	v_add_co_u32_e32 v148, vcc, s2, v38
	v_cvt_pk_bf16_f32 v168, v10, v11
	s_nop 0
	v_addc_co_u32_e32 v149, vcc, 0, v39, vcc
	v_mfma_f32_32x32x16_bf16 v[34:49], v[34:37], v[102:105], 0
	global_load_dwordx2 v[94:95], v[146:147], off
	global_load_dwordx2 v[96:97], v[146:147], off offset:16
	global_load_dwordx2 v[102:103], v[146:147], off offset:32
	global_load_dwordx2 v[104:105], v[146:147], off offset:48
	v_cvt_pk_bf16_f32 v169, v12, v13
	v_cvt_pk_bf16_f32 v170, v14, v15
	v_cvt_pk_bf16_f32 v171, v16, v17
	v_pk_mul_f32 v[16:17], v[88:89], v[16:17]
	v_pk_mul_f32 v[12:13], v[84:85], v[12:13]
	v_pk_mul_f32 v[8:9], v[80:81], v[8:9]
	v_mfma_f32_32x32x16_bf16 v[18:33], v[168:171], v[90:93], v[18:33]
	global_load_dwordx2 v[90:91], v[148:149], off
	global_load_dwordx2 v[92:93], v[148:149], off offset:16
	global_load_dwordx2 v[162:163], v[148:149], off offset:32
	global_load_dwordx2 v[164:165], v[148:149], off offset:48
	v_mul_f32_e64 v4, v76, v4
	v_mul_f32_e64 v5, v77, v5
	v_pk_mul_f32 v[14:15], v[86:87], v[14:15]
	v_pk_mul_f32 v[10:11], v[82:83], v[10:11]
	v_pk_mul_f32 v[6:7], v[78:79], v[6:7]
	v_pk_mul_f32 v[2:3], v[74:75], v[2:3]
	v_lshl_add_u64 v[158:159], s[48:49], 0, v[224:225]
	v_mfma_f32_32x32x16_bf16 v[34:49], v[168:171], v[98:101], v[34:49]
	global_load_dwordx4 v[146:149], v[158:159], off offset:-64
	global_load_dwordx4 v[150:153], v[158:159], off offset:-32
	global_load_dwordx4 v[154:157], v[158:159], off
	global_load_dwordx4 v[158:161], v[158:159], off offset:32
	ds_write2st64_b32 v181, v18, v19 offset1:1
	s_nop 5
	ds_write2st64_b32 v181, v34, v35 offset0:16 offset1:17
	ds_write2st64_b32 v181, v20, v21 offset0:2 offset1:3
	ds_write2st64_b32 v181, v36, v37 offset0:18 offset1:19
	ds_write2st64_b32 v181, v22, v23 offset0:4 offset1:5
	ds_write2st64_b32 v181, v38, v39 offset0:20 offset1:21
	ds_write2st64_b32 v181, v24, v25 offset0:6 offset1:7
	ds_write2st64_b32 v181, v40, v41 offset0:22 offset1:23
	ds_write2st64_b32 v181, v26, v27 offset0:8 offset1:9
	ds_write2st64_b32 v181, v42, v43 offset0:24 offset1:25
	ds_write2st64_b32 v181, v28, v29 offset0:10 offset1:11
	ds_write2st64_b32 v181, v44, v45 offset0:26 offset1:27
	ds_write2st64_b32 v181, v30, v31 offset0:12 offset1:13
	ds_write2st64_b32 v181, v46, v47 offset0:28 offset1:29
	ds_write2st64_b32 v181, v32, v33 offset0:14 offset1:15
	ds_write2st64_b32 v181, v48, v49 offset0:30 offset1:31
	v_mfma_f32_32x32x16_bf16 v[2:17], v[54:57], v[50:53], v[2:17]
	s_waitcnt lgkmcnt(0)
	s_barrier
	v_add_u32_e32 v183, s30, v177
	ds_read2st64_b32 v[18:19], v183 offset1:1
	ds_read2st64_b32 v[20:21], v183 offset0:2 offset1:3
	ds_read2st64_b32 v[22:23], v183 offset0:32 offset1:33
	ds_read2st64_b32 v[24:25], v183 offset0:34 offset1:35
	ds_read2st64_b32 v[26:27], v183 offset0:64 offset1:65
	ds_read2st64_b32 v[28:29], v183 offset0:66 offset1:67
	ds_read2st64_b32 v[30:31], v183 offset0:96 offset1:97
	ds_read2st64_b32 v[32:33], v183 offset0:98 offset1:99
	ds_read2st64_b32 v[34:35], v183 offset0:128 offset1:129
	ds_read2st64_b32 v[36:37], v183 offset0:130 offset1:131
	s_waitcnt lgkmcnt(0)
	v_pk_add_f32 v[20:21], v[20:21], 0 op_sel_hi:[1,0]
	v_pk_add_f32 v[18:19], v[18:19], 0 op_sel_hi:[1,0]
	v_mfma_f32_32x32x16_bf16 v[2:17], v[66:69], v[70:73], v[2:17]
	v_add_f32_e64 v18, v18, v22
	v_add_f32_e64 v19, v19, v23
	v_add_f32_e64 v20, v20, v24
	v_add_f32_e64 v21, v21, v25
	v_add_f32_e64 v18, v18, v26
	v_add_f32_e64 v19, v19, v27
	v_pk_add_f32 v[20:21], v[20:21], v[28:29]
	v_pk_add_f32 v[18:19], v[18:19], v[30:31]
	v_pk_add_f32 v[20:21], v[20:21], v[32:33]
	v_pk_add_f32 v[18:19], v[18:19], v[34:35]
	v_mfma_f32_32x32x16_bf16 v[2:17], v[58:61], v[62:65], v[2:17]
	v_add_f32_e64 v20, v20, v36
	v_add_f32_e64 v21, v21, v37
	v_lshl_add_u64 v[22:23], s[48:49], 0, v[218:219]
	global_store_dwordx4 v[22:23], v[18:21], off offset:-32
	v_add_u32_e32 v185, s31, v177
	ds_read2st64_b32 v[18:19], v185 offset1:1
	ds_read2st64_b32 v[20:21], v185 offset0:2 offset1:3
	ds_read2st64_b32 v[24:25], v185 offset0:32 offset1:33
	ds_read2st64_b32 v[26:27], v185 offset0:34 offset1:35
	ds_read2st64_b32 v[28:29], v185 offset0:64 offset1:65
	ds_read2st64_b32 v[30:31], v185 offset0:66 offset1:67
	ds_read2st64_b32 v[32:33], v185 offset0:96 offset1:97
	ds_read2st64_b32 v[34:35], v185 offset0:98 offset1:99
	ds_read2st64_b32 v[36:37], v185 offset0:128 offset1:129
	ds_read2st64_b32 v[38:39], v185 offset0:130 offset1:131
	s_waitcnt lgkmcnt(9)
	v_pk_add_f32 v[18:19], v[18:19], 0 op_sel_hi:[1,0]
	v_mfma_f32_32x32x16_bf16 v[2:17], v[106:109], v[110:113], v[2:17]
	s_waitcnt lgkmcnt(8)
	v_add_f32_e64 v20, v20, 0
	v_add_f32_e64 v21, v21, 0
	s_waitcnt lgkmcnt(7)
	v_add_f32_e64 v18, v18, v24
	v_add_f32_e64 v19, v19, v25
	s_waitcnt lgkmcnt(6)
	v_pk_add_f32 v[20:21], v[20:21], v[26:27]
	s_waitcnt lgkmcnt(5)
	v_pk_add_f32 v[18:19], v[18:19], v[28:29]
	s_waitcnt lgkmcnt(4)
	v_pk_add_f32 v[20:21], v[20:21], v[30:31]
	s_waitcnt lgkmcnt(3)
	v_pk_add_f32 v[18:19], v[18:19], v[32:33]
	s_waitcnt lgkmcnt(2)
	v_pk_add_f32 v[20:21], v[20:21], v[34:35]
	s_waitcnt lgkmcnt(1)
	v_pk_add_f32 v[18:19], v[18:19], v[36:37]
	v_cvt_pk_bf16_f32 v34, v2, v3
	v_cvt_pk_bf16_f32 v35, v4, v5
	v_cvt_pk_bf16_f32 v36, v6, v7
	v_cvt_pk_bf16_f32 v37, v8, v9
	s_add_i32 s15, s14, 3
	s_add_i32 s2, s14, 4
	s_waitcnt lgkmcnt(0)
	v_pk_add_f32 v[20:21], v[20:21], v[38:39]
	s_cmp_lt_u32 s15, 63
	global_store_dwordx4 v[22:23], v[18:21], off
	s_cselect_b32 s2, s2, 63
	v_lshl_or_b32 v0, s2, 6, v176
	s_waitcnt vmcnt(12)
	v_mfma_f32_32x32x16_bf16 v[18:33], v[34:37], v[94:97], 0
	v_lshlrev_b32_e32 v0, 1, v0
	s_lshl_b32 s56, s2, 7
	v_lshl_add_u64 v[38:39], v[212:213], 0, s[56:57]
	global_load_dwordx4 v[50:53], v0, s[12:13]
	global_load_dwordx4 v[54:57], v[38:39], off
	v_lshl_add_u64 v[40:41], v[210:211], 0, s[56:57]
	v_lshl_or_b32 v0, s2, 16, v214
	v_cvt_pk_bf16_f32 v168, v10, v11
	v_cvt_pk_bf16_f32 v169, v12, v13
	v_cvt_pk_bf16_f32 v170, v14, v15
	v_cvt_pk_bf16_f32 v171, v16, v17
	global_load_dwordx4 v[66:69], v[38:39], off offset:32
	global_load_dwordx4 v[58:61], v[38:39], off offset:64
	global_load_dwordx4 v[62:65], v[40:41], off offset:64
	global_load_dwordx4 v[110:113], v[40:41], off offset:96
	global_load_dwordx4 v[70:73], v[40:41], off offset:32
	global_load_dwordx4 v[106:109], v[38:39], off offset:96
	v_lshl_add_u64 v[38:39], s[18:19], 0, v[0:1]
	v_add_co_u32_e32 v74, vcc, s71, v38
	s_waitcnt vmcnt(18)
	v_mfma_f32_32x32x16_bf16 v[18:33], v[168:171], v[102:105], v[18:33]
	v_addc_co_u32_e32 v75, vcc, 0, v39, vcc
	s_waitcnt vmcnt(10)
	v_mul_f32_e64 v16, v160, v16
	v_mul_f32_e64 v17, v161, v17
	v_mul_f32_e64 v14, v158, v14
	v_mul_f32_e64 v15, v159, v15
	v_pk_mul_f32 v[12:13], v[156:157], v[12:13]
	v_pk_mul_f32 v[10:11], v[154:155], v[10:11]
	v_pk_mul_f32 v[8:9], v[152:153], v[8:9]
	v_mfma_f32_32x32x16_bf16 v[34:49], v[34:37], v[90:93], 0
	global_load_dwordx2 v[94:95], v0, s[18:19]
	global_load_dwordx2 v[96:97], v0, s[18:19] offset:16
	global_load_dwordx2 v[90:91], v0, s[18:19] offset:32
	global_load_dwordx2 v[92:93], v0, s[18:19] offset:48
	v_lshl_or_b32 v0, s2, 9, v182
	v_lshl_add_u64 v[86:87], v[0:1], 2, s[20:21]
	global_load_dwordx2 v[102:103], v[74:75], off
	global_load_dwordx2 v[104:105], v[74:75], off offset:16
	global_load_dwordx2 v[98:99], v[74:75], off offset:32
	global_load_dwordx2 v[100:101], v[74:75], off offset:48
	global_load_dwordx4 v[74:77], v[86:87], off
	global_load_dwordx4 v[78:81], v[86:87], off offset:32
	global_load_dwordx4 v[82:85], v[86:87], off offset:64
	global_load_dwordx4 v[86:89], v[86:87], off offset:96
	v_pk_mul_f32 v[6:7], v[150:151], v[6:7]
	v_pk_mul_f32 v[4:5], v[148:149], v[4:5]
	v_pk_mul_f32 v[2:3], v[146:147], v[2:3]
	v_mfma_f32_32x32x16_bf16 v[34:49], v[168:171], v[162:165], v[34:49]
	ds_write2st64_b32 v181, v18, v19 offset0:160 offset1:161
	s_nop 10
	ds_write2st64_b32 v181, v34, v35 offset0:176 offset1:177
	ds_write2st64_b32 v181, v20, v21 offset0:162 offset1:163
	ds_write2st64_b32 v181, v36, v37 offset0:178 offset1:179
	ds_write2st64_b32 v181, v22, v23 offset0:164 offset1:165
	ds_write2st64_b32 v181, v38, v39 offset0:180 offset1:181
	ds_write2st64_b32 v181, v24, v25 offset0:166 offset1:167
	ds_write2st64_b32 v181, v40, v41 offset0:182 offset1:183
	ds_write2st64_b32 v181, v26, v27 offset0:168 offset1:169
	ds_write2st64_b32 v181, v42, v43 offset0:184 offset1:185
	ds_write2st64_b32 v181, v28, v29 offset0:170 offset1:171
	ds_write2st64_b32 v181, v44, v45 offset0:186 offset1:187
	ds_write2st64_b32 v181, v30, v31 offset0:172 offset1:173
	ds_write2st64_b32 v181, v46, v47 offset0:188 offset1:189
	ds_write2st64_b32 v181, v32, v33 offset0:174 offset1:175
	ds_write2st64_b32 v181, v48, v49 offset0:190 offset1:191
	v_mfma_f32_32x32x16_bf16 v[2:17], v[126:129], v[122:125], v[2:17]
	s_waitcnt lgkmcnt(0)
	s_barrier
; DI void gla_scan_phase(int wv, LAS unsigned char* lds, const bf16_t* qd, const bf16_t* kst, const bf16_t* sbuf, const bf16_t* vt, const float* decay, float* obuf) {
;     ...
;             SCAN_LOADC(0, vA, kA, qB, dc);
; #pragma nounroll
;             for (int c = 0; c < 64; c += 2) {
;                 SCAN_BODYC(c, vA, kA, qB, dc, nvA, nkA, nqB, ndc);
;                 SCAN_BODYC(c + 1, nvA, nkA, nqB, ndc, vA, kA, qB, dc);
;             }
	ds_read2st64_b32 v[18:19], v183 offset0:160 offset1:161
	ds_read2st64_b32 v[20:21], v183 offset0:162 offset1:163
	ds_read2st64_b32 v[22:23], v183 offset0:192 offset1:193
	ds_read2st64_b32 v[24:25], v183 offset0:194 offset1:195
	ds_read2st64_b32 v[26:27], v183 offset0:224 offset1:225
	ds_read2st64_b32 v[28:29], v183 offset0:226 offset1:227
	v_add_u32_e32 v0, s35, v177
	v_add_u32_e32 v31, s36, v177
	v_add_u32_e32 v32, s37, v177
	v_mfma_f32_32x32x16_bf16 v[2:17], v[142:145], v[118:121], v[2:17]
	v_add_u32_e32 v33, s38, v177
	v_add_u32_e32 v34, s39, v177
	v_add_u32_e32 v35, s40, v177
	v_add_u32_e32 v36, s41, v177
	v_add_u32_e32 v37, s42, v177
	ds_read_b32 v30, v0 offset:40960
	ds_read_b32 v31, v31 offset:40960
	ds_read_b32 v32, v32 offset:40960
	ds_read_b32 v33, v33 offset:40960
	ds_read_b32 v34, v34 offset:40960
	ds_read_b32 v35, v35 offset:40960
	ds_read_b32 v36, v36 offset:40960
	ds_read_b32 v37, v37 offset:40960
	s_waitcnt lgkmcnt(12)
	v_pk_add_f32 v[20:21], v[20:21], 0 op_sel_hi:[1,0]
	v_mfma_f32_32x32x16_bf16 v[2:17], v[138:141], v[114:117], v[2:17]
	v_add_f32_e64 v18, v18, 0
	v_add_f32_e64 v19, v19, 0
	s_waitcnt lgkmcnt(10)
	v_add_f32_e64 v20, v20, v24
	v_add_f32_e64 v21, v21, v25
	v_pk_add_f32 v[18:19], v[18:19], v[22:23]
	s_waitcnt lgkmcnt(8)
	v_pk_add_f32 v[20:21], v[20:21], v[28:29]
	v_pk_add_f32 v[18:19], v[18:19], v[26:27]
	v_lshl_add_u64 v[22:23], s[48:49], 0, v[222:223]
	s_waitcnt lgkmcnt(6)
	v_pk_add_f32 v[18:19], v[18:19], v[30:31]
	s_waitcnt lgkmcnt(4)
	v_pk_add_f32 v[20:21], v[20:21], v[32:33]
	v_add_co_u32_e32 v22, vcc, s94, v22
	s_waitcnt lgkmcnt(0)
	v_pk_add_f32 v[20:21], v[20:21], v[36:37]
	v_pk_add_f32 v[18:19], v[18:19], v[34:35]
	v_addc_co_u32_e32 v23, vcc, 0, v23, vcc
	global_store_dwordx4 v[22:23], v[18:21], off
	ds_read2st64_b32 v[18:19], v185 offset0:160 offset1:161
	ds_read2st64_b32 v[20:21], v185 offset0:162 offset1:163
	ds_read2st64_b32 v[24:25], v185 offset0:192 offset1:193
	ds_read2st64_b32 v[26:27], v185 offset0:194 offset1:195
	ds_read2st64_b32 v[28:29], v185 offset0:224 offset1:225
	ds_read2st64_b32 v[30:31], v185 offset0:226 offset1:227
	v_mfma_f32_32x32x16_bf16 v[2:17], v[134:137], v[130:133], v[2:17]
	v_add_u32_e32 v0, s43, v177
	v_add_u32_e32 v33, s44, v177
	v_add_u32_e32 v34, s45, v177
	v_add_u32_e32 v35, s84, v177
	v_add_u32_e32 v36, s34, v177
	v_add_u32_e32 v37, s85, v177
	v_add_u32_e32 v38, s86, v177
	v_add_u32_e32 v39, s87, v177
	ds_read_b32 v32, v0 offset:40960
	ds_read_b32 v33, v33 offset:40960
	ds_read_b32 v34, v34 offset:40960
	ds_read_b32 v35, v35 offset:40960
	ds_read_b32 v36, v36 offset:40960
	ds_read_b32 v37, v37 offset:40960
	ds_read_b32 v38, v38 offset:40960
	ds_read_b32 v39, v39 offset:40960
	s_waitcnt lgkmcnt(12)
	v_pk_add_f32 v[20:21], v[20:21], 0 op_sel_hi:[1,0]
	v_pk_add_f32 v[18:19], v[18:19], 0 op_sel_hi:[1,0]
	s_waitcnt lgkmcnt(10)
	v_pk_add_f32 v[20:21], v[20:21], v[26:27]
	v_pk_add_f32 v[18:19], v[18:19], v[24:25]
	s_waitcnt lgkmcnt(8)
	v_pk_add_f32 v[20:21], v[20:21], v[30:31]
	v_pk_add_f32 v[18:19], v[18:19], v[28:29]
	s_mov_b64 s[16:17], 0x1000
	s_waitcnt lgkmcnt(6)
	v_pk_add_f32 v[18:19], v[18:19], v[32:33]
	s_waitcnt lgkmcnt(4)
	v_pk_add_f32 v[20:21], v[20:21], v[34:35]
	s_add_i32 s14, s14, 2
	v_lshl_add_u64 v[224:225], v[224:225], 0, s[16:17]
	s_mov_b64 s[16:17], 0x20000
	s_waitcnt lgkmcnt(0)
	v_pk_add_f32 v[20:21], v[20:21], v[38:39]
	v_pk_add_f32 v[18:19], v[18:19], v[36:37]
	v_lshl_add_u64 v[216:217], v[216:217], 0, s[60:61]
	v_lshl_add_u64 v[218:219], v[218:219], 0, s[66:67]
	v_lshl_add_u64 v[220:221], v[220:221], 0, s[60:61]
	v_lshl_add_u64 v[222:223], v[222:223], 0, s[66:67]
	v_lshl_add_u64 v[226:227], v[226:227], 0, s[16:17]
	v_lshl_add_u64 v[228:229], v[228:229], 0, s[60:61]
	v_lshl_add_u64 v[230:231], v[230:231], 0, s[60:61]
	s_cmp_gt_u32 s14, 61
	global_store_dwordx4 v[22:23], v[18:21], off offset:32
	s_cbranch_scc0 .LBB0_199
	v_mov_b64_e32 v[228:229], 0x800
	s_branch .LBB0_187

; DI unsigned pk2(float lo, float hi) { f32x2 f = {lo, hi}; bf2_t v = __builtin_convertvector(f, bf2_t); return __builtin_bit_cast(unsigned, v); }
; DI void gla_finish_phase(int wv, const float* obuf, const bf16_t* rb, const float* gn, bf16_t* ob) {
;     ...
;     for (int row0 = bid * 8 + wid; row0 < M_TOK; row0 += 2 * nw) {
;         f32x4 v[2][4]; u32x2 rw[2][4];
; #pragma unroll
;         for (int u = 0; u < 2; ++u) { const int row = (row0 + u * nw < M_TOK) ? row0 + u * nw : row0;
; #pragma unroll
;             for (int i = 0; i < 4; ++i) { v[u][i] = ((const f32x4*)(obuf + (size_t)row * 1024))[lane + 64 * i]; rw[u][i] = ((const u32x2*)(rb + (size_t)row * 1024))[lane + 64 * i]; } }
; #pragma unroll
;         for (int u = 0; u < 2; ++u) { const int row = row0 + u * nw; if (row < M_TOK) {
; #pragma unroll
;             for (int i = 0; i < 4; ++i) {
;                 const f32x4 x = v[u][i];
;                 const float ss = wave_sum((x.x * x.x + x.y * x.y) + (x.z * x.z + x.w * x.w));
;                 const float rn = 1.f / sqrtf(ss * (1.f / 256.f) + 1e-6f);
;                 const u32x2 r_ = rw[u][i];
;                 const float r0 = __uint_as_float(r_.x << 16), r1 = __uint_as_float(r_.x & 0xffff0000u), r2 = __uint_as_float(r_.y << 16), r3 = __uint_as_float(r_.y & 0xffff0000u);
;                 const float s0 = r0 / (1.f + expf(-r0)), s1 = r1 / (1.f + expf(-r1)), s2 = r2 / (1.f + expf(-r2)), s3 = r3 / (1.f + expf(-r3));
;                 u32x2 w; w.x = pk2(x.x * rn * g4.x * s0, x.y * rn * g4.y * s1); w.y = pk2(x.z * rn * g4.z * s2, x.w * rn * g4.w * s3);
;                 ((u32x2*)(ob + (size_t)row * 1024))[lane + 64 * i] = w;
.LBB0_238:
	v_add_u32_e32 v0, s47, v38
	v_cmp_gt_i32_e64 s[0:1], s71, v0
	v_lshl_add_u64 v[34:35], s[48:49], 0, v[48:49]
	v_lshl_add_u64 v[36:37], s[48:49], 0, v[50:51]
	v_cndmask_b32_e64 v6, v38, v0, s[0:1]
	v_ashrrev_i32_e32 v7, 31, v6
	v_lshlrev_b64 v[8:9], 12, v[6:7]
	v_lshlrev_b64 v[6:7], 11, v[6:7]
	v_lshl_add_u64 v[8:9], v[40:41], 0, v[8:9]
	v_lshl_add_u64 v[22:23], v[42:43], 0, v[6:7]
	global_load_dwordx4 v[18:21], v[8:9], off
	global_load_dwordx2 v[58:59], v[22:23], off
	global_load_dwordx4 v[14:17], v[8:9], off offset:1024
	global_load_dwordx2 v[56:57], v[22:23], off offset:512
	global_load_dwordx4 v[10:13], v[8:9], off offset:2048
	global_load_dwordx2 v[54:55], v[22:23], off offset:1024
	global_load_dwordx4 v[6:9], v[8:9], off offset:3072
	global_load_dwordx2 v[52:53], v[22:23], off offset:1536
	global_load_dwordx2 v[60:61], v[34:35], off offset:512
	global_load_dwordx4 v[22:25], v[36:37], off offset:3072
	global_load_dwordx2 v[62:63], v[34:35], off
	global_load_dwordx4 v[26:29], v[36:37], off offset:2048
	global_load_dwordx2 v[64:65], v[34:35], off offset:-512
	global_load_dwordx4 v[30:33], v[36:37], off offset:1024
	global_load_dwordx2 v[66:67], v[34:35], off offset:-1024
	global_load_dwordx4 v[34:37], v[36:37], off
	s_mov_b32 s2, 0xf800000
	s_waitcnt vmcnt(0)
	v_pk_mul_f32 v[68:69], v[36:37], v[36:37]
	v_pk_mul_f32 v[70:71], v[34:35], v[34:35]
	s_nop 0
	v_pk_mov_b32 v[72:73], v[70:71], v[68:69] op_sel:[1,0]
	v_mov_b32_e32 v71, v69
	v_pk_add_f32 v[68:69], v[72:73], v[70:71]
	s_nop 0
	v_add_f32_e32 v0, v68, v69
	ds_bpermute_b32 v39, v233, v0
	s_waitcnt lgkmcnt(0)
	v_add_f32_e32 v0, v0, v39
	ds_bpermute_b32 v39, v234, v0
	s_waitcnt lgkmcnt(0)
	v_add_f32_e32 v0, v0, v39
	ds_bpermute_b32 v39, v235, v0
	s_waitcnt lgkmcnt(0)
	v_add_f32_e32 v0, v0, v39
	ds_bpermute_b32 v39, v236, v0
	s_waitcnt lgkmcnt(0)
	v_add_f32_e32 v0, v0, v39
	ds_bpermute_b32 v39, v237, v0
	s_waitcnt lgkmcnt(0)
	v_add_f32_e32 v0, v0, v39
	ds_bpermute_b32 v39, v238, v0
	s_waitcnt lgkmcnt(0)
	v_add_f32_e32 v0, v0, v39
	v_fmamk_f32 v0, v0, 0x3b800000, v241
	v_cmp_gt_f32_e32 vcc, s2, v0
	v_mul_f32_e32 v39, 0x4f800000, v0
	s_nop 0
	v_cndmask_b32_e32 v0, v0, v39, vcc
	v_sqrt_f32_e32 v39, v0
	s_nop 0
	v_add_u32_e32 v68, -1, v39
	v_fma_f32 v69, -v68, v39, v0
	v_cmp_ge_f32_e64 s[4:5], 0, v69
	v_add_u32_e32 v69, 1, v39
	s_nop 0
	v_cndmask_b32_e64 v68, v39, v68, s[4:5]
	v_fma_f32 v39, -v69, v39, v0
	v_cmp_lt_f32_e64 s[4:5], 0, v39
	s_nop 1
	v_cndmask_b32_e64 v39, v68, v69, s[4:5]
	v_mul_f32_e32 v68, 0x37800000, v39
	v_cndmask_b32_e32 v39, v39, v68, vcc
	v_cmp_class_f32_e32 vcc, v0, v242
	s_nop 1
	v_cndmask_b32_e32 v0, v39, v0, vcc
	v_div_scale_f32 v39, s[4:5], v0, v0, 1.0
	v_rcp_f32_e32 v68, v39
	s_nop 0
	v_fma_f32 v69, -v39, v68, 1.0
	v_fmac_f32_e32 v68, v69, v68
	v_div_scale_f32 v69, vcc, 1.0, v0, 1.0
	v_mul_f32_e32 v70, v69, v68
	v_fma_f32 v71, -v39, v70, v69
	v_fmac_f32_e32 v70, v71, v68
	v_fma_f32 v39, -v39, v70, v69
	v_div_fmas_f32 v39, v39, v68, v70
	v_div_fixup_f32 v0, v39, v0, 1.0
	v_lshlrev_b32_e32 v39, 16, v66
	v_mul_f32_e32 v68, 0xbfb8aa3b, v39
	v_fma_f32 v69, v39, s89, -v68
	v_rndne_f32_e32 v70, v68
	v_fmac_f32_e32 v69, 0xb2a5705f, v39
	v_sub_f32_e32 v68, v68, v70
	v_add_f32_e32 v68, v68, v69
	v_exp_f32_e32 v68, v68
	v_cvt_i32_f32_e32 v69, v70
	v_and_b32_e32 v66, 0xffff0000, v66
	v_cmp_nlt_f32_e32 vcc, s96, v39
	v_pk_mul_f32 v[34:35], v[34:35], v[0:1] op_sel_hi:[1,0]
	v_ldexp_f32 v68, v68, v69
	v_mul_f32_e32 v69, 0xbfb8aa3b, v66
	v_fma_f32 v70, v66, s89, -v69
	v_rndne_f32_e32 v71, v69
	v_fmac_f32_e32 v70, 0xb2a5705f, v66
	v_sub_f32_e32 v69, v69, v71
	v_add_f32_e32 v69, v69, v70
	v_exp_f32_e32 v69, v69
	v_cvt_i32_f32_e32 v70, v71
	v_cndmask_b32_e32 v68, 0, v68, vcc
	v_cmp_ngt_f32_e32 vcc, s97, v39
	v_pk_mul_f32 v[34:35], v[2:3], v[34:35]
	v_ldexp_f32 v69, v69, v70
	v_cndmask_b32_e32 v68, v246, v68, vcc
	v_cmp_nlt_f32_e32 vcc, s96, v66
	v_pk_mul_f32 v[36:37], v[36:37], v[0:1] op_sel_hi:[1,0]
	s_nop 0
	v_cndmask_b32_e32 v69, 0, v69, vcc
	v_cmp_ngt_f32_e32 vcc, s97, v66
	v_pk_mul_f32 v[36:37], v[4:5], v[36:37]
	s_nop 0
	v_cndmask_b32_e32 v69, v246, v69, vcc
	v_pk_add_f32 v[68:69], v[68:69], 1.0 op_sel_hi:[1,0]
	s_nop 0
	v_div_scale_f32 v70, s[4:5], v69, v69, v66
	v_rcp_f32_e32 v71, v70
	s_nop 0
	v_fma_f32 v72, -v70, v71, 1.0
	v_fmac_f32_e32 v71, v72, v71
	v_div_scale_f32 v72, vcc, v66, v69, v66
	v_mul_f32_e32 v73, v72, v71
	v_fma_f32 v74, -v70, v73, v72
	v_fmac_f32_e32 v73, v74, v71
	v_fma_f32 v70, -v70, v73, v72
	v_div_fmas_f32 v70, v70, v71, v73
	v_div_fixup_f32 v69, v70, v69, v66
	v_div_scale_f32 v66, s[4:5], v68, v68, v39
	v_rcp_f32_e32 v70, v66
	s_nop 0
	v_fma_f32 v71, -v66, v70, 1.0
	v_fmac_f32_e32 v70, v71, v70
	v_div_scale_f32 v71, vcc, v39, v68, v39
	v_mul_f32_e32 v72, v71, v70
	v_fma_f32 v73, -v66, v72, v71
	v_fmac_f32_e32 v72, v73, v70
	v_fma_f32 v66, -v66, v72, v71
	v_div_fmas_f32 v66, v66, v70, v72
	v_div_fixup_f32 v68, v66, v68, v39
	v_pk_mul_f32 v[34:35], v[68:69], v[34:35]
	v_lshlrev_b32_e32 v39, 16, v67
	v_cvt_pk_bf16_f32 v66, v34, v35
	v_mul_f32_e32 v34, 0xbfb8aa3b, v39
	v_fma_f32 v35, v39, s89, -v34
	v_rndne_f32_e32 v68, v34
	v_fmac_f32_e32 v35, 0xb2a5705f, v39
	v_sub_f32_e32 v34, v34, v68
	v_add_f32_e32 v34, v34, v35
	v_exp_f32_e32 v34, v34
	v_cvt_i32_f32_e32 v35, v68
	v_and_b32_e32 v67, 0xffff0000, v67
	v_cmp_nlt_f32_e32 vcc, s96, v39
	v_ldexp_f32 v34, v34, v35
	v_mul_f32_e32 v35, 0xbfb8aa3b, v67
	v_fma_f32 v68, v67, s89, -v35
	v_rndne_f32_e32 v69, v35
	v_fmac_f32_e32 v68, 0xb2a5705f, v67
	v_sub_f32_e32 v35, v35, v69
	v_add_f32_e32 v35, v35, v68
	v_exp_f32_e32 v35, v35
	v_cvt_i32_f32_e32 v68, v69
	v_cndmask_b32_e32 v34, 0, v34, vcc
; DI unsigned pk2(float lo, float hi) { f32x2 f = {lo, hi}; bf2_t v = __builtin_convertvector(f, bf2_t); return __builtin_bit_cast(unsigned, v); }
; DI void gla_finish_phase(int wv, const float* obuf, const bf16_t* rb, const float* gn, bf16_t* ob) {
;     ...
;             for (int i = 0; i < 4; ++i) {
;                 const f32x4 x = v[u][i];
;                 const float ss = wave_sum((x.x * x.x + x.y * x.y) + (x.z * x.z + x.w * x.w));
;                 const float rn = 1.f / sqrtf(ss * (1.f / 256.f) + 1e-6f);
;                 const u32x2 r_ = rw[u][i];
;                 const float r0 = __uint_as_float(r_.x << 16), r1 = __uint_as_float(r_.x & 0xffff0000u), r2 = __uint_as_float(r_.y << 16), r3 = __uint_as_float(r_.y & 0xffff0000u);
;                 const float s0 = r0 / (1.f + expf(-r0)), s1 = r1 / (1.f + expf(-r1)), s2 = r2 / (1.f + expf(-r2)), s3 = r3 / (1.f + expf(-r3));
;                 u32x2 w; w.x = pk2(x.x * rn * g4.x * s0, x.y * rn * g4.y * s1); w.y = pk2(x.z * rn * g4.z * s2, x.w * rn * g4.w * s3);
;                 ((u32x2*)(ob + (size_t)row * 1024))[lane + 64 * i] = w;
	v_cmp_ngt_f32_e32 vcc, s97, v39
	v_ldexp_f32 v35, v35, v68
	s_nop 0
	v_cndmask_b32_e32 v34, v246, v34, vcc
	v_cmp_nlt_f32_e32 vcc, s96, v67
	s_nop 1
	v_cndmask_b32_e32 v35, 0, v35, vcc
	v_cmp_ngt_f32_e32 vcc, s97, v67
	s_nop 1
	v_cndmask_b32_e32 v35, v246, v35, vcc
	v_pk_add_f32 v[34:35], v[34:35], 1.0 op_sel_hi:[1,0]
	s_nop 0
	v_div_scale_f32 v68, s[4:5], v35, v35, v67
	v_rcp_f32_e32 v69, v68
	s_nop 0
	v_fma_f32 v70, -v68, v69, 1.0
	v_fmac_f32_e32 v69, v70, v69
	v_div_scale_f32 v70, vcc, v67, v35, v67
	v_mul_f32_e32 v71, v70, v69
	v_fma_f32 v72, -v68, v71, v70
	v_fmac_f32_e32 v71, v72, v69
	v_fma_f32 v68, -v68, v71, v70
	v_div_fmas_f32 v68, v68, v69, v71
	v_div_fixup_f32 v35, v68, v35, v67
	v_div_scale_f32 v67, s[4:5], v34, v34, v39
	v_rcp_f32_e32 v68, v67
	s_nop 0
	v_fma_f32 v69, -v67, v68, 1.0
	v_fmac_f32_e32 v68, v69, v68
	v_div_scale_f32 v69, vcc, v39, v34, v39
	v_mul_f32_e32 v70, v69, v68
	v_fma_f32 v71, -v67, v70, v69
	v_fmac_f32_e32 v70, v71, v68
	v_fma_f32 v67, -v67, v70, v69
	v_div_fmas_f32 v67, v67, v68, v70
	v_div_fixup_f32 v34, v67, v34, v39
	v_pk_mul_f32 v[34:35], v[34:35], v[36:37]
	v_pk_mul_f32 v[36:37], v[32:33], v[32:33]
	v_cvt_pk_bf16_f32 v67, v34, v35
	v_lshl_add_u64 v[34:35], s[48:49], 0, v[46:47]
	global_store_dwordx2 v[34:35], v[66:67], off offset:-1024
	v_pk_mul_f32 v[66:67], v[30:31], v[30:31]
	s_nop 0
	v_pk_mov_b32 v[68:69], v[66:67], v[36:37] op_sel:[1,0]
	v_mov_b32_e32 v67, v37
	v_pk_add_f32 v[36:37], v[68:69], v[66:67]
	s_nop 0
	v_add_f32_e32 v0, v36, v37
	ds_bpermute_b32 v36, v233, v0
	s_waitcnt lgkmcnt(0)
	v_add_f32_e32 v0, v0, v36
	ds_bpermute_b32 v36, v234, v0
	s_waitcnt lgkmcnt(0)
	v_add_f32_e32 v0, v0, v36
	ds_bpermute_b32 v36, v235, v0
	s_waitcnt lgkmcnt(0)
	v_add_f32_e32 v0, v0, v36
	ds_bpermute_b32 v36, v236, v0
	s_waitcnt lgkmcnt(0)
	v_add_f32_e32 v0, v0, v36
	ds_bpermute_b32 v36, v237, v0
	s_waitcnt lgkmcnt(0)
	v_add_f32_e32 v0, v0, v36
	ds_bpermute_b32 v36, v238, v0
	s_waitcnt lgkmcnt(0)
	v_add_f32_e32 v0, v0, v36
	v_fmamk_f32 v0, v0, 0x3b800000, v241
	v_cmp_gt_f32_e32 vcc, s2, v0
	v_mul_f32_e32 v36, 0x4f800000, v0
	s_nop 0
	v_cndmask_b32_e32 v0, v0, v36, vcc
	v_sqrt_f32_e32 v36, v0
	s_nop 0
	v_add_u32_e32 v37, -1, v36
	v_fma_f32 v39, -v37, v36, v0
	v_cmp_ge_f32_e64 s[4:5], 0, v39
	v_add_u32_e32 v39, 1, v36
	s_nop 0
	v_cndmask_b32_e64 v37, v36, v37, s[4:5]
	v_fma_f32 v36, -v39, v36, v0
	v_cmp_lt_f32_e64 s[4:5], 0, v36
	s_nop 1
	v_cndmask_b32_e64 v36, v37, v39, s[4:5]
	v_mul_f32_e32 v37, 0x37800000, v36
	v_cndmask_b32_e32 v36, v36, v37, vcc
	v_cmp_class_f32_e32 vcc, v0, v242
	s_nop 1
	v_cndmask_b32_e32 v0, v36, v0, vcc
	v_div_scale_f32 v36, s[4:5], v0, v0, 1.0
	v_rcp_f32_e32 v37, v36
	s_nop 0
	v_fma_f32 v39, -v36, v37, 1.0
	v_fmac_f32_e32 v37, v39, v37
	v_div_scale_f32 v39, vcc, 1.0, v0, 1.0
	v_mul_f32_e32 v66, v39, v37
	v_fma_f32 v67, -v36, v66, v39
	v_fmac_f32_e32 v66, v67, v37
	v_fma_f32 v36, -v36, v66, v39
	v_div_fmas_f32 v36, v36, v37, v66
	v_lshlrev_b32_e32 v39, 16, v64
	v_div_fixup_f32 v0, v36, v0, 1.0
	v_mul_f32_e32 v36, 0xbfb8aa3b, v39
	v_fma_f32 v37, v39, s89, -v36
	v_rndne_f32_e32 v66, v36
	v_fmac_f32_e32 v37, 0xb2a5705f, v39
	v_sub_f32_e32 v36, v36, v66
	v_add_f32_e32 v36, v36, v37
	v_exp_f32_e32 v36, v36
	v_cvt_i32_f32_e32 v37, v66
	v_and_b32_e32 v64, 0xffff0000, v64
	v_cmp_nlt_f32_e32 vcc, s96, v39
	v_pk_mul_f32 v[30:31], v[30:31], v[0:1] op_sel_hi:[1,0]
	v_ldexp_f32 v36, v36, v37
	v_mul_f32_e32 v37, 0xbfb8aa3b, v64
	v_fma_f32 v66, v64, s89, -v37
	v_rndne_f32_e32 v67, v37
	v_fmac_f32_e32 v66, 0xb2a5705f, v64
	v_sub_f32_e32 v37, v37, v67
	v_add_f32_e32 v37, v37, v66
	v_exp_f32_e32 v37, v37
	v_cvt_i32_f32_e32 v66, v67
	v_cndmask_b32_e32 v36, 0, v36, vcc
	v_cmp_ngt_f32_e32 vcc, s97, v39
	v_pk_mul_f32 v[30:31], v[2:3], v[30:31]
	v_ldexp_f32 v37, v37, v66
	v_cndmask_b32_e32 v36, v246, v36, vcc
	v_cmp_nlt_f32_e32 vcc, s96, v64
	v_pk_mul_f32 v[32:33], v[32:33], v[0:1] op_sel_hi:[1,0]
	s_nop 0
	v_cndmask_b32_e32 v37, 0, v37, vcc
	v_cmp_ngt_f32_e32 vcc, s97, v64
	v_pk_mul_f32 v[32:33], v[4:5], v[32:33]
	s_nop 0
	v_cndmask_b32_e32 v37, v246, v37, vcc
	v_pk_add_f32 v[36:37], v[36:37], 1.0 op_sel_hi:[1,0]
	s_nop 0
	v_div_scale_f32 v66, s[4:5], v37, v37, v64
	v_rcp_f32_e32 v67, v66
	s_nop 0
	v_fma_f32 v68, -v66, v67, 1.0
	v_fmac_f32_e32 v67, v68, v67
	v_div_scale_f32 v68, vcc, v64, v37, v64
	v_mul_f32_e32 v69, v68, v67
	v_fma_f32 v70, -v66, v69, v68
	v_fmac_f32_e32 v69, v70, v67
	v_fma_f32 v66, -v66, v69, v68
	v_div_fmas_f32 v66, v66, v67, v69
	v_div_fixup_f32 v37, v66, v37, v64
	v_div_scale_f32 v64, s[4:5], v36, v36, v39
	v_rcp_f32_e32 v66, v64
	s_nop 0
	v_fma_f32 v67, -v64, v66, 1.0
	v_fmac_f32_e32 v66, v67, v66
	v_div_scale_f32 v67, vcc, v39, v36, v39
	v_mul_f32_e32 v68, v67, v66
	v_fma_f32 v69, -v64, v68, v67
	v_fmac_f32_e32 v68, v69, v66
	v_fma_f32 v64, -v64, v68, v67
	v_div_fmas_f32 v64, v64, v66, v68
	v_div_fixup_f32 v36, v64, v36, v39
	v_pk_mul_f32 v[30:31], v[36:37], v[30:31]
	v_and_b32_e32 v39, 0xffff0000, v65
	v_cvt_pk_bf16_f32 v30, v30, v31
	v_lshlrev_b32_e32 v31, 16, v65
	v_mul_f32_e32 v36, 0xbfb8aa3b, v31
	v_fma_f32 v37, v31, s89, -v36
	v_rndne_f32_e32 v64, v36
	v_fmac_f32_e32 v37, 0xb2a5705f, v31
	v_sub_f32_e32 v36, v36, v64
	v_add_f32_e32 v36, v36, v37
	v_exp_f32_e32 v36, v36
	v_cvt_i32_f32_e32 v37, v64
	v_cmp_nlt_f32_e32 vcc, s96, v31
	v_ldexp_f32 v36, v36, v37
	v_mul_f32_e32 v37, 0xbfb8aa3b, v39
	v_fma_f32 v64, v39, s89, -v37
	v_rndne_f32_e32 v65, v37
	v_fmac_f32_e32 v64, 0xb2a5705f, v39
	v_sub_f32_e32 v37, v37, v65
	v_add_f32_e32 v37, v37, v64
	v_exp_f32_e32 v37, v37
	v_cvt_i32_f32_e32 v64, v65
	v_cndmask_b32_e32 v36, 0, v36, vcc
	v_cmp_ngt_f32_e32 vcc, s97, v31
; DI unsigned pk2(float lo, float hi) { f32x2 f = {lo, hi}; bf2_t v = __builtin_convertvector(f, bf2_t); return __builtin_bit_cast(unsigned, v); }
; DI void gla_finish_phase(int wv, const float* obuf, const bf16_t* rb, const float* gn, bf16_t* ob) {
;     ...
;             for (int i = 0; i < 4; ++i) {
;                 const f32x4 x = v[u][i];
;                 const float ss = wave_sum((x.x * x.x + x.y * x.y) + (x.z * x.z + x.w * x.w));
;                 const float rn = 1.f / sqrtf(ss * (1.f / 256.f) + 1e-6f);
;                 const u32x2 r_ = rw[u][i];
;                 const float r0 = __uint_as_float(r_.x << 16), r1 = __uint_as_float(r_.x & 0xffff0000u), r2 = __uint_as_float(r_.y << 16), r3 = __uint_as_float(r_.y & 0xffff0000u);
;                 const float s0 = r0 / (1.f + expf(-r0)), s1 = r1 / (1.f + expf(-r1)), s2 = r2 / (1.f + expf(-r2)), s3 = r3 / (1.f + expf(-r3));
;                 u32x2 w; w.x = pk2(x.x * rn * g4.x * s0, x.y * rn * g4.y * s1); w.y = pk2(x.z * rn * g4.z * s2, x.w * rn * g4.w * s3);
;                 ((u32x2*)(ob + (size_t)row * 1024))[lane + 64 * i] = w;
	v_ldexp_f32 v37, v37, v64
	s_nop 0
	v_cndmask_b32_e32 v36, v246, v36, vcc
	v_cmp_nlt_f32_e32 vcc, s96, v39
	s_nop 1
	v_cndmask_b32_e32 v37, 0, v37, vcc
	v_cmp_ngt_f32_e32 vcc, s97, v39
	s_nop 1
	v_cndmask_b32_e32 v37, v246, v37, vcc
	v_pk_add_f32 v[36:37], v[36:37], 1.0 op_sel_hi:[1,0]
	s_nop 0
	v_div_scale_f32 v64, s[4:5], v37, v37, v39
	v_rcp_f32_e32 v65, v64
	s_nop 0
	v_fma_f32 v66, -v64, v65, 1.0
	v_fmac_f32_e32 v65, v66, v65
	v_div_scale_f32 v66, vcc, v39, v37, v39
	v_mul_f32_e32 v67, v66, v65
	v_fma_f32 v68, -v64, v67, v66
	v_fmac_f32_e32 v67, v68, v65
	v_fma_f32 v64, -v64, v67, v66
	v_div_fmas_f32 v64, v64, v65, v67
	v_div_fixup_f32 v37, v64, v37, v39
	v_div_scale_f32 v39, s[4:5], v36, v36, v31
	v_rcp_f32_e32 v64, v39
	s_nop 0
	v_fma_f32 v65, -v39, v64, 1.0
	v_fmac_f32_e32 v64, v65, v64
	v_div_scale_f32 v65, vcc, v31, v36, v31
	v_mul_f32_e32 v66, v65, v64
	v_fma_f32 v67, -v39, v66, v65
	v_fmac_f32_e32 v66, v67, v64
	v_fma_f32 v39, -v39, v66, v65
	v_div_fmas_f32 v39, v39, v64, v66
	v_div_fixup_f32 v36, v39, v36, v31
	v_pk_mul_f32 v[32:33], v[36:37], v[32:33]
	s_nop 0
	v_cvt_pk_bf16_f32 v31, v32, v33
	global_store_dwordx2 v[34:35], v[30:31], off offset:-512
	v_pk_mul_f32 v[30:31], v[28:29], v[28:29]
	v_pk_mul_f32 v[32:33], v[26:27], v[26:27]
	s_nop 0
	v_pk_mov_b32 v[36:37], v[32:33], v[30:31] op_sel:[1,0]
	v_mov_b32_e32 v33, v31
	v_pk_add_f32 v[30:31], v[36:37], v[32:33]
	s_nop 0
	v_add_f32_e32 v0, v30, v31
	ds_bpermute_b32 v30, v233, v0
	s_waitcnt lgkmcnt(0)
	v_add_f32_e32 v0, v0, v30
	ds_bpermute_b32 v30, v234, v0
	s_waitcnt lgkmcnt(0)
	v_add_f32_e32 v0, v0, v30
	ds_bpermute_b32 v30, v235, v0
	s_waitcnt lgkmcnt(0)
	v_add_f32_e32 v0, v0, v30
	ds_bpermute_b32 v30, v236, v0
	s_waitcnt lgkmcnt(0)
	v_add_f32_e32 v0, v0, v30
	ds_bpermute_b32 v30, v237, v0
	s_waitcnt lgkmcnt(0)
	v_add_f32_e32 v0, v0, v30
	ds_bpermute_b32 v30, v238, v0
	s_waitcnt lgkmcnt(0)
	v_add_f32_e32 v0, v0, v30
	v_fmamk_f32 v0, v0, 0x3b800000, v241
	v_cmp_gt_f32_e32 vcc, s2, v0
	v_mul_f32_e32 v30, 0x4f800000, v0
	s_nop 0
	v_cndmask_b32_e32 v0, v0, v30, vcc
	v_sqrt_f32_e32 v30, v0
	s_nop 0
	v_add_u32_e32 v31, -1, v30
	v_fma_f32 v32, -v31, v30, v0
	v_cmp_ge_f32_e64 s[4:5], 0, v32
	v_add_u32_e32 v32, 1, v30
	s_nop 0
	v_cndmask_b32_e64 v31, v30, v31, s[4:5]
	v_fma_f32 v30, -v32, v30, v0
	v_cmp_lt_f32_e64 s[4:5], 0, v30
	s_nop 1
	v_cndmask_b32_e64 v30, v31, v32, s[4:5]
	v_mul_f32_e32 v31, 0x37800000, v30
	v_cndmask_b32_e32 v30, v30, v31, vcc
	v_cmp_class_f32_e32 vcc, v0, v242
	s_nop 1
	v_cndmask_b32_e32 v0, v30, v0, vcc
	v_div_scale_f32 v30, s[4:5], v0, v0, 1.0
	v_rcp_f32_e32 v31, v30
	s_nop 0
	v_fma_f32 v32, -v30, v31, 1.0
	v_fmac_f32_e32 v31, v32, v31
	v_div_scale_f32 v32, vcc, 1.0, v0, 1.0
	v_mul_f32_e32 v33, v32, v31
	v_fma_f32 v36, -v30, v33, v32
	v_fmac_f32_e32 v33, v36, v31
	v_fma_f32 v30, -v30, v33, v32
	v_div_fmas_f32 v30, v30, v31, v33
	v_lshlrev_b32_e32 v32, 16, v62
	v_div_fixup_f32 v0, v30, v0, 1.0
	v_mul_f32_e32 v30, 0xbfb8aa3b, v32
	v_fma_f32 v31, v32, s89, -v30
	v_rndne_f32_e32 v36, v30
	v_fmac_f32_e32 v31, 0xb2a5705f, v32
	v_sub_f32_e32 v30, v30, v36
	v_add_f32_e32 v30, v30, v31
	v_exp_f32_e32 v30, v30
	v_cvt_i32_f32_e32 v31, v36
	v_and_b32_e32 v33, 0xffff0000, v62
	v_cmp_nlt_f32_e32 vcc, s96, v32
	v_pk_mul_f32 v[26:27], v[26:27], v[0:1] op_sel_hi:[1,0]
	v_ldexp_f32 v30, v30, v31
	v_mul_f32_e32 v31, 0xbfb8aa3b, v33
	v_fma_f32 v36, v33, s89, -v31
	v_rndne_f32_e32 v37, v31
	v_fmac_f32_e32 v36, 0xb2a5705f, v33
	v_sub_f32_e32 v31, v31, v37
	v_add_f32_e32 v31, v31, v36
	v_exp_f32_e32 v31, v31
	v_cvt_i32_f32_e32 v36, v37
	v_cndmask_b32_e32 v30, 0, v30, vcc
	v_cmp_ngt_f32_e32 vcc, s97, v32
	v_pk_mul_f32 v[26:27], v[2:3], v[26:27]
	v_ldexp_f32 v31, v31, v36
	v_cndmask_b32_e32 v30, v246, v30, vcc
	v_cmp_nlt_f32_e32 vcc, s96, v33
	v_pk_mul_f32 v[28:29], v[28:29], v[0:1] op_sel_hi:[1,0]
	s_nop 0
	v_cndmask_b32_e32 v31, 0, v31, vcc
	v_cmp_ngt_f32_e32 vcc, s97, v33
	v_pk_mul_f32 v[28:29], v[4:5], v[28:29]
	s_nop 0
	v_cndmask_b32_e32 v31, v246, v31, vcc
	v_pk_add_f32 v[30:31], v[30:31], 1.0 op_sel_hi:[1,0]
	s_nop 0
	v_div_scale_f32 v36, s[4:5], v31, v31, v33
	v_rcp_f32_e32 v37, v36
	s_nop 0
	v_fma_f32 v39, -v36, v37, 1.0
	v_fmac_f32_e32 v37, v39, v37
	v_div_scale_f32 v39, vcc, v33, v31, v33
	v_mul_f32_e32 v62, v39, v37
	v_fma_f32 v64, -v36, v62, v39
	v_fmac_f32_e32 v62, v64, v37
	v_fma_f32 v36, -v36, v62, v39
	v_div_fmas_f32 v36, v36, v37, v62
	v_div_fixup_f32 v31, v36, v31, v33
	v_div_scale_f32 v33, s[4:5], v30, v30, v32
	v_rcp_f32_e32 v36, v33
	s_nop 0
	v_fma_f32 v37, -v33, v36, 1.0
	v_fmac_f32_e32 v36, v37, v36
	v_div_scale_f32 v37, vcc, v32, v30, v32
	v_mul_f32_e32 v39, v37, v36
	v_fma_f32 v62, -v33, v39, v37
	v_fmac_f32_e32 v39, v62, v36
	v_fma_f32 v33, -v33, v39, v37
	v_div_fmas_f32 v33, v33, v36, v39
	v_div_fixup_f32 v30, v33, v30, v32
	v_pk_mul_f32 v[26:27], v[30:31], v[26:27]
	v_and_b32_e32 v32, 0xffff0000, v63
	v_cvt_pk_bf16_f32 v26, v26, v27
	v_lshlrev_b32_e32 v27, 16, v63
	v_mul_f32_e32 v30, 0xbfb8aa3b, v27
	v_fma_f32 v31, v27, s89, -v30
	v_rndne_f32_e32 v33, v30
	v_fmac_f32_e32 v31, 0xb2a5705f, v27
	v_sub_f32_e32 v30, v30, v33
	v_add_f32_e32 v30, v30, v31
	v_exp_f32_e32 v30, v30
	v_cvt_i32_f32_e32 v31, v33
	v_cmp_nlt_f32_e32 vcc, s96, v27
	v_ldexp_f32 v30, v30, v31
	v_mul_f32_e32 v31, 0xbfb8aa3b, v32
	v_fma_f32 v33, v32, s89, -v31
	v_rndne_f32_e32 v36, v31
	v_fmac_f32_e32 v33, 0xb2a5705f, v32
	v_sub_f32_e32 v31, v31, v36
	v_add_f32_e32 v31, v31, v33
	v_exp_f32_e32 v31, v31
	v_cvt_i32_f32_e32 v33, v36
	v_cndmask_b32_e32 v30, 0, v30, vcc
	v_cmp_ngt_f32_e32 vcc, s97, v27
	v_ldexp_f32 v31, v31, v33
	s_nop 0
	v_cndmask_b32_e32 v30, v246, v30, vcc
	v_cmp_nlt_f32_e32 vcc, s96, v32
	s_nop 1
	v_cndmask_b32_e32 v31, 0, v31, vcc
	v_cmp_ngt_f32_e32 vcc, s97, v32
	s_nop 1
	v_cndmask_b32_e32 v31, v246, v31, vcc
	v_pk_add_f32 v[30:31], v[30:31], 1.0 op_sel_hi:[1,0]
	s_nop 0
	v_div_scale_f32 v33, s[4:5], v31, v31, v32
	v_rcp_f32_e32 v36, v33
	s_nop 0
	v_fma_f32 v37, -v33, v36, 1.0
	v_fmac_f32_e32 v36, v37, v36
	v_div_scale_f32 v37, vcc, v32, v31, v32
	v_mul_f32_e32 v39, v37, v36
	v_fma_f32 v62, -v33, v39, v37
	v_fmac_f32_e32 v39, v62, v36
	v_fma_f32 v33, -v33, v39, v37
	v_div_fmas_f32 v33, v33, v36, v39
	v_div_fixup_f32 v31, v33, v31, v32
	v_div_scale_f32 v32, s[4:5], v30, v30, v27
	v_rcp_f32_e32 v33, v32
	s_nop 0
	v_fma_f32 v36, -v32, v33, 1.0
	v_fmac_f32_e32 v33, v36, v33
	v_div_scale_f32 v36, vcc, v27, v30, v27
	v_mul_f32_e32 v37, v36, v33
	v_fma_f32 v39, -v32, v37, v36
	v_fmac_f32_e32 v37, v39, v33
	v_fma_f32 v32, -v32, v37, v36
	v_div_fmas_f32 v32, v32, v33, v37
	v_div_fixup_f32 v30, v32, v30, v27
	v_pk_mul_f32 v[28:29], v[30:31], v[28:29]
	s_nop 0
	v_cvt_pk_bf16_f32 v27, v28, v29
	global_store_dwordx2 v[34:35], v[26:27], off
	v_pk_mul_f32 v[26:27], v[24:25], v[24:25]
	v_pk_mul_f32 v[28:29], v[22:23], v[22:23]
	s_nop 0
	v_pk_mov_b32 v[30:31], v[28:29], v[26:27] op_sel:[1,0]
	v_mov_b32_e32 v29, v27
	v_pk_add_f32 v[26:27], v[30:31], v[28:29]
	s_nop 0
	v_add_f32_e32 v0, v26, v27
	ds_bpermute_b32 v26, v233, v0
	s_waitcnt lgkmcnt(0)
; DI unsigned pk2(float lo, float hi) { f32x2 f = {lo, hi}; bf2_t v = __builtin_convertvector(f, bf2_t); return __builtin_bit_cast(unsigned, v); }
; DI void gla_finish_phase(int wv, const float* obuf, const bf16_t* rb, const float* gn, bf16_t* ob) {
;     ...
;         for (int u = 0; u < 2; ++u) { const int row = row0 + u * nw; if (row < M_TOK) {
; #pragma unroll
;             for (int i = 0; i < 4; ++i) {
;                 const f32x4 x = v[u][i];
;                 const float ss = wave_sum((x.x * x.x + x.y * x.y) + (x.z * x.z + x.w * x.w));
;                 const float rn = 1.f / sqrtf(ss * (1.f / 256.f) + 1e-6f);
;                 const u32x2 r_ = rw[u][i];
;                 const float r0 = __uint_as_float(r_.x << 16), r1 = __uint_as_float(r_.x & 0xffff0000u), r2 = __uint_as_float(r_.y << 16), r3 = __uint_as_float(r_.y & 0xffff0000u);
;                 const float s0 = r0 / (1.f + expf(-r0)), s1 = r1 / (1.f + expf(-r1)), s2 = r2 / (1.f + expf(-r2)), s3 = r3 / (1.f + expf(-r3));
;                 u32x2 w; w.x = pk2(x.x * rn * g4.x * s0, x.y * rn * g4.y * s1); w.y = pk2(x.z * rn * g4.z * s2, x.w * rn * g4.w * s3);
;                 ((u32x2*)(ob + (size_t)row * 1024))[lane + 64 * i] = w;
	v_add_f32_e32 v0, v0, v26
	ds_bpermute_b32 v26, v234, v0
	s_waitcnt lgkmcnt(0)
	v_add_f32_e32 v0, v0, v26
	ds_bpermute_b32 v26, v235, v0
	s_waitcnt lgkmcnt(0)
	v_add_f32_e32 v0, v0, v26
	ds_bpermute_b32 v26, v236, v0
	s_waitcnt lgkmcnt(0)
	v_add_f32_e32 v0, v0, v26
	ds_bpermute_b32 v26, v237, v0
	s_waitcnt lgkmcnt(0)
	v_add_f32_e32 v0, v0, v26
	ds_bpermute_b32 v26, v238, v0
	s_waitcnt lgkmcnt(0)
	v_add_f32_e32 v0, v0, v26
	v_fmamk_f32 v0, v0, 0x3b800000, v241
	v_cmp_gt_f32_e32 vcc, s2, v0
	v_mul_f32_e32 v26, 0x4f800000, v0
	s_nop 0
	v_cndmask_b32_e32 v0, v0, v26, vcc
	v_sqrt_f32_e32 v26, v0
	s_nop 0
	v_add_u32_e32 v27, -1, v26
	v_fma_f32 v28, -v27, v26, v0
	v_cmp_ge_f32_e64 s[4:5], 0, v28
	v_add_u32_e32 v28, 1, v26
	s_nop 0
	v_cndmask_b32_e64 v27, v26, v27, s[4:5]
	v_fma_f32 v26, -v28, v26, v0
	v_cmp_lt_f32_e64 s[4:5], 0, v26
	s_nop 1
	v_cndmask_b32_e64 v26, v27, v28, s[4:5]
	v_mul_f32_e32 v27, 0x37800000, v26
	v_cndmask_b32_e32 v26, v26, v27, vcc
	v_cmp_class_f32_e32 vcc, v0, v242
	s_nop 1
	v_cndmask_b32_e32 v0, v26, v0, vcc
	v_div_scale_f32 v26, s[4:5], v0, v0, 1.0
	v_rcp_f32_e32 v27, v26
	s_nop 0
	v_fma_f32 v28, -v26, v27, 1.0
	v_fmac_f32_e32 v27, v28, v27
	v_div_scale_f32 v28, vcc, 1.0, v0, 1.0
	v_mul_f32_e32 v29, v28, v27
	v_fma_f32 v30, -v26, v29, v28
	v_fmac_f32_e32 v29, v30, v27
	v_fma_f32 v26, -v26, v29, v28
	v_div_fmas_f32 v26, v26, v27, v29
	v_lshlrev_b32_e32 v28, 16, v60
	v_div_fixup_f32 v0, v26, v0, 1.0
	v_mul_f32_e32 v26, 0xbfb8aa3b, v28
	v_fma_f32 v27, v28, s89, -v26
	v_rndne_f32_e32 v30, v26
	v_fmac_f32_e32 v27, 0xb2a5705f, v28
	v_sub_f32_e32 v26, v26, v30
	v_add_f32_e32 v26, v26, v27
	v_exp_f32_e32 v26, v26
	v_cvt_i32_f32_e32 v27, v30
	v_and_b32_e32 v29, 0xffff0000, v60
	v_cmp_nlt_f32_e32 vcc, s96, v28
	v_pk_mul_f32 v[22:23], v[22:23], v[0:1] op_sel_hi:[1,0]
	v_ldexp_f32 v26, v26, v27
	v_mul_f32_e32 v27, 0xbfb8aa3b, v29
	v_fma_f32 v30, v29, s89, -v27
	v_rndne_f32_e32 v31, v27
	v_fmac_f32_e32 v30, 0xb2a5705f, v29
	v_sub_f32_e32 v27, v27, v31
	v_add_f32_e32 v27, v27, v30
	v_exp_f32_e32 v27, v27
	v_cvt_i32_f32_e32 v30, v31
	v_cndmask_b32_e32 v26, 0, v26, vcc
	v_cmp_ngt_f32_e32 vcc, s97, v28
	v_pk_mul_f32 v[22:23], v[2:3], v[22:23]
	v_ldexp_f32 v27, v27, v30
	v_cndmask_b32_e32 v26, v246, v26, vcc
	v_cmp_nlt_f32_e32 vcc, s96, v29
	v_pk_mul_f32 v[24:25], v[24:25], v[0:1] op_sel_hi:[1,0]
	s_nop 0
	v_cndmask_b32_e32 v27, 0, v27, vcc
	v_cmp_ngt_f32_e32 vcc, s97, v29
	v_pk_mul_f32 v[24:25], v[4:5], v[24:25]
	s_nop 0
	v_cndmask_b32_e32 v27, v246, v27, vcc
	v_pk_add_f32 v[26:27], v[26:27], 1.0 op_sel_hi:[1,0]
	s_nop 0
	v_div_scale_f32 v30, s[4:5], v27, v27, v29
	v_rcp_f32_e32 v31, v30
	s_nop 0
	v_fma_f32 v32, -v30, v31, 1.0
	v_fmac_f32_e32 v31, v32, v31
	v_div_scale_f32 v32, vcc, v29, v27, v29
	v_mul_f32_e32 v33, v32, v31
	v_fma_f32 v36, -v30, v33, v32
	v_fmac_f32_e32 v33, v36, v31
	v_fma_f32 v30, -v30, v33, v32
	v_div_fmas_f32 v30, v30, v31, v33
	v_div_fixup_f32 v27, v30, v27, v29
	v_div_scale_f32 v29, s[4:5], v26, v26, v28
	v_rcp_f32_e32 v30, v29
	s_nop 0
	v_fma_f32 v31, -v29, v30, 1.0
	v_fmac_f32_e32 v30, v31, v30
	v_div_scale_f32 v31, vcc, v28, v26, v28
	v_mul_f32_e32 v32, v31, v30
	v_fma_f32 v33, -v29, v32, v31
	v_fmac_f32_e32 v32, v33, v30
	v_fma_f32 v29, -v29, v32, v31
	v_div_fmas_f32 v29, v29, v30, v32
	v_div_fixup_f32 v26, v29, v26, v28
	v_pk_mul_f32 v[22:23], v[26:27], v[22:23]
	v_and_b32_e32 v28, 0xffff0000, v61
	v_cvt_pk_bf16_f32 v22, v22, v23
	v_lshlrev_b32_e32 v23, 16, v61
	v_mul_f32_e32 v26, 0xbfb8aa3b, v23
	v_fma_f32 v27, v23, s89, -v26
	v_rndne_f32_e32 v29, v26
	v_fmac_f32_e32 v27, 0xb2a5705f, v23
	v_sub_f32_e32 v26, v26, v29
	v_add_f32_e32 v26, v26, v27
	v_exp_f32_e32 v26, v26
	v_cvt_i32_f32_e32 v27, v29
	v_cmp_nlt_f32_e32 vcc, s96, v23
	v_ldexp_f32 v26, v26, v27
	v_mul_f32_e32 v27, 0xbfb8aa3b, v28
	v_fma_f32 v29, v28, s89, -v27
	v_rndne_f32_e32 v30, v27
	v_fmac_f32_e32 v29, 0xb2a5705f, v28
	v_sub_f32_e32 v27, v27, v30
	v_add_f32_e32 v27, v27, v29
	v_exp_f32_e32 v27, v27
	v_cvt_i32_f32_e32 v29, v30
	v_cndmask_b32_e32 v26, 0, v26, vcc
	v_cmp_ngt_f32_e32 vcc, s97, v23
	v_ldexp_f32 v27, v27, v29
	s_nop 0
	v_cndmask_b32_e32 v26, v246, v26, vcc
	v_cmp_nlt_f32_e32 vcc, s96, v28
	s_nop 1
	v_cndmask_b32_e32 v27, 0, v27, vcc
	v_cmp_ngt_f32_e32 vcc, s97, v28
	s_nop 1
	v_cndmask_b32_e32 v27, v246, v27, vcc
	v_pk_add_f32 v[26:27], v[26:27], 1.0 op_sel_hi:[1,0]
	s_nop 0
	v_div_scale_f32 v29, s[4:5], v27, v27, v28
	v_rcp_f32_e32 v30, v29
	s_nop 0
	v_fma_f32 v31, -v29, v30, 1.0
	v_fmac_f32_e32 v30, v31, v30
	v_div_scale_f32 v31, vcc, v28, v27, v28
	v_mul_f32_e32 v32, v31, v30
	v_fma_f32 v33, -v29, v32, v31
	v_fmac_f32_e32 v32, v33, v30
	v_fma_f32 v29, -v29, v32, v31
	v_div_fmas_f32 v29, v29, v30, v32
	v_div_fixup_f32 v27, v29, v27, v28
	v_div_scale_f32 v28, s[4:5], v26, v26, v23
	v_rcp_f32_e32 v29, v28
	s_nop 0
	v_fma_f32 v30, -v28, v29, 1.0
	v_fmac_f32_e32 v29, v30, v29
	v_div_scale_f32 v30, vcc, v23, v26, v23
	v_mul_f32_e32 v31, v30, v29
	v_fma_f32 v32, -v28, v31, v30
	v_fmac_f32_e32 v31, v32, v29
	v_fma_f32 v28, -v28, v31, v30
	v_div_fmas_f32 v28, v28, v29, v31
	v_div_fixup_f32 v26, v28, v26, v23
	v_pk_mul_f32 v[24:25], v[26:27], v[24:25]
	s_nop 0
	v_cvt_pk_bf16_f32 v23, v24, v25
	global_store_dwordx2 v[34:35], v[22:23], off offset:512
	s_and_saveexec_b64 s[4:5], s[0:1]
	s_cbranch_execz .LBB0_237
; DI unsigned pk2(float lo, float hi) { f32x2 f = {lo, hi}; bf2_t v = __builtin_convertvector(f, bf2_t); return __builtin_bit_cast(unsigned, v); }
; DI void gla_finish_phase(int wv, const float* obuf, const bf16_t* rb, const float* gn, bf16_t* ob) {
;     ...
;             for (int i = 0; i < 4; ++i) {
;                 const f32x4 x = v[u][i];
;                 const float ss = wave_sum((x.x * x.x + x.y * x.y) + (x.z * x.z + x.w * x.w));
;                 const float rn = 1.f / sqrtf(ss * (1.f / 256.f) + 1e-6f);
;                 const u32x2 r_ = rw[u][i];
;                 const float r0 = __uint_as_float(r_.x << 16), r1 = __uint_as_float(r_.x & 0xffff0000u), r2 = __uint_as_float(r_.y << 16), r3 = __uint_as_float(r_.y & 0xffff0000u);
;                 const float s0 = r0 / (1.f + expf(-r0)), s1 = r1 / (1.f + expf(-r1)), s2 = r2 / (1.f + expf(-r2)), s3 = r3 / (1.f + expf(-r3));
;                 u32x2 w; w.x = pk2(x.x * rn * g4.x * s0, x.y * rn * g4.y * s1); w.y = pk2(x.z * rn * g4.z * s2, x.w * rn * g4.w * s3);
;                 ((u32x2*)(ob + (size_t)row * 1024))[lane + 64 * i] = w;
	v_pk_mul_f32 v[22:23], v[20:21], v[20:21]
	v_pk_mul_f32 v[24:25], v[18:19], v[18:19]
	s_nop 0
	v_pk_mov_b32 v[26:27], v[24:25], v[22:23] op_sel:[1,0]
	v_mov_b32_e32 v25, v23
	v_pk_add_f32 v[22:23], v[26:27], v[24:25]
	s_nop 0
	v_add_f32_e32 v0, v22, v23
	ds_bpermute_b32 v22, v233, v0
	s_waitcnt lgkmcnt(0)
	v_add_f32_e32 v0, v0, v22
	ds_bpermute_b32 v22, v234, v0
	s_waitcnt lgkmcnt(0)
	v_add_f32_e32 v0, v0, v22
	ds_bpermute_b32 v22, v235, v0
	s_waitcnt lgkmcnt(0)
	v_add_f32_e32 v0, v0, v22
	ds_bpermute_b32 v22, v236, v0
	s_waitcnt lgkmcnt(0)
	v_add_f32_e32 v0, v0, v22
	ds_bpermute_b32 v22, v237, v0
	s_waitcnt lgkmcnt(0)
	v_add_f32_e32 v0, v0, v22
	ds_bpermute_b32 v22, v238, v0
	s_waitcnt lgkmcnt(0)
	v_add_f32_e32 v0, v0, v22
	v_fmamk_f32 v0, v0, 0x3b800000, v241
	v_cmp_gt_f32_e32 vcc, s2, v0
	v_mul_f32_e32 v22, 0x4f800000, v0
	s_nop 0
	v_cndmask_b32_e32 v0, v0, v22, vcc
	v_sqrt_f32_e32 v22, v0
	s_nop 0
	v_add_u32_e32 v23, -1, v22
	v_fma_f32 v24, -v23, v22, v0
	v_cmp_ge_f32_e64 s[0:1], 0, v24
	v_add_u32_e32 v24, 1, v22
	s_nop 0
	v_cndmask_b32_e64 v23, v22, v23, s[0:1]
	v_fma_f32 v22, -v24, v22, v0
	v_cmp_lt_f32_e64 s[0:1], 0, v22
	s_nop 1
	v_cndmask_b32_e64 v22, v23, v24, s[0:1]
	v_mul_f32_e32 v23, 0x37800000, v22
	v_cndmask_b32_e32 v22, v22, v23, vcc
	v_cmp_class_f32_e32 vcc, v0, v242
	s_nop 1
	v_cndmask_b32_e32 v0, v22, v0, vcc
	v_div_scale_f32 v22, s[0:1], v0, v0, 1.0
	v_rcp_f32_e32 v23, v22
	s_nop 0
	v_fma_f32 v24, -v22, v23, 1.0
	v_fmac_f32_e32 v23, v24, v23
	v_div_scale_f32 v24, vcc, 1.0, v0, 1.0
	v_mul_f32_e32 v25, v24, v23
	v_fma_f32 v26, -v22, v25, v24
	v_fmac_f32_e32 v25, v26, v23
	v_fma_f32 v22, -v22, v25, v24
	v_div_fmas_f32 v22, v22, v23, v25
	v_lshlrev_b32_e32 v24, 16, v58
	v_div_fixup_f32 v0, v22, v0, 1.0
	v_mul_f32_e32 v22, 0xbfb8aa3b, v24
	v_fma_f32 v23, v24, s89, -v22
	v_rndne_f32_e32 v26, v22
	v_fmac_f32_e32 v23, 0xb2a5705f, v24
	v_sub_f32_e32 v22, v22, v26
	v_add_f32_e32 v22, v22, v23
	v_exp_f32_e32 v22, v22
	v_cvt_i32_f32_e32 v23, v26
	v_and_b32_e32 v25, 0xffff0000, v58
	v_cmp_nlt_f32_e32 vcc, s96, v24
	v_pk_mul_f32 v[18:19], v[18:19], v[0:1] op_sel_hi:[1,0]
	v_ldexp_f32 v22, v22, v23
	v_mul_f32_e32 v23, 0xbfb8aa3b, v25
	v_fma_f32 v26, v25, s89, -v23
	v_rndne_f32_e32 v27, v23
	v_fmac_f32_e32 v26, 0xb2a5705f, v25
	v_sub_f32_e32 v23, v23, v27
	v_add_f32_e32 v23, v23, v26
	v_exp_f32_e32 v23, v23
	v_cvt_i32_f32_e32 v26, v27
	v_cndmask_b32_e32 v22, 0, v22, vcc
	v_cmp_ngt_f32_e32 vcc, s97, v24
	v_pk_mul_f32 v[18:19], v[2:3], v[18:19]
	v_ldexp_f32 v23, v23, v26
	v_cndmask_b32_e32 v22, v246, v22, vcc
	v_cmp_nlt_f32_e32 vcc, s96, v25
	v_pk_mul_f32 v[20:21], v[20:21], v[0:1] op_sel_hi:[1,0]
	s_nop 0
	v_cndmask_b32_e32 v23, 0, v23, vcc
	v_cmp_ngt_f32_e32 vcc, s97, v25
	v_pk_mul_f32 v[20:21], v[4:5], v[20:21]
	s_nop 0
	v_cndmask_b32_e32 v23, v246, v23, vcc
	v_pk_add_f32 v[22:23], v[22:23], 1.0 op_sel_hi:[1,0]
	s_nop 0
	v_div_scale_f32 v26, s[0:1], v23, v23, v25
	v_rcp_f32_e32 v27, v26
	s_nop 0
	v_fma_f32 v28, -v26, v27, 1.0
	v_fmac_f32_e32 v27, v28, v27
	v_div_scale_f32 v28, vcc, v25, v23, v25
	v_mul_f32_e32 v29, v28, v27
	v_fma_f32 v30, -v26, v29, v28
	v_fmac_f32_e32 v29, v30, v27
	v_fma_f32 v26, -v26, v29, v28
	v_div_fmas_f32 v26, v26, v27, v29
	v_div_fixup_f32 v23, v26, v23, v25
	v_div_scale_f32 v25, s[0:1], v22, v22, v24
	v_rcp_f32_e32 v26, v25
	s_nop 0
	v_fma_f32 v27, -v25, v26, 1.0
	v_fmac_f32_e32 v26, v27, v26
	v_div_scale_f32 v27, vcc, v24, v22, v24
	v_mul_f32_e32 v28, v27, v26
	v_fma_f32 v29, -v25, v28, v27
	v_fmac_f32_e32 v28, v29, v26
	v_fma_f32 v25, -v25, v28, v27
	v_div_fmas_f32 v25, v25, v26, v28
	v_div_fixup_f32 v22, v25, v22, v24
	v_pk_mul_f32 v[18:19], v[22:23], v[18:19]
	v_lshlrev_b32_e32 v23, 16, v59
	v_cvt_pk_bf16_f32 v22, v18, v19
	v_mul_f32_e32 v18, 0xbfb8aa3b, v23
	v_fma_f32 v19, v23, s89, -v18
	v_rndne_f32_e32 v25, v18
	v_fmac_f32_e32 v19, 0xb2a5705f, v23
	v_sub_f32_e32 v18, v18, v25
	v_add_f32_e32 v18, v18, v19
	v_exp_f32_e32 v18, v18
	v_cvt_i32_f32_e32 v19, v25
	v_and_b32_e32 v24, 0xffff0000, v59
	v_cmp_nlt_f32_e32 vcc, s96, v23
	v_ldexp_f32 v18, v18, v19
	v_mul_f32_e32 v19, 0xbfb8aa3b, v24
	v_fma_f32 v25, v24, s89, -v19
	v_rndne_f32_e32 v26, v19
	v_fmac_f32_e32 v25, 0xb2a5705f, v24
	v_sub_f32_e32 v19, v19, v26
	v_add_f32_e32 v19, v19, v25
	v_exp_f32_e32 v19, v19
	v_cvt_i32_f32_e32 v25, v26
	v_cndmask_b32_e32 v18, 0, v18, vcc
	v_cmp_ngt_f32_e32 vcc, s97, v23
	v_ldexp_f32 v19, v19, v25
	s_nop 0
	v_cndmask_b32_e32 v18, v246, v18, vcc
	v_cmp_nlt_f32_e32 vcc, s96, v24
	s_nop 1
	v_cndmask_b32_e32 v19, 0, v19, vcc
	v_cmp_ngt_f32_e32 vcc, s97, v24
	s_nop 1
	v_cndmask_b32_e32 v19, v246, v19, vcc
	v_pk_add_f32 v[18:19], v[18:19], 1.0 op_sel_hi:[1,0]
	s_nop 0
	v_div_scale_f32 v25, s[0:1], v19, v19, v24
	v_rcp_f32_e32 v26, v25
	s_nop 0
	v_fma_f32 v27, -v25, v26, 1.0
	v_fmac_f32_e32 v26, v27, v26
	v_div_scale_f32 v27, vcc, v24, v19, v24
	v_mul_f32_e32 v28, v27, v26
	v_fma_f32 v29, -v25, v28, v27
	v_fmac_f32_e32 v28, v29, v26
	v_fma_f32 v25, -v25, v28, v27
	v_div_fmas_f32 v25, v25, v26, v28
	v_div_fixup_f32 v19, v25, v19, v24
	v_div_scale_f32 v24, s[0:1], v18, v18, v23
	v_rcp_f32_e32 v25, v24
	s_nop 0
	v_fma_f32 v26, -v24, v25, 1.0
	v_fmac_f32_e32 v25, v26, v25
	v_div_scale_f32 v26, vcc, v23, v18, v23
	v_mul_f32_e32 v27, v26, v25
	v_fma_f32 v28, -v24, v27, v26
	v_fmac_f32_e32 v27, v28, v25
	v_fma_f32 v24, -v24, v27, v26
	v_div_fmas_f32 v24, v24, v25, v27
	v_div_fixup_f32 v18, v24, v18, v23
	v_pk_mul_f32 v[18:19], v[18:19], v[20:21]
	v_pk_mul_f32 v[20:21], v[16:17], v[16:17]
	v_cvt_pk_bf16_f32 v23, v18, v19
	v_lshl_add_u64 v[18:19], s[48:49], 0, v[44:45]
	global_store_dwordx2 v[18:19], v[22:23], off offset:-1024
	v_pk_mul_f32 v[22:23], v[14:15], v[14:15]
	s_nop 0
	v_pk_mov_b32 v[24:25], v[22:23], v[20:21] op_sel:[1,0]
	v_mov_b32_e32 v23, v21
	v_pk_add_f32 v[20:21], v[24:25], v[22:23]
	s_nop 0
	v_add_f32_e32 v0, v20, v21
	ds_bpermute_b32 v20, v233, v0
	s_waitcnt lgkmcnt(0)
; DI unsigned pk2(float lo, float hi) { f32x2 f = {lo, hi}; bf2_t v = __builtin_convertvector(f, bf2_t); return __builtin_bit_cast(unsigned, v); }
; DI void gla_finish_phase(int wv, const float* obuf, const bf16_t* rb, const float* gn, bf16_t* ob) {
;     ...
;             for (int i = 0; i < 4; ++i) {
;                 const f32x4 x = v[u][i];
;                 const float ss = wave_sum((x.x * x.x + x.y * x.y) + (x.z * x.z + x.w * x.w));
;                 const float rn = 1.f / sqrtf(ss * (1.f / 256.f) + 1e-6f);
;                 const u32x2 r_ = rw[u][i];
;                 const float r0 = __uint_as_float(r_.x << 16), r1 = __uint_as_float(r_.x & 0xffff0000u), r2 = __uint_as_float(r_.y << 16), r3 = __uint_as_float(r_.y & 0xffff0000u);
;                 const float s0 = r0 / (1.f + expf(-r0)), s1 = r1 / (1.f + expf(-r1)), s2 = r2 / (1.f + expf(-r2)), s3 = r3 / (1.f + expf(-r3));
;                 u32x2 w; w.x = pk2(x.x * rn * g4.x * s0, x.y * rn * g4.y * s1); w.y = pk2(x.z * rn * g4.z * s2, x.w * rn * g4.w * s3);
;                 ((u32x2*)(ob + (size_t)row * 1024))[lane + 64 * i] = w;
	v_add_f32_e32 v0, v0, v20
	ds_bpermute_b32 v20, v234, v0
	s_waitcnt lgkmcnt(0)
	v_add_f32_e32 v0, v0, v20
	ds_bpermute_b32 v20, v235, v0
	s_waitcnt lgkmcnt(0)
	v_add_f32_e32 v0, v0, v20
	ds_bpermute_b32 v20, v236, v0
	s_waitcnt lgkmcnt(0)
	v_add_f32_e32 v0, v0, v20
	ds_bpermute_b32 v20, v237, v0
	s_waitcnt lgkmcnt(0)
	v_add_f32_e32 v0, v0, v20
	ds_bpermute_b32 v20, v238, v0
	s_waitcnt lgkmcnt(0)
	v_add_f32_e32 v0, v0, v20
	v_fmamk_f32 v0, v0, 0x3b800000, v241
	v_cmp_gt_f32_e32 vcc, s2, v0
	v_mul_f32_e32 v20, 0x4f800000, v0
	s_nop 0
	v_cndmask_b32_e32 v0, v0, v20, vcc
	v_sqrt_f32_e32 v20, v0
	s_nop 0
	v_add_u32_e32 v21, -1, v20
	v_fma_f32 v22, -v21, v20, v0
	v_cmp_ge_f32_e64 s[0:1], 0, v22
	v_add_u32_e32 v22, 1, v20
	s_nop 0
	v_cndmask_b32_e64 v21, v20, v21, s[0:1]
	v_fma_f32 v20, -v22, v20, v0
	v_cmp_lt_f32_e64 s[0:1], 0, v20
	s_nop 1
	v_cndmask_b32_e64 v20, v21, v22, s[0:1]
	v_mul_f32_e32 v21, 0x37800000, v20
	v_cndmask_b32_e32 v20, v20, v21, vcc
	v_cmp_class_f32_e32 vcc, v0, v242
	s_nop 1
	v_cndmask_b32_e32 v0, v20, v0, vcc
	v_div_scale_f32 v20, s[0:1], v0, v0, 1.0
	v_rcp_f32_e32 v21, v20
	s_nop 0
	v_fma_f32 v22, -v20, v21, 1.0
	v_fmac_f32_e32 v21, v22, v21
	v_div_scale_f32 v22, vcc, 1.0, v0, 1.0
	v_mul_f32_e32 v23, v22, v21
	v_fma_f32 v24, -v20, v23, v22
	v_fmac_f32_e32 v23, v24, v21
	v_fma_f32 v20, -v20, v23, v22
	v_div_fmas_f32 v20, v20, v21, v23
	v_lshlrev_b32_e32 v22, 16, v56
	v_div_fixup_f32 v0, v20, v0, 1.0
	v_mul_f32_e32 v20, 0xbfb8aa3b, v22
	v_fma_f32 v21, v22, s89, -v20
	v_rndne_f32_e32 v24, v20
	v_fmac_f32_e32 v21, 0xb2a5705f, v22
	v_sub_f32_e32 v20, v20, v24
	v_add_f32_e32 v20, v20, v21
	v_exp_f32_e32 v20, v20
	v_cvt_i32_f32_e32 v21, v24
	v_and_b32_e32 v23, 0xffff0000, v56
	v_cmp_nlt_f32_e32 vcc, s96, v22
	v_pk_mul_f32 v[14:15], v[14:15], v[0:1] op_sel_hi:[1,0]
	v_ldexp_f32 v20, v20, v21
	v_mul_f32_e32 v21, 0xbfb8aa3b, v23
	v_fma_f32 v24, v23, s89, -v21
	v_rndne_f32_e32 v25, v21
	v_fmac_f32_e32 v24, 0xb2a5705f, v23
	v_sub_f32_e32 v21, v21, v25
	v_add_f32_e32 v21, v21, v24
	v_exp_f32_e32 v21, v21
	v_cvt_i32_f32_e32 v24, v25
	v_cndmask_b32_e32 v20, 0, v20, vcc
	v_cmp_ngt_f32_e32 vcc, s97, v22
	v_pk_mul_f32 v[14:15], v[2:3], v[14:15]
	v_ldexp_f32 v21, v21, v24
	v_cndmask_b32_e32 v20, v246, v20, vcc
	v_cmp_nlt_f32_e32 vcc, s96, v23
	v_pk_mul_f32 v[16:17], v[16:17], v[0:1] op_sel_hi:[1,0]
	s_nop 0
	v_cndmask_b32_e32 v21, 0, v21, vcc
	v_cmp_ngt_f32_e32 vcc, s97, v23
	v_pk_mul_f32 v[16:17], v[4:5], v[16:17]
	s_nop 0
	v_cndmask_b32_e32 v21, v246, v21, vcc
	v_pk_add_f32 v[20:21], v[20:21], 1.0 op_sel_hi:[1,0]
	s_nop 0
	v_div_scale_f32 v24, s[0:1], v21, v21, v23
	v_rcp_f32_e32 v25, v24
	s_nop 0
	v_fma_f32 v26, -v24, v25, 1.0
	v_fmac_f32_e32 v25, v26, v25
	v_div_scale_f32 v26, vcc, v23, v21, v23
	v_mul_f32_e32 v27, v26, v25
	v_fma_f32 v28, -v24, v27, v26
	v_fmac_f32_e32 v27, v28, v25
	v_fma_f32 v24, -v24, v27, v26
	v_div_fmas_f32 v24, v24, v25, v27
	v_div_fixup_f32 v21, v24, v21, v23
	v_div_scale_f32 v23, s[0:1], v20, v20, v22
	v_rcp_f32_e32 v24, v23
	s_nop 0
	v_fma_f32 v25, -v23, v24, 1.0
	v_fmac_f32_e32 v24, v25, v24
	v_div_scale_f32 v25, vcc, v22, v20, v22
	v_mul_f32_e32 v26, v25, v24
	v_fma_f32 v27, -v23, v26, v25
	v_fmac_f32_e32 v26, v27, v24
	v_fma_f32 v23, -v23, v26, v25
	v_div_fmas_f32 v23, v23, v24, v26
	v_div_fixup_f32 v20, v23, v20, v22
	v_pk_mul_f32 v[14:15], v[20:21], v[14:15]
	v_and_b32_e32 v22, 0xffff0000, v57
	v_cvt_pk_bf16_f32 v14, v14, v15
	v_lshlrev_b32_e32 v15, 16, v57
	v_mul_f32_e32 v20, 0xbfb8aa3b, v15
	v_fma_f32 v21, v15, s89, -v20
	v_rndne_f32_e32 v23, v20
	v_fmac_f32_e32 v21, 0xb2a5705f, v15
	v_sub_f32_e32 v20, v20, v23
	v_add_f32_e32 v20, v20, v21
	v_exp_f32_e32 v20, v20
	v_cvt_i32_f32_e32 v21, v23
	v_cmp_nlt_f32_e32 vcc, s96, v15
	v_ldexp_f32 v20, v20, v21
	v_mul_f32_e32 v21, 0xbfb8aa3b, v22
	v_fma_f32 v23, v22, s89, -v21
	v_rndne_f32_e32 v24, v21
	v_fmac_f32_e32 v23, 0xb2a5705f, v22
	v_sub_f32_e32 v21, v21, v24
	v_add_f32_e32 v21, v21, v23
	v_exp_f32_e32 v21, v21
	v_cvt_i32_f32_e32 v23, v24
	v_cndmask_b32_e32 v20, 0, v20, vcc
	v_cmp_ngt_f32_e32 vcc, s97, v15
	v_ldexp_f32 v21, v21, v23
	s_nop 0
	v_cndmask_b32_e32 v20, v246, v20, vcc
	v_cmp_nlt_f32_e32 vcc, s96, v22
	s_nop 1
	v_cndmask_b32_e32 v21, 0, v21, vcc
	v_cmp_ngt_f32_e32 vcc, s97, v22
	s_nop 1
	v_cndmask_b32_e32 v21, v246, v21, vcc
	v_pk_add_f32 v[20:21], v[20:21], 1.0 op_sel_hi:[1,0]
	s_nop 0
	v_div_scale_f32 v23, s[0:1], v21, v21, v22
	v_rcp_f32_e32 v24, v23
	s_nop 0
	v_fma_f32 v25, -v23, v24, 1.0
	v_fmac_f32_e32 v24, v25, v24
	v_div_scale_f32 v25, vcc, v22, v21, v22
	v_mul_f32_e32 v26, v25, v24
	v_fma_f32 v27, -v23, v26, v25
	v_fmac_f32_e32 v26, v27, v24
	v_fma_f32 v23, -v23, v26, v25
	v_div_fmas_f32 v23, v23, v24, v26
	v_div_fixup_f32 v21, v23, v21, v22
	v_div_scale_f32 v22, s[0:1], v20, v20, v15
	v_rcp_f32_e32 v23, v22
	s_nop 0
	v_fma_f32 v24, -v22, v23, 1.0
	v_fmac_f32_e32 v23, v24, v23
	v_div_scale_f32 v24, vcc, v15, v20, v15
	v_mul_f32_e32 v25, v24, v23
	v_fma_f32 v26, -v22, v25, v24
	v_fmac_f32_e32 v25, v26, v23
	v_fma_f32 v22, -v22, v25, v24
	v_div_fmas_f32 v22, v22, v23, v25
	v_div_fixup_f32 v20, v22, v20, v15
	v_pk_mul_f32 v[16:17], v[20:21], v[16:17]
	s_nop 0
	v_cvt_pk_bf16_f32 v15, v16, v17
	global_store_dwordx2 v[18:19], v[14:15], off offset:-512
	v_pk_mul_f32 v[14:15], v[12:13], v[12:13]
	v_pk_mul_f32 v[16:17], v[10:11], v[10:11]
	s_nop 0
	v_pk_mov_b32 v[20:21], v[16:17], v[14:15] op_sel:[1,0]
	v_mov_b32_e32 v17, v15
	v_pk_add_f32 v[14:15], v[20:21], v[16:17]
	s_nop 0
	v_add_f32_e32 v0, v14, v15
	ds_bpermute_b32 v14, v233, v0
	s_waitcnt lgkmcnt(0)
	v_add_f32_e32 v0, v0, v14
	ds_bpermute_b32 v14, v234, v0
	s_waitcnt lgkmcnt(0)
; DI unsigned pk2(float lo, float hi) { f32x2 f = {lo, hi}; bf2_t v = __builtin_convertvector(f, bf2_t); return __builtin_bit_cast(unsigned, v); }
; DI void gla_finish_phase(int wv, const float* obuf, const bf16_t* rb, const float* gn, bf16_t* ob) {
;     ...
;             for (int i = 0; i < 4; ++i) {
;                 const f32x4 x = v[u][i];
;                 const float ss = wave_sum((x.x * x.x + x.y * x.y) + (x.z * x.z + x.w * x.w));
;                 const float rn = 1.f / sqrtf(ss * (1.f / 256.f) + 1e-6f);
;                 const u32x2 r_ = rw[u][i];
;                 const float r0 = __uint_as_float(r_.x << 16), r1 = __uint_as_float(r_.x & 0xffff0000u), r2 = __uint_as_float(r_.y << 16), r3 = __uint_as_float(r_.y & 0xffff0000u);
;                 const float s0 = r0 / (1.f + expf(-r0)), s1 = r1 / (1.f + expf(-r1)), s2 = r2 / (1.f + expf(-r2)), s3 = r3 / (1.f + expf(-r3));
;                 u32x2 w; w.x = pk2(x.x * rn * g4.x * s0, x.y * rn * g4.y * s1); w.y = pk2(x.z * rn * g4.z * s2, x.w * rn * g4.w * s3);
;                 ((u32x2*)(ob + (size_t)row * 1024))[lane + 64 * i] = w;
	v_add_f32_e32 v0, v0, v14
	ds_bpermute_b32 v14, v235, v0
	s_waitcnt lgkmcnt(0)
	v_add_f32_e32 v0, v0, v14
	ds_bpermute_b32 v14, v236, v0
	s_waitcnt lgkmcnt(0)
	v_add_f32_e32 v0, v0, v14
	ds_bpermute_b32 v14, v237, v0
	s_waitcnt lgkmcnt(0)
	v_add_f32_e32 v0, v0, v14
	ds_bpermute_b32 v14, v238, v0
	s_waitcnt lgkmcnt(0)
	v_add_f32_e32 v0, v0, v14
	v_fmamk_f32 v0, v0, 0x3b800000, v241
	v_cmp_gt_f32_e32 vcc, s2, v0
	v_mul_f32_e32 v14, 0x4f800000, v0
	s_nop 0
	v_cndmask_b32_e32 v0, v0, v14, vcc
	v_sqrt_f32_e32 v14, v0
	s_nop 0
	v_add_u32_e32 v15, -1, v14
	v_fma_f32 v16, -v15, v14, v0
	v_cmp_ge_f32_e64 s[0:1], 0, v16
	v_add_u32_e32 v16, 1, v14
	s_nop 0
	v_cndmask_b32_e64 v15, v14, v15, s[0:1]
	v_fma_f32 v14, -v16, v14, v0
	v_cmp_lt_f32_e64 s[0:1], 0, v14
	s_nop 1
	v_cndmask_b32_e64 v14, v15, v16, s[0:1]
	v_mul_f32_e32 v15, 0x37800000, v14
	v_cndmask_b32_e32 v14, v14, v15, vcc
	v_cmp_class_f32_e32 vcc, v0, v242
	s_nop 1
	v_cndmask_b32_e32 v0, v14, v0, vcc
	v_div_scale_f32 v14, s[0:1], v0, v0, 1.0
	v_rcp_f32_e32 v15, v14
	s_nop 0
	v_fma_f32 v16, -v14, v15, 1.0
	v_fmac_f32_e32 v15, v16, v15
	v_div_scale_f32 v16, vcc, 1.0, v0, 1.0
	v_mul_f32_e32 v17, v16, v15
	v_fma_f32 v20, -v14, v17, v16
	v_fmac_f32_e32 v17, v20, v15
	v_fma_f32 v14, -v14, v17, v16
	v_div_fmas_f32 v14, v14, v15, v17
	v_lshlrev_b32_e32 v16, 16, v54
	v_div_fixup_f32 v0, v14, v0, 1.0
	v_mul_f32_e32 v14, 0xbfb8aa3b, v16
	v_fma_f32 v15, v16, s89, -v14
	v_rndne_f32_e32 v20, v14
	v_fmac_f32_e32 v15, 0xb2a5705f, v16
	v_sub_f32_e32 v14, v14, v20
	v_add_f32_e32 v14, v14, v15
	v_exp_f32_e32 v14, v14
	v_cvt_i32_f32_e32 v15, v20
	v_and_b32_e32 v17, 0xffff0000, v54
	v_cmp_nlt_f32_e32 vcc, s96, v16
	v_pk_mul_f32 v[10:11], v[10:11], v[0:1] op_sel_hi:[1,0]
	v_ldexp_f32 v14, v14, v15
	v_mul_f32_e32 v15, 0xbfb8aa3b, v17
	v_fma_f32 v20, v17, s89, -v15
	v_rndne_f32_e32 v21, v15
	v_fmac_f32_e32 v20, 0xb2a5705f, v17
	v_sub_f32_e32 v15, v15, v21
	v_add_f32_e32 v15, v15, v20
	v_exp_f32_e32 v15, v15
	v_cvt_i32_f32_e32 v20, v21
	v_cndmask_b32_e32 v14, 0, v14, vcc
	v_cmp_ngt_f32_e32 vcc, s97, v16
	v_pk_mul_f32 v[10:11], v[2:3], v[10:11]
	v_ldexp_f32 v15, v15, v20
	v_cndmask_b32_e32 v14, v246, v14, vcc
	v_cmp_nlt_f32_e32 vcc, s96, v17
	v_pk_mul_f32 v[12:13], v[12:13], v[0:1] op_sel_hi:[1,0]
	s_nop 0
	v_cndmask_b32_e32 v15, 0, v15, vcc
	v_cmp_ngt_f32_e32 vcc, s97, v17
	v_pk_mul_f32 v[12:13], v[4:5], v[12:13]
	s_nop 0
	v_cndmask_b32_e32 v15, v246, v15, vcc
	v_pk_add_f32 v[14:15], v[14:15], 1.0 op_sel_hi:[1,0]
	s_nop 0
	v_div_scale_f32 v20, s[0:1], v15, v15, v17
	v_rcp_f32_e32 v21, v20
	s_nop 0
	v_fma_f32 v22, -v20, v21, 1.0
	v_fmac_f32_e32 v21, v22, v21
	v_div_scale_f32 v22, vcc, v17, v15, v17
	v_mul_f32_e32 v23, v22, v21
	v_fma_f32 v24, -v20, v23, v22
	v_fmac_f32_e32 v23, v24, v21
	v_fma_f32 v20, -v20, v23, v22
	v_div_fmas_f32 v20, v20, v21, v23
	v_div_fixup_f32 v15, v20, v15, v17
	v_div_scale_f32 v17, s[0:1], v14, v14, v16
	v_rcp_f32_e32 v20, v17
	s_nop 0
	v_fma_f32 v21, -v17, v20, 1.0
	v_fmac_f32_e32 v20, v21, v20
	v_div_scale_f32 v21, vcc, v16, v14, v16
	v_mul_f32_e32 v22, v21, v20
	v_fma_f32 v23, -v17, v22, v21
	v_fmac_f32_e32 v22, v23, v20
	v_fma_f32 v17, -v17, v22, v21
	v_div_fmas_f32 v17, v17, v20, v22
	v_div_fixup_f32 v14, v17, v14, v16
	v_pk_mul_f32 v[10:11], v[14:15], v[10:11]
	v_and_b32_e32 v16, 0xffff0000, v55
	v_cvt_pk_bf16_f32 v10, v10, v11
	v_lshlrev_b32_e32 v11, 16, v55
	v_mul_f32_e32 v14, 0xbfb8aa3b, v11
	v_fma_f32 v15, v11, s89, -v14
	v_rndne_f32_e32 v17, v14
	v_fmac_f32_e32 v15, 0xb2a5705f, v11
	v_sub_f32_e32 v14, v14, v17
	v_add_f32_e32 v14, v14, v15
	v_exp_f32_e32 v14, v14
	v_cvt_i32_f32_e32 v15, v17
	v_cmp_nlt_f32_e32 vcc, s96, v11
	v_ldexp_f32 v14, v14, v15
	v_mul_f32_e32 v15, 0xbfb8aa3b, v16
	v_fma_f32 v17, v16, s89, -v15
	v_rndne_f32_e32 v20, v15
	v_fmac_f32_e32 v17, 0xb2a5705f, v16
	v_sub_f32_e32 v15, v15, v20
	v_add_f32_e32 v15, v15, v17
	v_exp_f32_e32 v15, v15
	v_cvt_i32_f32_e32 v17, v20
	v_cndmask_b32_e32 v14, 0, v14, vcc
	v_cmp_ngt_f32_e32 vcc, s97, v11
	v_ldexp_f32 v15, v15, v17
	s_nop 0
	v_cndmask_b32_e32 v14, v246, v14, vcc
	v_cmp_nlt_f32_e32 vcc, s96, v16
	s_nop 1
	v_cndmask_b32_e32 v15, 0, v15, vcc
	v_cmp_ngt_f32_e32 vcc, s97, v16
	s_nop 1
	v_cndmask_b32_e32 v15, v246, v15, vcc
	v_pk_add_f32 v[14:15], v[14:15], 1.0 op_sel_hi:[1,0]
	s_nop 0
	v_div_scale_f32 v17, s[0:1], v15, v15, v16
	v_rcp_f32_e32 v20, v17
	s_nop 0
	v_fma_f32 v21, -v17, v20, 1.0
	v_fmac_f32_e32 v20, v21, v20
	v_div_scale_f32 v21, vcc, v16, v15, v16
	v_mul_f32_e32 v22, v21, v20
	v_fma_f32 v23, -v17, v22, v21
	v_fmac_f32_e32 v22, v23, v20
	v_fma_f32 v17, -v17, v22, v21
	v_div_fmas_f32 v17, v17, v20, v22
	v_div_fixup_f32 v15, v17, v15, v16
	v_div_scale_f32 v16, s[0:1], v14, v14, v11
	v_rcp_f32_e32 v17, v16
	s_nop 0
	v_fma_f32 v20, -v16, v17, 1.0
	v_fmac_f32_e32 v17, v20, v17
	v_div_scale_f32 v20, vcc, v11, v14, v11
	v_mul_f32_e32 v21, v20, v17
	v_fma_f32 v22, -v16, v21, v20
	v_fmac_f32_e32 v21, v22, v17
	v_fma_f32 v16, -v16, v21, v20
	v_div_fmas_f32 v16, v16, v17, v21
	v_div_fixup_f32 v14, v16, v14, v11
	v_pk_mul_f32 v[12:13], v[14:15], v[12:13]
	s_nop 0
	v_cvt_pk_bf16_f32 v11, v12, v13
	global_store_dwordx2 v[18:19], v[10:11], off
	v_pk_mul_f32 v[10:11], v[8:9], v[8:9]
	v_pk_mul_f32 v[12:13], v[6:7], v[6:7]
	s_nop 0
	v_pk_mov_b32 v[14:15], v[12:13], v[10:11] op_sel:[1,0]
	v_mov_b32_e32 v13, v11
	v_pk_add_f32 v[10:11], v[14:15], v[12:13]
	s_nop 0
	v_add_f32_e32 v0, v10, v11
	ds_bpermute_b32 v10, v233, v0
	s_waitcnt lgkmcnt(0)
; DI unsigned pk2(float lo, float hi) { f32x2 f = {lo, hi}; bf2_t v = __builtin_convertvector(f, bf2_t); return __builtin_bit_cast(unsigned, v); }
; DI void gla_finish_phase(int wv, const float* obuf, const bf16_t* rb, const float* gn, bf16_t* ob) {
;     ...
;             for (int i = 0; i < 4; ++i) {
;                 const f32x4 x = v[u][i];
;                 const float ss = wave_sum((x.x * x.x + x.y * x.y) + (x.z * x.z + x.w * x.w));
;                 const float rn = 1.f / sqrtf(ss * (1.f / 256.f) + 1e-6f);
;                 const u32x2 r_ = rw[u][i];
;                 const float r0 = __uint_as_float(r_.x << 16), r1 = __uint_as_float(r_.x & 0xffff0000u), r2 = __uint_as_float(r_.y << 16), r3 = __uint_as_float(r_.y & 0xffff0000u);
;                 const float s0 = r0 / (1.f + expf(-r0)), s1 = r1 / (1.f + expf(-r1)), s2 = r2 / (1.f + expf(-r2)), s3 = r3 / (1.f + expf(-r3));
;                 u32x2 w; w.x = pk2(x.x * rn * g4.x * s0, x.y * rn * g4.y * s1); w.y = pk2(x.z * rn * g4.z * s2, x.w * rn * g4.w * s3);
;                 ((u32x2*)(ob + (size_t)row * 1024))[lane + 64 * i] = w;
;             } } }
;     }
	v_add_f32_e32 v0, v0, v10
	ds_bpermute_b32 v10, v234, v0
	s_waitcnt lgkmcnt(0)
	v_add_f32_e32 v0, v0, v10
	ds_bpermute_b32 v10, v235, v0
	s_waitcnt lgkmcnt(0)
	v_add_f32_e32 v0, v0, v10
	ds_bpermute_b32 v10, v236, v0
	s_waitcnt lgkmcnt(0)
	v_add_f32_e32 v0, v0, v10
	ds_bpermute_b32 v10, v237, v0
	s_waitcnt lgkmcnt(0)
	v_add_f32_e32 v0, v0, v10
	ds_bpermute_b32 v10, v238, v0
	s_waitcnt lgkmcnt(0)
	v_add_f32_e32 v0, v0, v10
	v_fmamk_f32 v0, v0, 0x3b800000, v241
	v_cmp_gt_f32_e32 vcc, s2, v0
	v_mul_f32_e32 v10, 0x4f800000, v0
	s_nop 0
	v_cndmask_b32_e32 v0, v0, v10, vcc
	v_sqrt_f32_e32 v10, v0
	s_nop 0
	v_add_u32_e32 v11, -1, v10
	v_fma_f32 v12, -v11, v10, v0
	v_cmp_ge_f32_e64 s[0:1], 0, v12
	v_add_u32_e32 v12, 1, v10
	s_nop 0
	v_cndmask_b32_e64 v11, v10, v11, s[0:1]
	v_fma_f32 v10, -v12, v10, v0
	v_cmp_lt_f32_e64 s[0:1], 0, v10
	s_nop 1
	v_cndmask_b32_e64 v10, v11, v12, s[0:1]
	v_mul_f32_e32 v11, 0x37800000, v10
	v_cndmask_b32_e32 v10, v10, v11, vcc
	v_cmp_class_f32_e32 vcc, v0, v242
	s_nop 1
	v_cndmask_b32_e32 v0, v10, v0, vcc
	v_div_scale_f32 v10, s[0:1], v0, v0, 1.0
	v_rcp_f32_e32 v11, v10
	s_nop 0
	v_fma_f32 v12, -v10, v11, 1.0
	v_fmac_f32_e32 v11, v12, v11
	v_div_scale_f32 v12, vcc, 1.0, v0, 1.0
	v_mul_f32_e32 v13, v12, v11
	v_fma_f32 v14, -v10, v13, v12
	v_fmac_f32_e32 v13, v14, v11
	v_fma_f32 v10, -v10, v13, v12
	v_div_fmas_f32 v10, v10, v11, v13
	v_lshlrev_b32_e32 v12, 16, v52
	v_div_fixup_f32 v0, v10, v0, 1.0
	v_mul_f32_e32 v10, 0xbfb8aa3b, v12
	v_fma_f32 v11, v12, s89, -v10
	v_rndne_f32_e32 v14, v10
	v_fmac_f32_e32 v11, 0xb2a5705f, v12
	v_sub_f32_e32 v10, v10, v14
	v_add_f32_e32 v10, v10, v11
	v_exp_f32_e32 v10, v10
	v_cvt_i32_f32_e32 v11, v14
	v_and_b32_e32 v13, 0xffff0000, v52
	v_cmp_nlt_f32_e32 vcc, s96, v12
	v_pk_mul_f32 v[6:7], v[6:7], v[0:1] op_sel_hi:[1,0]
	v_ldexp_f32 v10, v10, v11
	v_mul_f32_e32 v11, 0xbfb8aa3b, v13
	v_fma_f32 v14, v13, s89, -v11
	v_rndne_f32_e32 v15, v11
	v_fmac_f32_e32 v14, 0xb2a5705f, v13
	v_sub_f32_e32 v11, v11, v15
	v_add_f32_e32 v11, v11, v14
	v_exp_f32_e32 v11, v11
	v_cvt_i32_f32_e32 v14, v15
	v_cndmask_b32_e32 v10, 0, v10, vcc
	v_cmp_ngt_f32_e32 vcc, s97, v12
	v_pk_mul_f32 v[6:7], v[2:3], v[6:7]
	v_ldexp_f32 v11, v11, v14
	v_cndmask_b32_e32 v10, v246, v10, vcc
	v_cmp_nlt_f32_e32 vcc, s96, v13
	v_pk_mul_f32 v[8:9], v[8:9], v[0:1] op_sel_hi:[1,0]
	s_nop 0
	v_cndmask_b32_e32 v11, 0, v11, vcc
	v_cmp_ngt_f32_e32 vcc, s97, v13
	v_pk_mul_f32 v[8:9], v[4:5], v[8:9]
	s_nop 0
	v_cndmask_b32_e32 v11, v246, v11, vcc
	v_pk_add_f32 v[10:11], v[10:11], 1.0 op_sel_hi:[1,0]
	s_nop 0
	v_div_scale_f32 v14, s[0:1], v11, v11, v13
	v_rcp_f32_e32 v15, v14
	s_nop 0
	v_fma_f32 v16, -v14, v15, 1.0
	v_fmac_f32_e32 v15, v16, v15
	v_div_scale_f32 v16, vcc, v13, v11, v13
	v_mul_f32_e32 v17, v16, v15
	v_fma_f32 v20, -v14, v17, v16
	v_fmac_f32_e32 v17, v20, v15
	v_fma_f32 v14, -v14, v17, v16
	v_div_fmas_f32 v14, v14, v15, v17
	v_div_fixup_f32 v11, v14, v11, v13
	v_div_scale_f32 v13, s[0:1], v10, v10, v12
	v_rcp_f32_e32 v14, v13
	s_nop 0
	v_fma_f32 v15, -v13, v14, 1.0
	v_fmac_f32_e32 v14, v15, v14
	v_div_scale_f32 v15, vcc, v12, v10, v12
	v_mul_f32_e32 v16, v15, v14
	v_fma_f32 v17, -v13, v16, v15
	v_fmac_f32_e32 v16, v17, v14
	v_fma_f32 v13, -v13, v16, v15
	v_div_fmas_f32 v13, v13, v14, v16
	v_div_fixup_f32 v10, v13, v10, v12
	v_pk_mul_f32 v[6:7], v[10:11], v[6:7]
	v_and_b32_e32 v12, 0xffff0000, v53
	v_cvt_pk_bf16_f32 v6, v6, v7
	v_lshlrev_b32_e32 v7, 16, v53
	v_mul_f32_e32 v10, 0xbfb8aa3b, v7
	v_fma_f32 v11, v7, s89, -v10
	v_rndne_f32_e32 v13, v10
	v_fmac_f32_e32 v11, 0xb2a5705f, v7
	v_sub_f32_e32 v10, v10, v13
	v_add_f32_e32 v10, v10, v11
	v_exp_f32_e32 v10, v10
	v_cvt_i32_f32_e32 v11, v13
	v_cmp_nlt_f32_e32 vcc, s96, v7
	v_ldexp_f32 v10, v10, v11
	v_mul_f32_e32 v11, 0xbfb8aa3b, v12
	v_fma_f32 v13, v12, s89, -v11
	v_rndne_f32_e32 v14, v11
	v_fmac_f32_e32 v13, 0xb2a5705f, v12
	v_sub_f32_e32 v11, v11, v14
	v_add_f32_e32 v11, v11, v13
	v_exp_f32_e32 v11, v11
	v_cvt_i32_f32_e32 v13, v14
	v_cndmask_b32_e32 v10, 0, v10, vcc
	v_cmp_ngt_f32_e32 vcc, s97, v7
	v_ldexp_f32 v11, v11, v13
	s_nop 0
	v_cndmask_b32_e32 v10, v246, v10, vcc
	v_cmp_nlt_f32_e32 vcc, s96, v12
	s_nop 1
	v_cndmask_b32_e32 v11, 0, v11, vcc
	v_cmp_ngt_f32_e32 vcc, s97, v12
	s_nop 1
	v_cndmask_b32_e32 v11, v246, v11, vcc
	v_pk_add_f32 v[10:11], v[10:11], 1.0 op_sel_hi:[1,0]
	s_nop 0
	v_div_scale_f32 v13, s[0:1], v11, v11, v12
	v_rcp_f32_e32 v14, v13
	s_nop 0
	v_fma_f32 v15, -v13, v14, 1.0
	v_fmac_f32_e32 v14, v15, v14
	v_div_scale_f32 v15, vcc, v12, v11, v12
	v_mul_f32_e32 v16, v15, v14
	v_fma_f32 v17, -v13, v16, v15
	v_fmac_f32_e32 v16, v17, v14
	v_fma_f32 v13, -v13, v16, v15
	v_div_fmas_f32 v13, v13, v14, v16
	v_div_fixup_f32 v11, v13, v11, v12
	v_div_scale_f32 v12, s[0:1], v10, v10, v7
	v_rcp_f32_e32 v13, v12
	s_nop 0
	v_fma_f32 v14, -v12, v13, 1.0
	v_fmac_f32_e32 v13, v14, v13
	v_div_scale_f32 v14, vcc, v7, v10, v7
	v_mul_f32_e32 v15, v14, v13
	v_fma_f32 v16, -v12, v15, v14
	v_fmac_f32_e32 v15, v16, v13
	v_fma_f32 v12, -v12, v15, v14
	v_div_fmas_f32 v12, v12, v13, v15
	v_div_fixup_f32 v10, v12, v10, v7
	v_pk_mul_f32 v[8:9], v[10:11], v[8:9]
	s_nop 0
	v_cvt_pk_bf16_f32 v7, v8, v9
	global_store_dwordx2 v[18:19], v[6:7], off offset:512
	s_branch .LBB0_237

; #define LAS __attribute__((address_space(3)))
; DI int mk_tid(int wv) { int w = wv; asm volatile("" : "+s"(w)); int l = __builtin_amdgcn_mbcnt_hi(~0u, __builtin_amdgcn_mbcnt_lo(~0u, 0u)); asm volatile("" : "+v"(l)); return w * 64 + l; }
; DI int opaque_bid() { int b = blockIdx.x; asm volatile("" : "+s"(b)); return b; }
; DI void diff_attn_phase(int wv, LAS unsigned char* lds, const bf16_t* qk, const bf16_t* vt, bf16_t* ob, const float* lq1, const float* lk1, const float* lq2, const float* lk2,
;                         const float* subg, int layer_idx) {
;     const int tid = mk_tid(wv), wid = __builtin_amdgcn_readfirstlane(tid >> 6), lane = tid & 63, rr = lane & 31, hh = lane >> 5; const int bid = opaque_bid();
;     const int map = wid >> 2, qsub = wid & 3;
;     int li_ = layer_idx; asm volatile("" : "+s"(li_)); const float lambda_init = (li_ == 0) ? 0.2f : 0.5560582041f;
;     const float d1 = wave_sum(lq1[lane] * lk1[lane]), d2 = wave_sum(lq2[lane] * lk2[lane]);
;     const float lam = expf(d1) - expf(d2) + lambda_init;
;     LAS float* xch = (LAS float*)lds;
;     const float c1 = 0.125f * LOG2E;
;     const int prr = (rr & 0x13) | ((rr & 4) << 1) | ((rr & 8) >> 1);
;     const int koff = prr * DA_KP + (map * 64 + hh * 8) * 2;
;     const int voff = DA_KB + rr * DA_VP + hh * 16;
;     const int krow0 = tid >> 4, kch = tid & 15, vrow0 = tid >> 3, vch = tid & 7;
;     const int kst_off = krow0 * DA_KP + kch * 16, vst_off = DA_KB + vrow0 * DA_VP + vch * 16;
.LBB0_416:
	s_andn2_b64 vcc, exec, s[0:1]
	s_cbranch_vccnz .LBB0_77
	v_readlane_b32 s0, v253, 54
	v_readlane_b32 s1, v253, 55
	s_load_dwordx8 s[8:15], s[0:1], 0x8
	s_mov_b32 s0, s68
	v_mov_b32_e32 v3, v232
	s_mov_b32 s18, s55
	v_and_b32_e32 v2, 63, v3
	v_readlane_b32 s4, v253, 17
	v_lshlrev_b32_e32 v0, 2, v2
	s_waitcnt lgkmcnt(0)
	global_load_dword v4, v0, s[8:9]
	global_load_dword v5, v0, s[10:11]
	global_load_dword v6, v0, s[12:13]
	global_load_dword v0, v0, s[14:15]
	s_cmpk_gt_i32 s18, 0x7ff
	s_waitcnt vmcnt(0)
	v_mul_f32_e32 v7, v4, v5
	ds_bpermute_b32 v7, v233, v7
	v_mul_f32_e32 v8, v6, v0
	ds_bpermute_b32 v8, v233, v8
	s_waitcnt lgkmcnt(1)
	v_fmac_f32_e32 v7, v4, v5
	s_waitcnt lgkmcnt(0)
	v_fmac_f32_e32 v8, v6, v0
	ds_bpermute_b32 v0, v234, v7
	ds_bpermute_b32 v4, v234, v8
	s_waitcnt lgkmcnt(1)
	v_add_f32_e32 v0, v7, v0
	s_waitcnt lgkmcnt(0)
	v_add_f32_e32 v4, v8, v4
	ds_bpermute_b32 v5, v235, v0
	ds_bpermute_b32 v6, v235, v4
	s_waitcnt lgkmcnt(1)
	v_add_f32_e32 v0, v0, v5
	s_waitcnt lgkmcnt(0)
	v_add_f32_e32 v4, v4, v6
	ds_bpermute_b32 v5, v236, v0
	ds_bpermute_b32 v6, v236, v4
	s_waitcnt lgkmcnt(1)
	v_add_f32_e32 v0, v0, v5
	s_waitcnt lgkmcnt(0)
	v_add_f32_e32 v4, v4, v6
	ds_bpermute_b32 v5, v237, v0
	ds_bpermute_b32 v7, v237, v4
	s_waitcnt lgkmcnt(1)
	v_add_f32_e32 v6, v0, v5
	s_waitcnt lgkmcnt(0)
	v_add_f32_e32 v0, v4, v7
	ds_bpermute_b32 v7, v238, v6
	ds_bpermute_b32 v5, v238, v0
	v_lshl_add_u32 v4, s0, 6, v3
	s_nop 0
	v_readfirstlane_b32 s10, v4
	s_cbranch_scc1 .LBB0_440
	s_waitcnt lgkmcnt(1)
	v_add_f32_e32 v6, v6, v7
	v_mul_f32_e32 v7, 0x3fb8aa3b, v6
	s_mov_b32 s3, 0x3fb8aa3b
	v_fma_f32 v9, v6, s3, -v7
	v_rndne_f32_e32 v10, v7
	v_fmac_f32_e32 v9, 0x32a5705f, v6
	v_sub_f32_e32 v7, v7, v10
	v_add_f32_e32 v7, v7, v9
	v_exp_f32_e32 v7, v7
	v_cvt_i32_f32_e32 v9, v10
	s_ashr_i32 s2, s10, 8
	s_cmp_eq_u32 s4, 0
	s_waitcnt lgkmcnt(0)
	v_add_f32_e32 v0, v0, v5
	s_cselect_b64 vcc, -1, 0
	v_mov_b32_e32 v10, 0x3f0e59d5
	v_mov_b32_e32 v11, 0x3e4ccccd
	v_ldexp_f32 v5, v7, v9
	v_mul_f32_e32 v7, 0x3fb8aa3b, v0
	v_cndmask_b32_e32 v10, v10, v11, vcc
	v_fma_f32 v9, v0, s3, -v7
	v_rndne_f32_e32 v11, v7
	v_fmac_f32_e32 v9, 0x32a5705f, v0
	v_sub_f32_e32 v7, v7, v11
	v_add_f32_e32 v7, v7, v9
	v_exp_f32_e32 v7, v7
	v_cvt_i32_f32_e32 v9, v11
	s_mov_b32 s3, 0xc2ce8ed0
	v_cmp_ngt_f32_e32 vcc, s3, v6
	s_mov_b32 s4, 0x42b17218
	v_ashrrev_i32_e32 v161, 3, v4
	v_cndmask_b32_e32 v5, 0, v5, vcc
	v_cmp_nlt_f32_e32 vcc, s4, v6
	v_ldexp_f32 v6, v7, v9
	v_readlane_b32 s8, v253, 0
	v_cndmask_b32_e32 v5, v246, v5, vcc
	v_cmp_ngt_f32_e32 vcc, s3, v0
	s_movk_i32 s3, 0x110
	v_readlane_b32 s9, v253, 1
	v_cndmask_b32_e32 v6, 0, v6, vcc
	v_cmp_nlt_f32_e32 vcc, s4, v0
	s_lshl_b32 s4, s2, 6
	s_ashr_i32 s5, s4, 31
	v_cndmask_b32_e32 v0, v246, v6, vcc
	v_sub_f32_e32 v0, v5, v0
	v_lshlrev_b32_e32 v5, 1, v3
	v_lshrrev_b32_e32 v6, 1, v3
	v_add_f32_e32 v149, v10, v0
	v_and_b32_e32 v0, 19, v3
	v_and_b32_e32 v5, 8, v5
	v_and_b32_e32 v6, 4, v6
	v_or3_b32 v0, v0, v5, v6
	v_ashrrev_i32_e32 v6, 4, v4
	v_mul_lo_u32 v4, v6, s3
	s_ashr_i32 s3, s10, 6
	s_and_b32 s11, s3, 3
	s_lshl_b32 s3, s3, 12
	s_add_i32 s3, s3, 0
	s_lshl_b32 s19, s11, 5
	s_add_i32 s3, s3, 0x11800
	s_cmp_eq_u32 s2, 1
	s_load_dword s2, s[8:9], 0x10
	v_readlane_b32 s0, v253, 54
	v_readlane_b32 s1, v253, 55
	s_cselect_b64 s[6:7], -1, 0
	s_cmpk_lt_u32 s10, 0x100
	s_load_dwordx2 s[0:1], s[0:1], 0x28
	s_cselect_b64 s[8:9], -1, 0
	s_waitcnt lgkmcnt(0)
	s_lshr_b32 s2, s2, 16
	v_lshrrev_b32_e32 v8, 5, v2
	s_cmp_lg_u32 s2, 0
	v_lshlrev_b32_e32 v146, 3, v8
	s_cselect_b64 s[12:13], -1, 0
	v_mul_u32_u24_e32 v0, 0x110, v0
	v_or_b32_e32 v5, s4, v146
	s_cmp_lg_u64 s[12:13], 0
	v_and_b32_e32 v147, 31, v3
	v_lshl_add_u32 v153, v5, 1, v0
	v_lshlrev_b32_e32 v0, 4, v8
	s_movk_i32 s14, 0x90
	s_addc_u32 s20, s46, 0
	s_lshl_b32 s2, s10, 8
	v_and_b32_e32 v5, 15, v3
	v_mad_u32_u24 v211, v147, s14, v0
	s_and_b32 s10, s2, 0xc000
	s_or_b32 s21, s2, 0x3f00
	v_lshl_add_u64 v[154:155], s[0:1], 0, v[0:1]
	v_sub_u32_e32 v0, v146, v147
	v_and_b32_e32 v3, 7, v3
	v_lshl_add_u32 v167, v5, 4, v4
	v_mul_lo_u32 v4, v161, s14
	v_lshlrev_b32_e32 v9, 4, v2
	v_ashrrev_i32_e32 v7, 31, v6
	v_lshl_add_u32 v209, v2, 2, 0
	v_lshlrev_b32_e32 v2, 2, v8
	v_add_u32_e32 v212, 0, v211
	s_cmp_lt_u32 s11, 2
	v_subrev_u32_e32 v0, s19, v0
	v_lshlrev_b32_e32 v148, 3, v5
	v_lshlrev_b64 v[150:151], 11, v[6:7]
	v_lshlrev_b32_e32 v152, 3, v3
	v_lshl_add_u32 v208, v3, 4, v4
	v_sub_f32_e32 v210, 1.0, v10
	v_add_u32_e32 v213, 0xd000, v212
	v_lshl_add_u32 v214, s11, 14, v209
	v_add_u32_e32 v215, s10, v209
	s_cselect_b64 s[10:11], -1, 0
	v_add_u32_e32 v216, 0xfffff200, v0
	s_mov_b64 s[12:13], 0
	v_lshlrev_b32_e32 v156, 1, v146
	v_lshlrev_b32_e32 v158, 1, v2
	v_add_u32_e32 v217, s3, v9
	s_branch .LBB0_420

; #define LAS __attribute__((address_space(3)))
; #define MFMA32(a, b, c) __builtin_amdgcn_mfma_f32_32x32x16_bf16((a), (b), (c), 0, 0, 0)
; DI f32x16 zero16() { f32x16 z; for (int i = 0; i < 16; ++i) z[i] = 0.f; return z; }
; DI void diff_attn_phase(int wv, LAS unsigned char* lds, const bf16_t* qk, const bf16_t* vt, bf16_t* ob, const float* lq1, const float* lk1, const float* lq2, const float* lk2,
;                         const float* subg, int layer_idx) {
;     ...
;             const int key0 = t * 64;
;             const bool more = true;
;             if (more) {
; #pragma unroll
;                 for (int i = 0; i < 2; ++i) gk[i] = *(const u32x4*)(kg + (size_t)(key0 + 64 + i * 32) * 2048); }
;             LAS unsigned char* buf = lds + (t & 1) * DA_BUF;
;             {
;                 f32x16 S0 = zero16(), S1 = zero16();
;                 {
;                     bf16x8 kf[2][4];
; #pragma unroll
;                     for (int sub = 0; sub < 2; ++sub)
; #pragma unroll
;                         for (int ks = 0; ks < 4; ++ks) kf[sub][ks] = *(const LAS bf16x8*)(buf + koff + sub * 32 * DA_KP + ks * 32);
; #pragma unroll
;                     for (int ks = 0; ks < 4; ++ks) { const bf16x8 qfr = *(const LAS bf16x8*)(qlds + ks * 1024); S0 = MFMA32(kf[0][ks], qfr, S0); S1 = MFMA32(kf[1][ks], qfr, S1); }
;                 }
;                 __builtin_amdgcn_sched_barrier(0);
; #pragma unroll
;                 for (int i = 0; i < 2; ++i) gv[i] = *(const u32x4*)(vg + (size_t)i * 64 * M_TOK + key0 + 64);
;                 bf16x8 vf[4][2];
; #pragma unroll
;                 for (int d = 0; d < 4; ++d)
; #pragma unroll
;                     for (int s2 = 0; s2 < 2; ++s2) vf[d][s2] = *(const LAS bf16x8*)(buf + voff + d * 32 * DA_VP + (16 * s2) * 2);
;                 const float base = slope2 * (float)(key0 + 8 * hh - qpos), b32 = 32.f * slope2;
; #pragma unroll
;                 for (int i = 0; i < 16; ++i) { S0[i] = S0[i] * c1 + cb[i]; S1[i] = S1[i] * c1 + cb[i]; }
;                 float mx = -INFINITY, mx1 = -INFINITY;
; #pragma unroll
;                 for (int i = 0; i < 16; ++i) { mx = fmaxf(mx, S0[i]); mx1 = fmaxf(mx1, S1[i]); }
;                 mx = fmaxf(mx, mx1 + b32) + base;
;                 mx = fmaxf(mx, __shfl_xor(mx, 32));
.LBB0_424:
	s_add_i32 s14, s16, 64
	s_ashr_i32 s15, s14, 31
	s_lshl_b64 s[26:27], s[14:15], 12
	v_lshl_add_u64 v[66:67], v[114:115], 0, s[26:27]
	s_add_i32 s26, s16, 0x60
	s_ashr_i32 s27, s26, 31
	s_lshl_b64 s[26:27], s[26:27], 12
	global_load_dwordx4 v[98:101], v[66:67], off offset:2048
	v_lshl_add_u64 v[66:67], v[114:115], 0, s[26:27]
	global_load_dwordx4 v[102:105], v[66:67], off offset:2048
	s_bitcmp1_b32 s25, 0
	s_cselect_b32 s2, 0x8c00, 0
	s_add_i32 s2, s2, 0
	v_add_u32_e32 v70, s2, v153
	ds_read_b128 v[126:129], v217
	ds_read_b128 v[66:69], v70
	ds_read_b128 v[130:133], v217 offset:1024
	ds_read_b128 v[82:85], v70 offset:32
	ds_read_b128 v[134:137], v217 offset:2048
	ds_read_b128 v[86:89], v70 offset:64
	ds_read_b128 v[138:141], v217 offset:3072
	ds_read_b128 v[90:93], v70 offset:96
	ds_read_b128 v[94:97], v70 offset:8704
	ds_read_b128 v[106:109], v70 offset:8736
	ds_read_b128 v[110:113], v70 offset:8768
	ds_read_b128 v[122:125], v70 offset:8800
	v_mov_b32_e32 v121, v159
	v_mov_b32_e32 v0, v218
	s_waitcnt lgkmcnt(10)
	v_mfma_f32_32x32x16_bf16 v[66:81], v[66:69], v[126:129], 0
	s_ashr_i32 s17, s16, 31
	s_mov_b32 s3, 0x400000
	v_add_u32_e32 v118, s16, v120
	v_add_u32_e32 v191, s2, v211
	s_waitcnt lgkmcnt(8)
	v_mfma_f32_32x32x16_bf16 v[66:81], v[82:85], v[130:133], v[66:81]
	s_waitcnt lgkmcnt(6)
	v_mfma_f32_32x32x16_bf16 v[66:81], v[86:89], v[134:137], v[66:81]
	s_waitcnt lgkmcnt(4)
	v_mfma_f32_32x32x16_bf16 v[66:81], v[90:93], v[138:141], v[66:81]
	s_waitcnt lgkmcnt(3)
	v_mfma_f32_32x32x16_bf16 v[82:97], v[94:97], v[126:129], 0
	s_nop 10
	v_fmamk_f32 v127, v66, 0x3e38aa3b, v192
	v_max_f32_e32 v66, 0xff800000, v127
	v_fmamk_f32 v129, v69, 0x3e38aa3b, v189
	v_fmamk_f32 v159, v74, 0x3e38aa3b, v182
	v_fmamk_f32 v193, v75, 0x3e38aa3b, v183
	v_fmamk_f32 v196, v76, 0x3e38aa3b, v180
	v_cvt_f32_i32_e32 v126, v118
	s_waitcnt lgkmcnt(2)
	v_mfma_f32_32x32x16_bf16 v[82:97], v[106:109], v[130:133], v[82:97]
	v_lshl_add_u64 v[106:107], s[16:17], 1, v[116:117]
	v_add_co_u32_e32 v108, vcc, s3, v106
	v_fmamk_f32 v131, v70, 0x3e38aa3b, v186
	s_nop 0
	v_addc_co_u32_e32 v109, vcc, 0, v107, vcc
	v_fmamk_f32 v133, v71, 0x3e38aa3b, v187
	s_waitcnt lgkmcnt(1)
	v_mfma_f32_32x32x16_bf16 v[82:97], v[110:113], v[134:137], v[82:97]
	global_load_dwordx4 v[110:113], v[106:107], off offset:128
	global_load_dwordx4 v[106:109], v[108:109], off offset:128
	v_fmamk_f32 v135, v72, 0x3e38aa3b, v184
	v_fmamk_f32 v137, v73, 0x3e38aa3b, v185
	v_fmamk_f32 v199, v77, 0x3e38aa3b, v181
	v_fmamk_f32 v200, v78, 0x3e38aa3b, v178
	v_fmamk_f32 v204, v79, 0x3e38aa3b, v179
	v_fmamk_f32 v207, v80, 0x3e38aa3b, v176
	s_waitcnt lgkmcnt(0)
	v_mfma_f32_32x32x16_bf16 v[82:97], v[122:125], v[138:141], v[82:97]
	v_fmamk_f32 v123, v67, 0x3e38aa3b, v160
	v_fmamk_f32 v125, v68, 0x3e38aa3b, v188
	v_max3_f32 v66, v66, v123, v125
	v_max3_f32 v66, v66, v129, v131
	v_max3_f32 v66, v66, v133, v135
	v_max3_f32 v66, v66, v137, v159
	v_max3_f32 v66, v66, v193, v196
	s_nop 4
	v_fmamk_f32 v122, v82, 0x3e38aa3b, v192
	v_fmamk_f32 v124, v83, 0x3e38aa3b, v160
	v_fmamk_f32 v128, v84, 0x3e38aa3b, v188
	v_fmamk_f32 v130, v85, 0x3e38aa3b, v189
	v_max3_f32 v67, v122, s54, v124
	v_fmamk_f32 v132, v86, 0x3e38aa3b, v186
	v_fmamk_f32 v134, v87, 0x3e38aa3b, v187
	v_max3_f32 v67, v67, v128, v130
	v_fmamk_f32 v136, v88, 0x3e38aa3b, v184
	v_fmamk_f32 v143, v89, 0x3e38aa3b, v185
	v_max3_f32 v67, v67, v132, v134
	v_fmamk_f32 v169, v90, 0x3e38aa3b, v182
	v_fmamk_f32 v195, v91, 0x3e38aa3b, v183
	v_max3_f32 v67, v67, v136, v143
	v_fmamk_f32 v198, v92, 0x3e38aa3b, v180
	v_fmamk_f32 v202, v93, 0x3e38aa3b, v181
	v_max3_f32 v67, v67, v169, v195
	v_fmamk_f32 v203, v94, 0x3e38aa3b, v178
	v_fmamk_f32 v206, v95, 0x3e38aa3b, v179
	v_max3_f32 v67, v67, v198, v202
	v_fmamk_f32 v219, v96, 0x3e38aa3b, v176
	v_fmamk_f32 v222, v97, 0x3e38aa3b, v177
	v_max3_f32 v67, v67, v203, v206
	v_max3_f32 v66, v66, v199, v200
	v_max3_f32 v67, v67, v219, v222
	v_fmamk_f32 v220, v81, 0x3e38aa3b, v177
	v_max3_f32 v66, v66, v204, v207
	v_add_f32_e32 v67, v157, v67
	v_max3_f32 v66, v66, v220, v67
	v_fmac_f32_e32 v66, v160, v126
	v_mov_b32_e32 v67, v66
	s_nop 1
	v_permlane32_swap_b32_e32 v66, v67
	ds_read_b128 v[94:97], v191 offset:17408
	ds_read_b128 v[90:93], v191 offset:17440
	ds_read_b128 v[86:89], v191 offset:22016
	ds_read_b128 v[82:85], v191 offset:22048
	s_waitcnt lgkmcnt(4)
; DI float fexp2(float x) { return __builtin_amdgcn_exp2f(x); }
; DI void diff_attn_phase(int wv, LAS unsigned char* lds, const bf16_t* qk, const bf16_t* vt, bf16_t* ob, const float* lq1, const float* lk1, const float* lq2, const float* lk2,
;                         const float* subg, int layer_idx) {
;     ...
;                     const float mn = fmaxf(m, mx), alpha = fexp2(m - mn); m = mn; l *= alpha;
; #pragma unroll
;                     for (int d = 0; d < 4; ++d) O[d] = O[d] * alpha;
;                 }
;                 const float off = base - m, off1 = off + b32;
;                 float ps = 0.f;
; #pragma unroll
;                 for (int i = 0; i < 16; ++i) { S0[i] = fexp2(S0[i] + off); S1[i] = fexp2(S1[i] + off1); ps += S0[i] + S1[i]; }
;                 l += ps;
;                 const bf16x8 p0 = pack8(S0, 0), p1 = pack8(S0, 1), p2 = pack8(S1, 0), p3 = pack8(S1, 1);
	v_max3_f32 v218, v0, v66, v67
	v_sub_f32_e32 v0, v0, v218
	v_fma_f32 v126, v160, v126, -v218
	v_exp_f32_e32 v118, v0
	v_add_f32_e32 v223, v157, v126
	v_add_f32_e32 v0, v127, v126
	v_exp_f32_e32 v127, v0
	v_add_f32_e32 v0, v122, v223
	v_add_f32_e32 v122, v125, v126
	v_exp_f32_e32 v224, v0
	v_add_f32_e32 v0, v123, v126
	v_exp_f32_e32 v123, v122
	v_add_f32_e32 v122, v128, v223
	v_exp_f32_e32 v225, v122
	v_add_f32_e32 v122, v129, v126
	v_exp_f32_e32 v140, v122
	v_add_f32_e32 v122, v130, v223
	v_exp_f32_e32 v142, v122
	v_add_f32_e32 v122, v133, v126
	v_exp_f32_e32 v144, v122
	v_add_f32_e32 v122, v134, v223
	v_exp_f32_e32 v168, v122
	v_add_f32_e32 v122, v137, v126
	v_exp_f32_e32 v170, v122
	v_add_f32_e32 v122, v143, v223
	v_add_f32_e32 v129, v169, v223
	v_exp_f32_e32 v194, v122
	v_add_f32_e32 v122, v193, v126
	v_exp_f32_e32 v134, v129
	v_add_f32_e32 v129, v196, v126
	v_exp_f32_e32 v196, v122
	v_add_f32_e32 v122, v195, v223
	v_add_f32_e32 v125, v132, v223
	v_add_f32_e32 v130, v198, v223
	v_exp_f32_e32 v198, v122
	v_add_f32_e32 v122, v199, v126
	v_exp_f32_e32 v132, v125
	v_add_f32_e32 v125, v135, v126
	v_exp_f32_e32 v135, v130
	v_add_f32_e32 v130, v200, v126
	v_exp_f32_e32 v200, v122
	v_add_f32_e32 v122, v202, v223
	v_exp_f32_e32 v202, v122
	v_add_f32_e32 v122, v204, v126
	ds_read_b128 v[78:81], v191 offset:26624
	ds_read_b128 v[74:77], v191 offset:26656
	ds_read_b128 v[70:73], v191 offset:31232
	ds_read_b128 v[66:69], v191 offset:31264
	v_exp_f32_e32 v204, v122
	v_add_f32_e32 v122, v206, v223
	v_exp_f32_e32 v138, v0
	v_add_f32_e32 v0, v124, v223
	v_add_f32_e32 v124, v131, v126
	v_add_f32_e32 v128, v136, v223
	v_add_f32_e32 v131, v203, v223
	v_exp_f32_e32 v206, v122
	v_add_f32_e32 v122, v220, v126
	v_exp_f32_e32 v133, v128
	v_add_f32_e32 v128, v159, v126
	v_exp_f32_e32 v136, v131
	v_add_f32_e32 v131, v207, v126
	v_add_f32_e32 v137, v219, v223
	v_exp_f32_e32 v220, v122
	v_add_f32_e32 v122, v222, v223
	v_exp_f32_e32 v0, v0
	v_exp_f32_e32 v124, v124
	v_exp_f32_e32 v125, v125
	v_exp_f32_e32 v128, v128
	v_exp_f32_e32 v129, v129
	v_exp_f32_e32 v130, v130
	v_exp_f32_e32 v131, v131
	v_exp_f32_e32 v137, v137
	v_exp_f32_e32 v222, v122
	v_pk_mul_f32 v[64:65], v[64:65], v[118:119] op_sel_hi:[1,0]
	v_pk_mul_f32 v[62:63], v[62:63], v[118:119] op_sel_hi:[1,0]
	v_pk_mul_f32 v[60:61], v[60:61], v[118:119] op_sel_hi:[1,0]
	v_pk_mul_f32 v[58:59], v[58:59], v[118:119] op_sel_hi:[1,0]
	v_pk_mul_f32 v[56:57], v[56:57], v[118:119] op_sel_hi:[1,0]
	v_pk_mul_f32 v[54:55], v[54:55], v[118:119] op_sel_hi:[1,0]
	v_pk_mul_f32 v[52:53], v[52:53], v[118:119] op_sel_hi:[1,0]
	v_pk_mul_f32 v[50:51], v[50:51], v[118:119] op_sel_hi:[1,0]
	v_pk_mul_f32 v[48:49], v[48:49], v[118:119] op_sel_hi:[1,0]
	v_pk_mul_f32 v[46:47], v[46:47], v[118:119] op_sel_hi:[1,0]
	v_pk_mul_f32 v[44:45], v[44:45], v[118:119] op_sel_hi:[1,0]
	v_pk_mul_f32 v[42:43], v[42:43], v[118:119] op_sel_hi:[1,0]
	v_pk_mul_f32 v[40:41], v[40:41], v[118:119] op_sel_hi:[1,0]
	v_pk_mul_f32 v[38:39], v[38:39], v[118:119] op_sel_hi:[1,0]
	v_pk_mul_f32 v[36:37], v[36:37], v[118:119] op_sel_hi:[1,0]
	v_pk_mul_f32 v[34:35], v[34:35], v[118:119] op_sel_hi:[1,0]
	v_pk_mul_f32 v[32:33], v[32:33], v[118:119] op_sel_hi:[1,0]
	v_pk_mul_f32 v[30:31], v[30:31], v[118:119] op_sel_hi:[1,0]
	v_pk_mul_f32 v[28:29], v[28:29], v[118:119] op_sel_hi:[1,0]
	v_pk_mul_f32 v[26:27], v[26:27], v[118:119] op_sel_hi:[1,0]
	v_pk_mul_f32 v[24:25], v[24:25], v[118:119] op_sel_hi:[1,0]
	v_pk_mul_f32 v[22:23], v[22:23], v[118:119] op_sel_hi:[1,0]
	v_pk_mul_f32 v[20:21], v[20:21], v[118:119] op_sel_hi:[1,0]
	v_pk_mul_f32 v[18:19], v[18:19], v[118:119] op_sel_hi:[1,0]
	v_pk_mul_f32 v[16:17], v[16:17], v[118:119] op_sel_hi:[1,0]
	v_pk_mul_f32 v[14:15], v[14:15], v[118:119] op_sel_hi:[1,0]
	v_pk_mul_f32 v[12:13], v[12:13], v[118:119] op_sel_hi:[1,0]
	v_pk_mul_f32 v[10:11], v[10:11], v[118:119] op_sel_hi:[1,0]
	v_pk_mul_f32 v[8:9], v[8:9], v[118:119] op_sel_hi:[1,0]
	v_pk_mul_f32 v[6:7], v[6:7], v[118:119] op_sel_hi:[1,0]
	v_pk_mul_f32 v[4:5], v[4:5], v[118:119] op_sel_hi:[1,0]
	v_pk_mul_f32 v[2:3], v[2:3], v[118:119] op_sel_hi:[1,0]
	v_add_f32_e32 v139, v127, v224
	v_add_f32_e32 v141, v123, v225
	v_add_f32_e32 v145, v124, v132
	v_add_f32_e32 v171, v125, v133
	v_add_f32_e32 v197, v128, v134
	v_add_f32_e32 v201, v129, v135
	v_add_f32_e32 v205, v130, v136
	v_add_f32_e32 v221, v131, v137
	v_cvt_pk_bf16_f32 v122, v127, v138
	v_cvt_pk_bf16_f32 v123, v123, v140
	v_cvt_pk_bf16_f32 v124, v124, v144
	v_cvt_pk_bf16_f32 v125, v125, v170
	v_cvt_pk_bf16_f32 v126, v128, v196
	v_cvt_pk_bf16_f32 v127, v129, v200
	v_cvt_pk_bf16_f32 v128, v130, v204
	v_cvt_pk_bf16_f32 v129, v131, v220
	v_cvt_pk_bf16_f32 v130, v224, v0
	v_cvt_pk_bf16_f32 v131, v225, v142
	v_cvt_pk_bf16_f32 v132, v132, v168
	v_cvt_pk_bf16_f32 v133, v133, v194
	v_cvt_pk_bf16_f32 v134, v134, v198
	v_cvt_pk_bf16_f32 v135, v135, v202
	v_cvt_pk_bf16_f32 v136, v136, v206
	v_cvt_pk_bf16_f32 v137, v137, v222
	s_waitcnt lgkmcnt(5)
; #define LAS __attribute__((address_space(3)))
; #define MFMA32(a, b, c) __builtin_amdgcn_mfma_f32_32x32x16_bf16((a), (b), (c), 0, 0, 0)
; DI void diff_attn_phase(int wv, LAS unsigned char* lds, const bf16_t* qk, const bf16_t* vt, bf16_t* ob, const float* lq1, const float* lk1, const float* lq2, const float* lk2,
;                         const float* subg, int layer_idx) {
;     ...
; #pragma unroll
;                 for (int d = 0; d < 4; ++d) { O[d] = MFMA32(vf[d][0], p0, O[d]); O[d] = MFMA32(vf[d][1], p1, O[d]); }
;                 __builtin_amdgcn_sched_barrier(0);
; #pragma unroll
;                 for (int d = 0; d < 4; ++d)
; #pragma unroll
;                     for (int s2 = 0; s2 < 2; ++s2) vf[d][s2] = *(const LAS bf16x8*)(buf + voff + d * 32 * DA_VP + (32 + 16 * s2) * 2);
; #pragma unroll
;                 for (int d = 0; d < 4; ++d) { O[d] = MFMA32(vf[d][0], p2, O[d]); O[d] = MFMA32(vf[d][1], p3, O[d]); }
;             }
;             if (more) {
;                 LAS unsigned char* nb = lds + ((t + 1) & 1) * DA_BUF;
; #pragma unroll
;                 for (int i = 0; i < 2; ++i) { *(LAS u32x4*)(nb + kst_off + i * 32 * DA_KP) = gk[i]; *(LAS u32x4*)(nb + vst_off + i * 64 * DA_VP) = gv[i]; } }
;             __syncthreads();
;         }
	v_mfma_f32_32x32x16_bf16 v[34:49], v[86:89], v[122:125], v[34:49]
	s_waitcnt lgkmcnt(4)
	v_mfma_f32_32x32x16_bf16 v[34:49], v[82:85], v[126:129], v[34:49]
	v_add_f32_e64 v82, v138, v0
	v_add_f32_e64 v83, v139, v1
	s_waitcnt lgkmcnt(3)
	v_mfma_f32_32x32x16_bf16 v[18:33], v[78:81], v[122:125], v[18:33]
	v_add_f32_e64 v78, v82, v82
	v_add_f32_e64 v79, v82, v83
	v_mov_b32_e32 v143, v79
	v_add_f32_e64 v78, v140, v142
	v_add_f32_e64 v79, v141, v143
	v_pk_add_f32 v[78:79], v[78:79], v[78:79] op_sel_hi:[0,1]
	v_mov_b32_e32 v169, v79
	v_pk_add_f32 v[78:79], v[144:145], v[168:169]
	v_mfma_f32_32x32x16_bf16 v[50:65], v[94:97], v[122:125], v[50:65]
	v_pk_add_f32 v[78:79], v[78:79], v[78:79] op_sel_hi:[0,1]
	v_mov_b32_e32 v195, v79
	s_waitcnt lgkmcnt(1)
	v_mfma_f32_32x32x16_bf16 v[2:17], v[70:73], v[122:125], v[2:17]
	v_mfma_f32_32x32x16_bf16 v[18:33], v[74:77], v[126:129], v[18:33]
	v_add_f32_e64 v74, v170, v194
	v_add_f32_e64 v75, v171, v195
	v_pk_add_f32 v[74:75], v[74:75], v[74:75] op_sel_hi:[0,1]
	v_mov_b32_e32 v199, v75
	v_pk_add_f32 v[74:75], v[196:197], v[198:199]
	s_nop 0
	v_pk_add_f32 v[74:75], v[74:75], v[74:75] op_sel_hi:[0,1]
	v_mov_b32_e32 v203, v75
	v_mfma_f32_32x32x16_bf16 v[50:65], v[90:93], v[126:129], v[50:65]
	v_add_f32_e64 v70, v200, v202
	v_add_f32_e64 v71, v201, v203
	v_pk_add_f32 v[70:71], v[70:71], v[70:71] op_sel_hi:[0,1]
	v_mov_b32_e32 v207, v71
	v_pk_add_f32 v[70:71], v[204:205], v[206:207]
	s_nop 0
	v_pk_add_f32 v[70:71], v[70:71], v[70:71] op_sel_hi:[0,1]
	s_waitcnt lgkmcnt(0)
	v_mfma_f32_32x32x16_bf16 v[2:17], v[66:69], v[126:129], v[2:17]
	v_mov_b32_e32 v223, v71
	v_add_f32_e64 v70, v220, v222
	v_add_f32_e64 v71, v221, v223
	v_add_f32_e32 v159, v70, v71
	ds_read_b128 v[66:69], v191 offset:17472
	ds_read_b128 v[70:73], v191 offset:17504
	ds_read_b128 v[78:81], v191 offset:22080
	ds_read_b128 v[82:85], v191 offset:22112
	ds_read_b128 v[86:89], v191 offset:26688
	ds_read_b128 v[90:93], v191 offset:26720
	ds_read_b128 v[94:97], v191 offset:31296
	ds_read_b128 v[74:77], v191 offset:31328
	s_add_i32 s25, s25, 1
	s_bitcmp1_b32 s25, 0
	s_cselect_b32 s2, 0x8c00, 0
	s_add_i32 s2, s2, 0
	v_add_u32_e32 v0, s2, v167
	v_add_u32_e32 v223, s2, v208
	v_fmac_f32_e32 v159, v121, v118
	s_cmp_eq_u32 s1, s25
	s_mov_b32 s16, s14
	s_waitcnt vmcnt(3)
	ds_write_b128 v0, v[98:101]
	s_waitcnt vmcnt(1)
	ds_write_b128 v223, v[110:113] offset:17408
	ds_write_b128 v0, v[102:105] offset:8704
	s_waitcnt vmcnt(0)
	ds_write_b128 v223, v[106:109] offset:26624
	s_waitcnt lgkmcnt(11)
	v_mfma_f32_32x32x16_bf16 v[50:65], v[66:69], v[130:133], v[50:65]
	s_waitcnt lgkmcnt(10)
	v_mfma_f32_32x32x16_bf16 v[50:65], v[70:73], v[134:137], v[50:65]
	s_waitcnt lgkmcnt(9)
	v_mfma_f32_32x32x16_bf16 v[34:49], v[78:81], v[130:133], v[34:49]
	s_waitcnt lgkmcnt(8)
	v_mfma_f32_32x32x16_bf16 v[34:49], v[82:85], v[134:137], v[34:49]
	s_waitcnt lgkmcnt(7)
	v_mfma_f32_32x32x16_bf16 v[18:33], v[86:89], v[130:133], v[18:33]
	s_waitcnt lgkmcnt(6)
	v_mfma_f32_32x32x16_bf16 v[18:33], v[90:93], v[134:137], v[18:33]
	s_waitcnt lgkmcnt(5)
	v_mfma_f32_32x32x16_bf16 v[2:17], v[94:97], v[130:133], v[2:17]
	s_waitcnt lgkmcnt(0)
	s_barrier
	v_mfma_f32_32x32x16_bf16 v[2:17], v[74:77], v[134:137], v[2:17]
	s_cbranch_scc0 .LBB0_424
	s_branch .LBB0_427

; DI void ln_phase(int wv, const bf16_t* y, float* xo, const float* g, const float* bta, bf16_t* xb) {
;     ...
;     for (int row0 = bid * 8 + wid; row0 < M_TOK; row0 += R * nw) {
;         u32x4 raw[R][2], rsd[R][2];
; #pragma unroll
;         for (int r = 0; r < R; ++r) { const int row = (row0 + r * nw < M_TOK) ? row0 + r * nw : row0;
; #pragma unroll
;             for (int j = 0; j < 2; ++j) { raw[r][j] = *(const u32x4*)(y + (size_t)row * DM + j * 512 + lane * 8); rsd[r][j] = *(const u32x4*)(xb + (size_t)row * DM + j * 512 + lane * 8); } }
; #pragma unroll
;         for (int r = 0; r < R; ++r) {
;             const int row = row0 + r * nw;
;             if (row < M_TOK) {
;                 f32x4 v[4];
; #pragma unroll
;                 for (int j = 0; j < 2; ++j) { const u32x4 q = raw[r][j], x_ = rsd[r][j];
;                     v[2 * j] = (f32x4){__uint_as_float(q.x << 16), __uint_as_float(q.x & 0xffff0000u), __uint_as_float(q.y << 16), __uint_as_float(q.y & 0xffff0000u)}
;                              + (f32x4){__uint_as_float(x_.x << 16), __uint_as_float(x_.x & 0xffff0000u), __uint_as_float(x_.y << 16), __uint_as_float(x_.y & 0xffff0000u)} * ALPHA_RES;
;                     v[2 * j + 1] = (f32x4){__uint_as_float(q.z << 16), __uint_as_float(q.z & 0xffff0000u), __uint_as_float(q.w << 16), __uint_as_float(q.w & 0xffff0000u)}
;                                  + (f32x4){__uint_as_float(x_.z << 16), __uint_as_float(x_.z & 0xffff0000u), __uint_as_float(x_.w << 16), __uint_as_float(x_.w & 0xffff0000u)} * ALPHA_RES; }
;                 float s_ = 0.f;
; #pragma unroll
;                 for (int j = 0; j < 4; ++j) s_ += (v[j].x + v[j].y) + (v[j].z + v[j].w);
;                 const float mean = wave_sum(s_) * (1.f / DM); float s2 = 0.f;
.LBB0_586:
	v_ashrrev_i32_e32 v83, 31, v82
	s_waitcnt vmcnt(0)
	v_lshlrev_b64 v[38:39], 11, v[82:83]
	v_lshl_add_u64 v[42:43], v[90:91], 0, v[38:39]
	global_load_dwordx4 v[34:37], v[42:43], off
	s_nop 0
	v_lshl_add_u64 v[102:103], v[92:93], 0, v[38:39]
	global_load_dwordx4 v[38:41], v[102:103], off
	global_load_dwordx4 v[42:45], v[42:43], off offset:1024
	global_load_dwordx4 v[46:49], v[102:103], off offset:1024
	s_mul_i32 s0, s46, 24
	v_add_u32_e32 v98, s0, v82
	v_cmp_gt_i32_e64 s[8:9], s71, v98
	v_add_u32_e32 v96, s47, v82
	v_add_u32_e32 v100, s36, v82
	v_cmp_gt_i32_e64 s[6:7], s71, v96
	v_cmp_gt_i32_e64 s[4:5], s71, v100
	s_nop 1
	v_cndmask_b32_e64 v148, v82, v96, s[6:7]
	v_cndmask_b32_e64 v150, v82, v100, s[4:5]
	v_cndmask_b32_e64 v152, v82, v98, s[8:9]
	v_ashrrev_i32_e32 v149, 31, v148
	v_ashrrev_i32_e32 v151, 31, v150
	v_ashrrev_i32_e32 v153, 31, v152
	v_lshlrev_b64 v[148:149], 11, v[148:149]
	v_lshlrev_b64 v[150:151], 11, v[150:151]
	v_lshlrev_b64 v[152:153], 11, v[152:153]
	v_lshl_add_u64 v[154:155], v[90:91], 0, v[148:149]
	v_lshl_add_u64 v[148:149], v[92:93], 0, v[148:149]
	v_lshl_add_u64 v[156:157], v[90:91], 0, v[150:151]
	v_lshl_add_u64 v[150:151], v[92:93], 0, v[150:151]
	v_lshl_add_u64 v[158:159], v[90:91], 0, v[152:153]
	v_lshl_add_u64 v[152:153], v[92:93], 0, v[152:153]
	global_load_dwordx4 v[176:179], v[154:155], off
	global_load_dwordx4 v[180:183], v[154:155], off offset:1024
	global_load_dwordx4 v[184:187], v[148:149], off
	global_load_dwordx4 v[188:191], v[148:149], off offset:1024
	global_load_dwordx4 v[192:195], v[156:157], off
	global_load_dwordx4 v[196:199], v[156:157], off offset:1024
	global_load_dwordx4 v[200:203], v[150:151], off
	global_load_dwordx4 v[204:207], v[150:151], off offset:1024
	global_load_dwordx4 v[208:211], v[158:159], off
	global_load_dwordx4 v[212:215], v[158:159], off offset:1024
	global_load_dwordx4 v[216:219], v[152:153], off
	global_load_dwordx4 v[220:223], v[152:153], off offset:1024
	s_waitcnt vmcnt(14)
	v_lshlrev_b32_e32 v56, 16, v38
	v_lshlrev_b32_e32 v54, 16, v34
	v_and_b32_e32 v55, 0xffff0000, v34
	v_lshlrev_b32_e32 v34, 16, v35
	v_and_b32_e32 v35, 0xffff0000, v35
	v_and_b32_e32 v57, 0xffff0000, v38
	v_lshlrev_b32_e32 v38, 16, v39
	v_and_b32_e32 v39, 0xffff0000, v39
	v_lshlrev_b32_e32 v58, 16, v36
	v_and_b32_e32 v59, 0xffff0000, v36
	v_lshlrev_b32_e32 v36, 16, v37
	v_and_b32_e32 v37, 0xffff0000, v37
	v_lshlrev_b32_e32 v60, 16, v40
	v_and_b32_e32 v61, 0xffff0000, v40
	v_lshlrev_b32_e32 v40, 16, v41
	v_and_b32_e32 v41, 0xffff0000, v41
	v_pk_fma_f32 v[84:85], v[38:39], s[70:71], v[34:35] op_sel_hi:[1,0,1]
	v_pk_fma_f32 v[112:113], v[56:57], s[70:71], v[54:55] op_sel_hi:[1,0,1]
	v_pk_fma_f32 v[86:87], v[40:41], s[70:71], v[36:37] op_sel_hi:[1,0,1]
	v_pk_fma_f32 v[88:89], v[60:61], s[70:71], v[58:59] op_sel_hi:[1,0,1]
	v_pk_mov_b32 v[34:35], v[112:113], v[84:85] op_sel:[1,0]
	v_mov_b32_e32 v36, v112
	v_mov_b32_e32 v37, v85
	v_pk_mov_b32 v[38:39], v[88:89], v[86:87] op_sel:[1,0]
	v_mov_b32_e32 v40, v88
	v_mov_b32_e32 v41, v87
	s_waitcnt vmcnt(13)
	v_lshlrev_b32_e32 v62, 16, v42
	v_and_b32_e32 v63, 0xffff0000, v42
	v_lshlrev_b32_e32 v42, 16, v43
	v_and_b32_e32 v43, 0xffff0000, v43
	s_waitcnt vmcnt(12)
	v_lshlrev_b32_e32 v64, 16, v46
	v_and_b32_e32 v65, 0xffff0000, v46
	v_lshlrev_b32_e32 v46, 16, v47
	v_and_b32_e32 v47, 0xffff0000, v47
	v_lshlrev_b32_e32 v66, 16, v44
	v_and_b32_e32 v67, 0xffff0000, v44
	v_lshlrev_b32_e32 v44, 16, v45
	v_and_b32_e32 v45, 0xffff0000, v45
	v_lshlrev_b32_e32 v68, 16, v48
	v_and_b32_e32 v69, 0xffff0000, v48
	v_lshlrev_b32_e32 v48, 16, v49
	v_and_b32_e32 v49, 0xffff0000, v49
	v_pk_add_f32 v[34:35], v[34:35], v[36:37]
	v_pk_add_f32 v[36:37], v[38:39], v[40:41]
	v_pk_fma_f32 v[108:109], v[46:47], s[70:71], v[42:43] op_sel_hi:[1,0,1]
	v_pk_fma_f32 v[110:111], v[64:65], s[70:71], v[62:63] op_sel_hi:[1,0,1]
	v_pk_fma_f32 v[104:105], v[48:49], s[70:71], v[44:45] op_sel_hi:[1,0,1]
	v_pk_fma_f32 v[106:107], v[68:69], s[70:71], v[66:67] op_sel_hi:[1,0,1]
	v_add_f32_e32 v0, v34, v35
	v_pk_add_f32 v[34:35], v[36:37], v[36:37] op_sel_hi:[0,1]
	v_add_f32_e32 v43, v110, v111
	v_add_f32_e32 v45, v108, v109
	v_mov_b32_e32 v42, v106
	v_mov_b32_e32 v44, v107
	v_mov_b32_e32 v46, v105
	v_add_f32_e32 v47, 0, v0
	v_mov_b32_e32 v34, v104
	v_pk_add_f32 v[38:39], v[42:43], v[44:45]
	v_pk_add_f32 v[34:35], v[34:35], v[46:47]
	v_cndmask_b32_e64 v50, v82, v96, s[6:7]
	v_pk_add_f32 v[34:35], v[38:39], v[34:35]
	v_cndmask_b32_e64 v52, v82, v100, s[4:5]
	v_add_f32_e32 v0, v34, v35
	ds_bpermute_b32 v35, v233, v0
	v_cndmask_b32_e64 v34, v82, v98, s[8:9]
	v_ashrrev_i32_e32 v51, 31, v50
	v_ashrrev_i32_e32 v53, 31, v52
	v_lshlrev_b64 v[36:37], 11, v[50:51]
	s_waitcnt lgkmcnt(0)
	v_add_f32_e32 v0, v0, v35
	ds_bpermute_b32 v40, v234, v0
	v_ashrrev_i32_e32 v35, 31, v34
	v_lshlrev_b64 v[34:35], 11, v[34:35]
	v_lshl_add_u64 v[114:115], v[92:93], 0, v[34:35]
	v_lshlrev_b64 v[38:39], 11, v[52:53]
	s_waitcnt lgkmcnt(0)
	v_add_f32_e32 v0, v0, v40
	ds_bpermute_b32 v44, v235, v0
	v_lshl_add_u64 v[40:41], v[90:91], 0, v[36:37]
	v_lshl_add_u64 v[36:37], v[92:93], 0, v[36:37]
	v_lshl_add_u64 v[42:43], v[90:91], 0, v[38:39]
	s_waitcnt vmcnt(0)
	v_mov_b32_e32 v74, v176
	v_mov_b32_e32 v75, v177
	v_mov_b32_e32 v76, v178
	v_mov_b32_e32 v77, v179
	v_mov_b32_e32 v66, v180
	v_mov_b32_e32 v67, v181
	v_mov_b32_e32 v68, v182
	v_mov_b32_e32 v69, v183
	s_waitcnt lgkmcnt(0)
; DI void ln_phase(int wv, const bf16_t* y, float* xo, const float* g, const float* bta, bf16_t* xb) {
;     ...
;                 const float mean = wave_sum(s_) * (1.f / DM); float s2 = 0.f;
; #pragma unroll
;                 for (int j = 0; j < 4; ++j) { v[j] = v[j] - mean; s2 += (v[j].x * v[j].x + v[j].y * v[j].y) + (v[j].z * v[j].z + v[j].w * v[j].w); }
;                 const float rstd = 1.f / sqrtf(wave_sum(s2) * (1.f / DM) + 1e-5f);
; #pragma unroll
;                 for (int j = 0; j < 2; ++j) { const f32x4 y0 = v[2 * j] * rstd * gv[2 * j] + bv[2 * j], y1 = v[2 * j + 1] * rstd * gv[2 * j + 1] + bv[2 * j + 1];
;                     if (xo) { *(f32x4*)(xo + (size_t)row * DM + j * 512 + lane * 8) = y0; *(f32x4*)(xo + (size_t)row * DM + j * 512 + lane * 8 + 4) = y1; }
	v_add_f32_e32 v0, v0, v44
	ds_bpermute_b32 v46, v236, v0
	v_lshl_add_u64 v[44:45], v[90:91], 0, v[34:35]
	v_mov_b32_e32 v78, v184
	v_mov_b32_e32 v79, v185
	v_mov_b32_e32 v80, v186
	v_mov_b32_e32 v81, v187
	v_mov_b32_e32 v70, v188
	v_mov_b32_e32 v71, v189
	v_mov_b32_e32 v72, v190
	v_mov_b32_e32 v73, v191
	v_mov_b32_e32 v58, v192
	v_mov_b32_e32 v59, v193
	v_mov_b32_e32 v60, v194
	v_mov_b32_e32 v61, v195
	v_mov_b32_e32 v50, v196
	v_mov_b32_e32 v51, v197
	v_mov_b32_e32 v52, v198
	v_mov_b32_e32 v53, v199
	v_lshl_add_u64 v[38:39], v[92:93], 0, v[38:39]
	v_lshlrev_b64 v[82:83], 12, v[82:83]
	s_waitcnt lgkmcnt(0)
	v_add_f32_e32 v0, v0, v46
	ds_bpermute_b32 v34, v237, v0
	s_waitcnt lgkmcnt(0)
	v_add_f32_e32 v0, v0, v34
	ds_bpermute_b32 v42, v238, v0
	v_mov_b32_e32 v62, v200
	v_mov_b32_e32 v63, v201
	v_mov_b32_e32 v64, v202
	v_mov_b32_e32 v65, v203
	v_mov_b32_e32 v54, v204
	v_mov_b32_e32 v55, v205
	v_mov_b32_e32 v56, v206
	v_mov_b32_e32 v57, v207
	s_nop 0
	v_mov_b32_e32 v38, v208
	v_mov_b32_e32 v39, v209
	v_mov_b32_e32 v40, v210
	v_mov_b32_e32 v41, v211
	v_mov_b32_e32 v34, v212
	v_mov_b32_e32 v35, v213
	v_mov_b32_e32 v36, v214
	v_mov_b32_e32 v37, v215
	s_waitcnt lgkmcnt(0)
	v_add_f32_e32 v97, v0, v42
	v_fmamk_f32 v113, v97, 0xba800000, v113
	v_fmac_f32_e32 v112, 0xba800000, v97
	v_fmamk_f32 v85, v97, 0xba800000, v85
	v_fmac_f32_e32 v84, 0xba800000, v97
	v_fmamk_f32 v89, v97, 0xba800000, v89
	v_fmac_f32_e32 v88, 0xba800000, v97
	v_fmamk_f32 v87, v97, 0xba800000, v87
	v_fmac_f32_e32 v86, 0xba800000, v97
	v_pk_mul_f32 v[42:43], v[84:85], v[84:85]
	v_pk_mul_f32 v[44:45], v[112:113], v[112:113]
	v_pk_mul_f32 v[46:47], v[86:87], v[86:87]
	v_pk_mul_f32 v[48:49], v[88:89], v[88:89]
	v_fmac_f32_e32 v110, 0xba800000, v97
	v_pk_mov_b32 v[116:117], v[44:45], v[42:43] op_sel:[1,0]
	v_mov_b32_e32 v45, v43
	v_pk_mov_b32 v[42:43], v[48:49], v[46:47] op_sel:[1,0]
	v_mov_b32_e32 v49, v47
	v_fmac_f32_e32 v108, 0xba800000, v97
	v_fmamk_f32 v111, v97, 0xba800000, v111
	v_mul_f32_e32 v0, v110, v110
	v_fmamk_f32 v109, v97, 0xba800000, v109
	v_pk_add_f32 v[44:45], v[116:117], v[44:45]
	v_pk_add_f32 v[42:43], v[42:43], v[48:49]
	v_pk_fma_f32 v[46:47], v[110:111], v[110:111], v[0:1] op_sel_hi:[1,1,0]
	v_mul_f32_e32 v0, v108, v108
	v_pk_add_f32 v[44:45], v[44:45], v[44:45] op_sel_hi:[0,1]
	v_pk_add_f32 v[42:43], v[42:43], v[42:43] op_sel_hi:[0,1]
	v_pk_fma_f32 v[48:49], v[108:109], v[108:109], v[0:1] op_sel_hi:[1,1,0]
	v_fmamk_f32 v105, v97, 0xba800000, v105
	v_fmac_f32_e32 v104, 0xba800000, v97
	v_fmamk_f32 v107, v97, 0xba800000, v107
	v_fmac_f32_e32 v106, 0xba800000, v97
	v_mul_f32_e32 v46, v106, v106
	v_mul_f32_e32 v48, v107, v107
	v_mul_f32_e32 v44, v104, v104
	v_mul_f32_e32 v42, v105, v105
	v_pk_add_f32 v[46:47], v[46:47], v[48:49]
	v_pk_add_f32 v[42:43], v[44:45], v[42:43]
	s_nop 0
	v_pk_add_f32 v[42:43], v[46:47], v[42:43]
	s_nop 0
	v_add_f32_e32 v0, v42, v43
	v_mov_b32_e32 v46, v216
	v_mov_b32_e32 v47, v217
	v_mov_b32_e32 v48, v218
	v_mov_b32_e32 v49, v219
	v_mov_b32_e32 v42, v220
	v_mov_b32_e32 v43, v221
	v_mov_b32_e32 v44, v222
	v_mov_b32_e32 v45, v223
	ds_bpermute_b32 v97, v233, v0
	s_waitcnt lgkmcnt(0)
	v_add_f32_e32 v0, v0, v97
	ds_bpermute_b32 v97, v234, v0
	s_waitcnt lgkmcnt(0)
	v_add_f32_e32 v0, v0, v97
	ds_bpermute_b32 v97, v235, v0
	s_waitcnt lgkmcnt(0)
	v_add_f32_e32 v0, v0, v97
	ds_bpermute_b32 v97, v236, v0
	s_waitcnt lgkmcnt(0)
	v_add_f32_e32 v0, v0, v97
	ds_bpermute_b32 v97, v237, v0
	s_waitcnt lgkmcnt(0)
	v_add_f32_e32 v0, v0, v97
	ds_bpermute_b32 v97, v238, v0
	s_waitcnt lgkmcnt(0)
	v_add_f32_e32 v0, v0, v97
	v_fmamk_f32 v0, v0, 0x3a800000, v243
	v_mul_f32_e32 v97, 0x4f800000, v0
	v_cmp_gt_f32_e32 vcc, s37, v0
	s_nop 1
	v_cndmask_b32_e32 v0, v0, v97, vcc
	v_sqrt_f32_e32 v97, v0
	s_nop 0
	v_add_u32_e32 v99, -1, v97
	v_add_u32_e32 v101, 1, v97
	v_fma_f32 v114, -v99, v97, v0
	v_fma_f32 v115, -v101, v97, v0
	v_cmp_ge_f32_e64 s[0:1], 0, v114
	s_nop 1
	v_cndmask_b32_e64 v97, v97, v99, s[0:1]
	v_cmp_lt_f32_e64 s[0:1], 0, v115
	v_lshl_add_u64 v[114:115], v[94:95], 0, v[82:83]
	s_nop 0
	v_cndmask_b32_e64 v97, v97, v101, s[0:1]
	v_mul_f32_e32 v99, 0x37800000, v97
	v_cndmask_b32_e32 v97, v97, v99, vcc
	v_cmp_class_f32_e32 vcc, v0, v242
	s_nop 1
	v_cndmask_b32_e32 v0, v97, v0, vcc
	v_div_scale_f32 v97, s[0:1], v0, v0, 1.0
	v_rcp_f32_e32 v99, v97
	v_div_scale_f32 v82, vcc, 1.0, v0, 1.0
	v_fma_f32 v83, -v97, v99, 1.0
	v_fmac_f32_e32 v99, v83, v99
	v_mul_f32_e32 v83, v82, v99
	v_fma_f32 v101, -v97, v83, v82
	v_fmac_f32_e32 v83, v101, v99
	v_fma_f32 v82, -v97, v83, v82
	v_div_fmas_f32 v82, v82, v99, v83
	v_div_fixup_f32 v116, v82, v0, 1.0
	v_pk_mul_f32 v[82:83], v[112:113], v[116:117] op_sel_hi:[1,0]
	v_pk_mul_f32 v[84:85], v[84:85], v[116:117] op_sel_hi:[1,0]
	v_pk_mul_f32 v[112:113], v[88:89], v[116:117] op_sel_hi:[1,0]
	v_pk_mul_f32 v[86:87], v[86:87], v[116:117] op_sel_hi:[1,0]
	v_cndmask_b32_e64 v0, 0, 1, s[28:29]
	v_pk_fma_f32 v[84:85], v[12:13], v[84:85], v[16:17]
	v_pk_fma_f32 v[82:83], v[10:11], v[82:83], v[14:15]
	v_pk_fma_f32 v[88:89], v[4:5], v[86:87], v[8:9]
	v_cmp_ne_u32_e64 s[0:1], 1, v0
	s_andn2_b64 vcc, exec, s[28:29]
	v_pk_fma_f32 v[86:87], v[2:3], v[112:113], v[6:7]
	s_cbranch_vccnz .LBB0_588
	global_store_dwordx4 v[114:115], v[82:85], off
	global_store_dwordx4 v[114:115], v[86:89], off offset:16

; #define LAS __attribute__((address_space(3)))
; #define scr (p.ws + opq_off(SCR_OFF))
; DI void transpose_item(const float* W, int K, int ldw, int nblk, bf16_t* WT, LAS float* scr, int item, int lane) {
;     const int kb = item / nblk, nb = item % nblk, k0 = 64 * kb, n0 = 32 * nb;
;     float wv_[32];
; #pragma unroll
;     for (int i = 0; i < 32; ++i) { const int kk = 2 * i + (lane >> 5); wv_[i] = W[(size_t)(k0 + kk) * ldw + n0 + (lane & 31)]; }
; #pragma unroll
;     for (int i = 0; i < 32; ++i) { const int kk = 2 * i + (lane >> 5); scr[kk * 33 + (lane & 31)] = wv_[i]; }
;     asm volatile("s_waitcnt lgkmcnt(0)" ::: "memory");
; DI void wprep_layer(int wv, LAS unsigned char* lds, const Params& p, int layer, bf16_t* wb) {
;     ...
;         transpose_item(w2, 4096, 1024, 32, wb_2, scr, r, lane);
.LBB0_611:
	v_cmp_le_i32_e32 vcc, s44, v19
	s_and_saveexec_b64 s[6:7], vcc
	s_xor_b64 s[6:7], exec, s[6:7]
	s_cbranch_execz .LBB0_621
	v_add_u32_e32 v0, s73, v19
	s_movk_i32 s2, 0x1ff
	v_cmp_lt_i32_e32 vcc, s2, v0
	s_and_saveexec_b64 s[8:9], vcc
	s_xor_b64 s[8:9], exec, s[8:9]
	s_cbranch_execz .LBB0_618
	s_movk_i32 s2, 0x9ff
	v_cmp_lt_u32_e32 vcc, s2, v0
	s_and_saveexec_b64 s[12:13], vcc
	s_xor_b64 s[20:21], exec, s[12:13]
	s_cbranch_execz .LBB0_615
	v_and_b32_e32 v0, 0x7fffffc0, v35
	v_add_u32_e32 v20, 0xffffec00, v0
	v_and_b32_e32 v26, 0x3e0, v18
	v_or_b32_e32 v24, v20, v28
	v_lshlrev_b32_e32 v0, 2, v26
	v_mov_b32_e32 v25, v1
	v_lshl_add_u64 v[22:23], v[2:3], 0, v[0:1]
	v_lshlrev_b64 v[36:37], 12, v[24:25]
	v_lshl_add_u64 v[36:37], v[22:23], 0, v[36:37]
	v_or_b32_e32 v0, 2, v24
	global_load_dword v21, v[36:37], off
	v_lshlrev_b64 v[36:37], 12, v[0:1]
	v_lshl_add_u64 v[36:37], v[22:23], 0, v[36:37]
	v_or_b32_e32 v0, 4, v24
	global_load_dword v27, v[36:37], off
	v_lshlrev_b64 v[36:37], 12, v[0:1]
	v_lshl_add_u64 v[36:37], v[22:23], 0, v[36:37]
	v_or_b32_e32 v0, 6, v24
	global_load_dword v38, v[36:37], off
	v_lshlrev_b64 v[36:37], 12, v[0:1]
	v_lshl_add_u64 v[36:37], v[22:23], 0, v[36:37]
	v_or_b32_e32 v0, 8, v24
	global_load_dword v39, v[36:37], off
	v_lshlrev_b64 v[36:37], 12, v[0:1]
	v_lshl_add_u64 v[36:37], v[22:23], 0, v[36:37]
	v_or_b32_e32 v0, 10, v24
	global_load_dword v40, v[36:37], off
	v_lshlrev_b64 v[36:37], 12, v[0:1]
	v_lshl_add_u64 v[36:37], v[22:23], 0, v[36:37]
	v_or_b32_e32 v0, 12, v24
	global_load_dword v41, v[36:37], off
	v_lshlrev_b64 v[36:37], 12, v[0:1]
	v_lshl_add_u64 v[36:37], v[22:23], 0, v[36:37]
	v_or_b32_e32 v0, 14, v24
	global_load_dword v42, v[36:37], off
	v_lshlrev_b64 v[36:37], 12, v[0:1]
	v_lshl_add_u64 v[36:37], v[22:23], 0, v[36:37]
	v_or_b32_e32 v0, 16, v24
	global_load_dword v43, v[36:37], off
	v_lshlrev_b64 v[36:37], 12, v[0:1]
	v_lshl_add_u64 v[36:37], v[22:23], 0, v[36:37]
	v_or_b32_e32 v0, 18, v24
	global_load_dword v44, v[36:37], off
	v_lshlrev_b64 v[36:37], 12, v[0:1]
	v_lshl_add_u64 v[36:37], v[22:23], 0, v[36:37]
	v_or_b32_e32 v0, 20, v24
	global_load_dword v45, v[36:37], off
	v_lshlrev_b64 v[36:37], 12, v[0:1]
	v_lshl_add_u64 v[36:37], v[22:23], 0, v[36:37]
	v_or_b32_e32 v0, 22, v24
	global_load_dword v46, v[36:37], off
	v_lshlrev_b64 v[36:37], 12, v[0:1]
	v_lshl_add_u64 v[36:37], v[22:23], 0, v[36:37]
	v_or_b32_e32 v0, 24, v24
	global_load_dword v47, v[36:37], off
	v_lshlrev_b64 v[36:37], 12, v[0:1]
	v_lshl_add_u64 v[36:37], v[22:23], 0, v[36:37]
	v_or_b32_e32 v0, 26, v24
	global_load_dword v48, v[36:37], off
	v_lshlrev_b64 v[36:37], 12, v[0:1]
	v_lshl_add_u64 v[36:37], v[22:23], 0, v[36:37]
	v_or_b32_e32 v0, 28, v24
	global_load_dword v49, v[36:37], off
	v_lshlrev_b64 v[36:37], 12, v[0:1]
	v_lshl_add_u64 v[36:37], v[22:23], 0, v[36:37]
	v_or_b32_e32 v0, 30, v24
	global_load_dword v50, v[36:37], off
	v_lshlrev_b64 v[36:37], 12, v[0:1]
	v_lshl_add_u64 v[36:37], v[22:23], 0, v[36:37]
	v_or_b32_e32 v0, 32, v24
	global_load_dword v51, v[36:37], off
	v_lshlrev_b64 v[36:37], 12, v[0:1]
	v_lshl_add_u64 v[36:37], v[22:23], 0, v[36:37]
	v_or_b32_e32 v0, 34, v24
	global_load_dword v52, v[36:37], off
	v_lshlrev_b64 v[36:37], 12, v[0:1]
	v_lshl_add_u64 v[36:37], v[22:23], 0, v[36:37]
	v_or_b32_e32 v0, 36, v24
	global_load_dword v53, v[36:37], off
	v_lshlrev_b64 v[36:37], 12, v[0:1]
	v_lshl_add_u64 v[36:37], v[22:23], 0, v[36:37]
	v_or_b32_e32 v0, 38, v24
	global_load_dword v54, v[36:37], off
	v_lshlrev_b64 v[36:37], 12, v[0:1]
	v_lshl_add_u64 v[36:37], v[22:23], 0, v[36:37]
	v_or_b32_e32 v0, 40, v24
	global_load_dword v55, v[36:37], off
	v_lshlrev_b64 v[36:37], 12, v[0:1]
	v_lshl_add_u64 v[36:37], v[22:23], 0, v[36:37]
	v_or_b32_e32 v0, 42, v24
	global_load_dword v56, v[36:37], off
	v_lshlrev_b64 v[36:37], 12, v[0:1]
	v_lshl_add_u64 v[36:37], v[22:23], 0, v[36:37]
	v_or_b32_e32 v0, 44, v24
	global_load_dword v57, v[36:37], off
	v_lshlrev_b64 v[36:37], 12, v[0:1]
	v_lshl_add_u64 v[36:37], v[22:23], 0, v[36:37]
	v_or_b32_e32 v0, 46, v24
	global_load_dword v58, v[36:37], off
	v_lshlrev_b64 v[36:37], 12, v[0:1]
	v_lshl_add_u64 v[36:37], v[22:23], 0, v[36:37]
	v_or_b32_e32 v0, 48, v24
	global_load_dword v59, v[36:37], off
	v_lshlrev_b64 v[36:37], 12, v[0:1]
	v_lshl_add_u64 v[36:37], v[22:23], 0, v[36:37]
	v_or_b32_e32 v0, 50, v24
	global_load_dword v60, v[36:37], off
	v_lshlrev_b64 v[36:37], 12, v[0:1]
	v_lshl_add_u64 v[36:37], v[22:23], 0, v[36:37]
	v_or_b32_e32 v0, 52, v24
	global_load_dword v61, v[36:37], off
	v_lshlrev_b64 v[36:37], 12, v[0:1]
	v_lshl_add_u64 v[36:37], v[22:23], 0, v[36:37]
	v_or_b32_e32 v0, 54, v24
	global_load_dword v62, v[36:37], off
	v_lshlrev_b64 v[36:37], 12, v[0:1]
	v_lshl_add_u64 v[36:37], v[22:23], 0, v[36:37]
	v_or_b32_e32 v0, 56, v24
	global_load_dword v63, v[36:37], off
	v_lshlrev_b64 v[36:37], 12, v[0:1]
	v_lshl_add_u64 v[36:37], v[22:23], 0, v[36:37]
	v_or_b32_e32 v0, 58, v24
	global_load_dword v64, v[36:37], off
	v_lshlrev_b64 v[36:37], 12, v[0:1]
	v_lshl_add_u64 v[36:37], v[22:23], 0, v[36:37]
	v_or_b32_e32 v0, 60, v24
	global_load_dword v65, v[36:37], off
	v_lshlrev_b64 v[36:37], 12, v[0:1]
	v_or_b32_e32 v0, 62, v24
	v_lshlrev_b64 v[24:25], 12, v[0:1]
	v_lshl_add_u64 v[36:37], v[22:23], 0, v[36:37]
	v_lshl_add_u64 v[22:23], v[22:23], 0, v[24:25]
	global_load_dword v36, v[36:37], off
	global_load_dword v0, v[22:23], off
	s_waitcnt vmcnt(30)
; #define LAS __attribute__((address_space(3)))
; DI unsigned pk2(float lo, float hi) { f32x2 f = {lo, hi}; bf2_t v = __builtin_convertvector(f, bf2_t); return __builtin_bit_cast(unsigned, v); }
; #define scr (p.ws + opq_off(SCR_OFF))
; DI void transpose_item(const float* W, int K, int ldw, int nblk, bf16_t* WT, LAS float* scr, int item, int lane) {
;     ...
;     for (int i = 0; i < 32; ++i) { const int kk = 2 * i + (lane >> 5); scr[kk * 33 + (lane & 31)] = wv_[i]; }
;     asm volatile("s_waitcnt lgkmcnt(0)" ::: "memory");
;     const int c = lane & 7;
; #pragma unroll
;     for (int j = 0; j < 4; ++j) { const int n = (lane >> 3) + 8 * j; const LAS float* s = scr + (8 * c) * 33 + n;
;         u32x4 o; o.x = pk2(s[0 * 33], s[1 * 33]); o.y = pk2(s[2 * 33], s[3 * 33]); o.z = pk2(s[4 * 33], s[5 * 33]); o.w = pk2(s[6 * 33], s[7 * 33]);
;         *(u32x4*)(WT + (size_t)(n0 + n) * K + k0 + 8 * c) = o; }
;     asm volatile("s_waitcnt lgkmcnt(0)" ::: "memory");
	ds_write2_b32 v29, v21, v27 offset1:66
	s_waitcnt vmcnt(28)
	ds_write2_b32 v29, v38, v39 offset0:132 offset1:198
	v_add_u32_e32 v21, 0x400, v29
	s_waitcnt vmcnt(26)
	ds_write2_b32 v21, v40, v41 offset0:8 offset1:74
	s_waitcnt vmcnt(24)
	ds_write2_b32 v21, v42, v43 offset0:140 offset1:206
	v_add_u32_e32 v21, 0x800, v29
	s_waitcnt vmcnt(22)
	ds_write2_b32 v21, v44, v45 offset0:16 offset1:82
	s_waitcnt vmcnt(20)
	ds_write2_b32 v21, v46, v47 offset0:148 offset1:214
	v_add_u32_e32 v21, 0xc00, v29
	s_waitcnt vmcnt(18)
	ds_write2_b32 v21, v48, v49 offset0:24 offset1:90
	s_waitcnt vmcnt(16)
	ds_write2_b32 v21, v50, v51 offset0:156 offset1:222
	v_add_u32_e32 v21, 0x1000, v29
	s_waitcnt vmcnt(14)
	ds_write2_b32 v21, v52, v53 offset0:32 offset1:98
	s_waitcnt vmcnt(12)
	ds_write2_b32 v21, v54, v55 offset0:164 offset1:230
	v_add_u32_e32 v21, 0x1400, v29
	s_waitcnt vmcnt(10)
	ds_write2_b32 v21, v56, v57 offset0:40 offset1:106
	s_waitcnt vmcnt(8)
	ds_write2_b32 v21, v58, v59 offset0:172 offset1:238
	v_add_u32_e32 v21, 0x1800, v29
	s_waitcnt vmcnt(6)
	ds_write2_b32 v21, v60, v61 offset0:48 offset1:114
	s_waitcnt vmcnt(4)
	ds_write2_b32 v21, v62, v63 offset0:180 offset1:246
	v_add_u32_e32 v21, 0x1c00, v29
	s_waitcnt vmcnt(2)
	ds_write2_b32 v21, v64, v65 offset0:56 offset1:122
	s_waitcnt vmcnt(0)
	ds_write2_b32 v21, v36, v0 offset0:188 offset1:254
	s_waitcnt lgkmcnt(0)
	ds_read2_b32 v[36:37], v31 offset0:33 offset1:41
	ds_read2_b32 v[38:39], v31 offset1:8
	ds_read2_b32 v[40:41], v31 offset0:66 offset1:74
	ds_read2_b32 v[42:43], v31 offset0:99 offset1:107
	ds_read2_b32 v[44:45], v31 offset0:132 offset1:140
	ds_read2_b32 v[46:47], v31 offset0:165 offset1:173
	ds_read2_b32 v[48:49], v31 offset0:198 offset1:206
	ds_read2_b32 v[50:51], v31 offset0:231 offset1:239
	v_mov_b32_e32 v21, v1
	v_or_b32_e32 v0, v26, v30
	v_lshl_add_u64 v[24:25], v[20:21], 1, v[6:7]
	v_lshlrev_b32_e32 v0, 13, v0
	v_lshl_add_u64 v[52:53], v[24:25], 0, v[0:1]
	v_or_b32_e32 v0, v26, v32
	s_waitcnt lgkmcnt(6)
	v_cvt_pk_bf16_f32 v20, v38, v36
	s_waitcnt lgkmcnt(4)
	v_cvt_pk_bf16_f32 v21, v40, v42
	s_waitcnt lgkmcnt(2)
	v_cvt_pk_bf16_f32 v22, v44, v46
	s_waitcnt lgkmcnt(0)
	v_cvt_pk_bf16_f32 v23, v48, v50
	v_lshlrev_b32_e32 v0, 13, v0
	global_store_dwordx4 v[52:53], v[20:23], off
	s_nop 1
	v_cvt_pk_bf16_f32 v20, v39, v37
	v_cvt_pk_bf16_f32 v21, v41, v43
	v_cvt_pk_bf16_f32 v22, v45, v47
	v_cvt_pk_bf16_f32 v23, v49, v51
	v_lshl_add_u64 v[36:37], v[24:25], 0, v[0:1]
	global_store_dwordx4 v[36:37], v[20:23], off
	ds_read2_b32 v[36:37], v31 offset0:49 offset1:57
	ds_read2_b32 v[38:39], v31 offset0:16 offset1:24
	ds_read2_b32 v[40:41], v31 offset0:82 offset1:90
	ds_read2_b32 v[42:43], v31 offset0:115 offset1:123
	ds_read2_b32 v[44:45], v31 offset0:148 offset1:156
	ds_read2_b32 v[46:47], v31 offset0:181 offset1:189
	ds_read2_b32 v[48:49], v31 offset0:214 offset1:222
	ds_read2_b32 v[50:51], v31 offset0:247 offset1:255
	v_or_b32_e32 v0, v26, v33
	v_lshlrev_b32_e32 v0, 13, v0
	v_lshl_add_u64 v[52:53], v[24:25], 0, v[0:1]
	v_or_b32_e32 v0, v26, v34
	s_waitcnt lgkmcnt(6)
	v_cvt_pk_bf16_f32 v20, v38, v36
	s_waitcnt lgkmcnt(4)
	v_cvt_pk_bf16_f32 v21, v40, v42
	s_waitcnt lgkmcnt(2)
	v_cvt_pk_bf16_f32 v22, v44, v46
	s_waitcnt lgkmcnt(0)
	v_cvt_pk_bf16_f32 v23, v48, v50
	v_lshlrev_b32_e32 v0, 13, v0
	global_store_dwordx4 v[52:53], v[20:23], off
	v_lshl_add_u64 v[24:25], v[24:25], 0, v[0:1]
	s_nop 0
	v_cvt_pk_bf16_f32 v20, v39, v37
	v_cvt_pk_bf16_f32 v21, v41, v43
	v_cvt_pk_bf16_f32 v22, v45, v47
	v_cvt_pk_bf16_f32 v23, v49, v51
	global_store_dwordx4 v[24:25], v[20:23], off
	s_waitcnt lgkmcnt(0)

; #define LAS __attribute__((address_space(3)))
; #define scr (p.ws + opq_off(SCR_OFF))
; DI void transpose_item(const float* W, int K, int ldw, int nblk, bf16_t* WT, LAS float* scr, int item, int lane) {
;     const int kb = item / nblk, nb = item % nblk, k0 = 64 * kb, n0 = 32 * nb;
;     float wv_[32];
; #pragma unroll
;     for (int i = 0; i < 32; ++i) { const int kk = 2 * i + (lane >> 5); wv_[i] = W[(size_t)(k0 + kk) * ldw + n0 + (lane & 31)]; }
; #pragma unroll
;     for (int i = 0; i < 32; ++i) { const int kk = 2 * i + (lane >> 5); scr[kk * 33 + (lane & 31)] = wv_[i]; }
;     asm volatile("s_waitcnt lgkmcnt(0)" ::: "memory");
; DI void wprep_layer(int wv, LAS unsigned char* lds, const Params& p, int layer, bf16_t* wb) {
;     ...
;         if (r < I1) { transpose_item(w_out, 1024, 1024, 32, wb_out, scr, r, lane); continue; } r -= I1;
.LBB0_618:
	s_andn2_saveexec_b64 s[8:9], s[8:9]
	s_cbranch_execz .LBB0_620
	v_ashrrev_i32_e32 v20, 31, v0
	v_lshrrev_b32_e32 v20, 27, v20
	v_add_u32_e32 v20, v0, v20
	v_and_b32_e32 v21, 0x7ffffe0, v20
	v_lshlrev_b32_e32 v20, 1, v20
	v_sub_u32_e32 v0, v0, v21
	v_and_b32_e32 v22, 0xffffffc0, v20
	v_lshlrev_b32_e32 v20, 5, v0
	v_or_b32_e32 v26, v22, v28
	v_ashrrev_i32_e32 v21, 31, v20
	v_ashrrev_i32_e32 v27, 31, v26
	v_lshl_add_u64 v[24:25], v[20:21], 2, v[12:13]
	v_lshlrev_b64 v[36:37], 12, v[26:27]
	v_lshl_add_u64 v[36:37], v[24:25], 0, v[36:37]
	global_load_dword v0, v[36:37], off
	v_or_b32_e32 v36, 2, v26
	v_ashrrev_i32_e32 v37, 31, v36
	v_lshlrev_b64 v[36:37], 12, v[36:37]
	v_lshl_add_u64 v[36:37], v[24:25], 0, v[36:37]
	global_load_dword v21, v[36:37], off
	v_or_b32_e32 v36, 4, v26
	v_ashrrev_i32_e32 v37, 31, v36
	v_lshlrev_b64 v[36:37], 12, v[36:37]
	v_lshl_add_u64 v[36:37], v[24:25], 0, v[36:37]
	global_load_dword v23, v[36:37], off
	v_or_b32_e32 v36, 6, v26
	v_ashrrev_i32_e32 v37, 31, v36
	v_lshlrev_b64 v[36:37], 12, v[36:37]
	v_lshl_add_u64 v[36:37], v[24:25], 0, v[36:37]
	global_load_dword v38, v[36:37], off
	v_or_b32_e32 v36, 8, v26
	v_ashrrev_i32_e32 v37, 31, v36
	v_lshlrev_b64 v[36:37], 12, v[36:37]
	v_lshl_add_u64 v[36:37], v[24:25], 0, v[36:37]
	global_load_dword v39, v[36:37], off
	v_or_b32_e32 v36, 10, v26
	v_ashrrev_i32_e32 v37, 31, v36
	v_lshlrev_b64 v[36:37], 12, v[36:37]
	v_lshl_add_u64 v[36:37], v[24:25], 0, v[36:37]
	global_load_dword v40, v[36:37], off
	v_or_b32_e32 v36, 12, v26
	v_ashrrev_i32_e32 v37, 31, v36
	v_lshlrev_b64 v[36:37], 12, v[36:37]
	v_lshl_add_u64 v[36:37], v[24:25], 0, v[36:37]
	global_load_dword v41, v[36:37], off
	v_or_b32_e32 v36, 14, v26
	v_ashrrev_i32_e32 v37, 31, v36
	v_lshlrev_b64 v[36:37], 12, v[36:37]
	v_lshl_add_u64 v[36:37], v[24:25], 0, v[36:37]
	global_load_dword v42, v[36:37], off
	v_or_b32_e32 v36, 16, v26
	v_ashrrev_i32_e32 v37, 31, v36
	v_lshlrev_b64 v[36:37], 12, v[36:37]
	v_lshl_add_u64 v[36:37], v[24:25], 0, v[36:37]
	global_load_dword v43, v[36:37], off
	v_or_b32_e32 v36, 18, v26
	v_ashrrev_i32_e32 v37, 31, v36
	v_lshlrev_b64 v[36:37], 12, v[36:37]
	v_lshl_add_u64 v[36:37], v[24:25], 0, v[36:37]
	global_load_dword v44, v[36:37], off
	v_or_b32_e32 v36, 20, v26
	v_ashrrev_i32_e32 v37, 31, v36
	v_lshlrev_b64 v[36:37], 12, v[36:37]
	v_lshl_add_u64 v[36:37], v[24:25], 0, v[36:37]
	global_load_dword v45, v[36:37], off
	v_or_b32_e32 v36, 22, v26
	v_ashrrev_i32_e32 v37, 31, v36
	v_lshlrev_b64 v[36:37], 12, v[36:37]
	v_lshl_add_u64 v[36:37], v[24:25], 0, v[36:37]
	global_load_dword v46, v[36:37], off
	v_or_b32_e32 v36, 24, v26
	v_ashrrev_i32_e32 v37, 31, v36
	v_lshlrev_b64 v[36:37], 12, v[36:37]
	v_lshl_add_u64 v[36:37], v[24:25], 0, v[36:37]
	global_load_dword v47, v[36:37], off
	v_or_b32_e32 v36, 26, v26
	v_ashrrev_i32_e32 v37, 31, v36
	v_lshlrev_b64 v[36:37], 12, v[36:37]
	v_lshl_add_u64 v[36:37], v[24:25], 0, v[36:37]
	global_load_dword v48, v[36:37], off
	v_or_b32_e32 v36, 28, v26
	v_ashrrev_i32_e32 v37, 31, v36
	v_lshlrev_b64 v[36:37], 12, v[36:37]
	v_lshl_add_u64 v[36:37], v[24:25], 0, v[36:37]
	global_load_dword v49, v[36:37], off
	v_or_b32_e32 v36, 30, v26
	v_ashrrev_i32_e32 v37, 31, v36
	v_lshlrev_b64 v[36:37], 12, v[36:37]
	v_lshl_add_u64 v[36:37], v[24:25], 0, v[36:37]
	global_load_dword v50, v[36:37], off
	v_or_b32_e32 v36, 32, v26
	v_ashrrev_i32_e32 v37, 31, v36
	v_lshlrev_b64 v[36:37], 12, v[36:37]
	v_lshl_add_u64 v[36:37], v[24:25], 0, v[36:37]
	global_load_dword v51, v[36:37], off
	v_or_b32_e32 v36, 34, v26
	v_ashrrev_i32_e32 v37, 31, v36
	v_lshlrev_b64 v[36:37], 12, v[36:37]
	v_lshl_add_u64 v[36:37], v[24:25], 0, v[36:37]
	global_load_dword v52, v[36:37], off
	v_or_b32_e32 v36, 36, v26
	v_ashrrev_i32_e32 v37, 31, v36
	v_lshlrev_b64 v[36:37], 12, v[36:37]
	v_lshl_add_u64 v[36:37], v[24:25], 0, v[36:37]
	global_load_dword v53, v[36:37], off
	v_or_b32_e32 v36, 38, v26
	v_ashrrev_i32_e32 v37, 31, v36
	v_lshlrev_b64 v[36:37], 12, v[36:37]
	v_lshl_add_u64 v[36:37], v[24:25], 0, v[36:37]
	global_load_dword v54, v[36:37], off
	v_or_b32_e32 v36, 40, v26
	v_ashrrev_i32_e32 v37, 31, v36
	v_lshlrev_b64 v[36:37], 12, v[36:37]
	v_lshl_add_u64 v[36:37], v[24:25], 0, v[36:37]
	global_load_dword v55, v[36:37], off
	v_or_b32_e32 v36, 42, v26
	v_ashrrev_i32_e32 v37, 31, v36
	v_lshlrev_b64 v[36:37], 12, v[36:37]
	v_lshl_add_u64 v[36:37], v[24:25], 0, v[36:37]
	global_load_dword v56, v[36:37], off
	v_or_b32_e32 v36, 44, v26
	v_ashrrev_i32_e32 v37, 31, v36
	v_lshlrev_b64 v[36:37], 12, v[36:37]
	v_lshl_add_u64 v[36:37], v[24:25], 0, v[36:37]
	global_load_dword v57, v[36:37], off
	v_or_b32_e32 v36, 46, v26
	v_ashrrev_i32_e32 v37, 31, v36
	v_lshlrev_b64 v[36:37], 12, v[36:37]
	v_lshl_add_u64 v[36:37], v[24:25], 0, v[36:37]
	global_load_dword v58, v[36:37], off
	v_or_b32_e32 v36, 48, v26
	v_ashrrev_i32_e32 v37, 31, v36
	v_lshlrev_b64 v[36:37], 12, v[36:37]
	v_lshl_add_u64 v[36:37], v[24:25], 0, v[36:37]
	global_load_dword v59, v[36:37], off
	v_or_b32_e32 v36, 50, v26
	v_ashrrev_i32_e32 v37, 31, v36
	v_lshlrev_b64 v[36:37], 12, v[36:37]
	v_lshl_add_u64 v[36:37], v[24:25], 0, v[36:37]
	global_load_dword v60, v[36:37], off
	v_or_b32_e32 v36, 52, v26
	v_ashrrev_i32_e32 v37, 31, v36
	v_lshlrev_b64 v[36:37], 12, v[36:37]
	v_lshl_add_u64 v[36:37], v[24:25], 0, v[36:37]
	global_load_dword v61, v[36:37], off
	v_or_b32_e32 v36, 54, v26
	v_ashrrev_i32_e32 v37, 31, v36
	v_lshlrev_b64 v[36:37], 12, v[36:37]
	v_lshl_add_u64 v[36:37], v[24:25], 0, v[36:37]
	global_load_dword v62, v[36:37], off
	v_or_b32_e32 v36, 56, v26
	v_ashrrev_i32_e32 v37, 31, v36
	v_lshlrev_b64 v[36:37], 12, v[36:37]
	v_lshl_add_u64 v[36:37], v[24:25], 0, v[36:37]
	global_load_dword v63, v[36:37], off
	v_or_b32_e32 v36, 58, v26
	v_ashrrev_i32_e32 v37, 31, v36
	v_lshlrev_b64 v[36:37], 12, v[36:37]
	v_lshl_add_u64 v[36:37], v[24:25], 0, v[36:37]
	global_load_dword v64, v[36:37], off
	v_or_b32_e32 v36, 60, v26
	v_or_b32_e32 v26, 62, v26
	v_ashrrev_i32_e32 v37, 31, v36
	v_ashrrev_i32_e32 v27, 31, v26
	v_lshlrev_b64 v[36:37], 12, v[36:37]
	v_lshlrev_b64 v[26:27], 12, v[26:27]
	v_lshl_add_u64 v[36:37], v[24:25], 0, v[36:37]
	v_lshl_add_u64 v[24:25], v[24:25], 0, v[26:27]
	global_load_dword v36, v[36:37], off
	global_load_dword v24, v[24:25], off
	s_waitcnt vmcnt(30)
; #define LAS __attribute__((address_space(3)))
; DI unsigned pk2(float lo, float hi) { f32x2 f = {lo, hi}; bf2_t v = __builtin_convertvector(f, bf2_t); return __builtin_bit_cast(unsigned, v); }
; #define scr (p.ws + opq_off(SCR_OFF))
; DI void transpose_item(const float* W, int K, int ldw, int nblk, bf16_t* WT, LAS float* scr, int item, int lane) {
;     ...
;     for (int i = 0; i < 32; ++i) { const int kk = 2 * i + (lane >> 5); scr[kk * 33 + (lane & 31)] = wv_[i]; }
;     asm volatile("s_waitcnt lgkmcnt(0)" ::: "memory");
;     const int c = lane & 7;
; #pragma unroll
;     for (int j = 0; j < 4; ++j) { const int n = (lane >> 3) + 8 * j; const LAS float* s = scr + (8 * c) * 33 + n;
;         u32x4 o; o.x = pk2(s[0 * 33], s[1 * 33]); o.y = pk2(s[2 * 33], s[3 * 33]); o.z = pk2(s[4 * 33], s[5 * 33]); o.w = pk2(s[6 * 33], s[7 * 33]);
;         *(u32x4*)(WT + (size_t)(n0 + n) * K + k0 + 8 * c) = o; }
;     asm volatile("s_waitcnt lgkmcnt(0)" ::: "memory");
	ds_write2_b32 v29, v0, v21 offset1:66
	s_waitcnt vmcnt(28)
	ds_write2_b32 v29, v23, v38 offset0:132 offset1:198
	v_add_u32_e32 v0, 0x400, v29
	s_waitcnt vmcnt(26)
	ds_write2_b32 v0, v39, v40 offset0:8 offset1:74
	s_waitcnt vmcnt(24)
	ds_write2_b32 v0, v41, v42 offset0:140 offset1:206
	v_add_u32_e32 v0, 0x800, v29
	s_waitcnt vmcnt(22)
	ds_write2_b32 v0, v43, v44 offset0:16 offset1:82
	s_waitcnt vmcnt(20)
	ds_write2_b32 v0, v45, v46 offset0:148 offset1:214
	v_add_u32_e32 v0, 0xc00, v29
	s_waitcnt vmcnt(18)
	ds_write2_b32 v0, v47, v48 offset0:24 offset1:90
	s_waitcnt vmcnt(16)
	ds_write2_b32 v0, v49, v50 offset0:156 offset1:222
	v_add_u32_e32 v0, 0x1000, v29
	s_waitcnt vmcnt(14)
	ds_write2_b32 v0, v51, v52 offset0:32 offset1:98
	s_waitcnt vmcnt(12)
	ds_write2_b32 v0, v53, v54 offset0:164 offset1:230
	v_add_u32_e32 v0, 0x1400, v29
	s_waitcnt vmcnt(10)
	ds_write2_b32 v0, v55, v56 offset0:40 offset1:106
	s_waitcnt vmcnt(8)
	ds_write2_b32 v0, v57, v58 offset0:172 offset1:238
	v_add_u32_e32 v0, 0x1800, v29
	s_waitcnt vmcnt(6)
	ds_write2_b32 v0, v59, v60 offset0:48 offset1:114
	s_waitcnt vmcnt(4)
	ds_write2_b32 v0, v61, v62 offset0:180 offset1:246
	v_add_u32_e32 v0, 0x1c00, v29
	s_waitcnt vmcnt(2)
	ds_write2_b32 v0, v63, v64 offset0:56 offset1:122
	s_waitcnt vmcnt(0)
	ds_write2_b32 v0, v36, v24 offset0:188 offset1:254
	s_waitcnt lgkmcnt(0)
	ds_read2_b32 v[36:37], v31 offset0:33 offset1:41
	ds_read2_b32 v[38:39], v31 offset1:8
	ds_read2_b32 v[40:41], v31 offset0:66 offset1:74
	ds_read2_b32 v[42:43], v31 offset0:99 offset1:107
	ds_read2_b32 v[44:45], v31 offset0:132 offset1:140
	ds_read2_b32 v[46:47], v31 offset0:165 offset1:173
	ds_read2_b32 v[48:49], v31 offset0:198 offset1:206
	ds_read2_b32 v[50:51], v31 offset0:231 offset1:239
	v_or_b32_e32 v52, v20, v30
	v_ashrrev_i32_e32 v23, 31, v22
	v_ashrrev_i32_e32 v53, 31, v52
	v_lshl_add_u64 v[26:27], v[22:23], 1, v[4:5]
	v_lshlrev_b64 v[52:53], 11, v[52:53]
	s_waitcnt lgkmcnt(6)
	v_cvt_pk_bf16_f32 v22, v38, v36
	s_waitcnt lgkmcnt(4)
	v_cvt_pk_bf16_f32 v23, v40, v42
	s_waitcnt lgkmcnt(2)
	v_cvt_pk_bf16_f32 v24, v44, v46
	s_waitcnt lgkmcnt(0)
	v_cvt_pk_bf16_f32 v25, v48, v50
	v_lshl_add_u64 v[52:53], v[26:27], 0, v[52:53]
	v_or_b32_e32 v36, v20, v32
	global_store_dwordx4 v[52:53], v[22:25], off
	v_or_b32_e32 v52, v20, v33
	v_ashrrev_i32_e32 v53, 31, v52
	v_cvt_pk_bf16_f32 v22, v39, v37
	v_ashrrev_i32_e32 v37, 31, v36
	v_lshlrev_b64 v[36:37], 11, v[36:37]
	v_cvt_pk_bf16_f32 v23, v41, v43
	v_cvt_pk_bf16_f32 v24, v45, v47
	v_cvt_pk_bf16_f32 v25, v49, v51
	v_lshl_add_u64 v[36:37], v[26:27], 0, v[36:37]
	global_store_dwordx4 v[36:37], v[22:25], off
	ds_read2_b32 v[36:37], v31 offset0:49 offset1:57
	ds_read2_b32 v[38:39], v31 offset0:16 offset1:24
	ds_read2_b32 v[40:41], v31 offset0:82 offset1:90
	ds_read2_b32 v[42:43], v31 offset0:115 offset1:123
	ds_read2_b32 v[44:45], v31 offset0:148 offset1:156
	ds_read2_b32 v[46:47], v31 offset0:181 offset1:189
	ds_read2_b32 v[48:49], v31 offset0:214 offset1:222
	ds_read2_b32 v[50:51], v31 offset0:247 offset1:255
	v_or_b32_e32 v20, v20, v34
	v_lshlrev_b64 v[52:53], 11, v[52:53]
	v_ashrrev_i32_e32 v21, 31, v20
	s_waitcnt lgkmcnt(6)
	v_cvt_pk_bf16_f32 v22, v38, v36
	s_waitcnt lgkmcnt(4)
	v_cvt_pk_bf16_f32 v23, v40, v42
	s_waitcnt lgkmcnt(2)
	v_cvt_pk_bf16_f32 v24, v44, v46
	s_waitcnt lgkmcnt(0)
	v_cvt_pk_bf16_f32 v25, v48, v50
	v_lshl_add_u64 v[52:53], v[26:27], 0, v[52:53]
	v_lshlrev_b64 v[20:21], 11, v[20:21]
	global_store_dwordx4 v[52:53], v[22:25], off
	v_lshl_add_u64 v[20:21], v[26:27], 0, v[20:21]
	s_nop 0
	v_cvt_pk_bf16_f32 v22, v39, v37
	v_cvt_pk_bf16_f32 v23, v41, v43
	v_cvt_pk_bf16_f32 v24, v45, v47
	v_cvt_pk_bf16_f32 v25, v49, v51
	global_store_dwordx4 v[20:21], v[22:25], off
	s_waitcnt lgkmcnt(0)
